# p6nt + nt hint on the 272 read-once f32 weight loads of phase 0 and the 8 x2 row loads of P14
# baseline (speedup 1.0000x reference)
; #define LAS __attribute__((address_space(3)))
; #define LDS_WAIT() asm volatile("s_waitcnt lgkmcnt(0)" ::: "memory")
; __device__ __forceinline__ void transpose_item(const float* W, int ldw, int k0, int n0, bf16_t* WT, int ldt, int drow0, LAS float* scr, int lane) {
; #pragma unroll 8
;     for (int i = 0; i < 32; ++i) { const int kk = 2 * i + (lane >> 5); scr[kk * 33 + (lane & 31)] = W[(size_t)(k0 + kk) * ldw + n0 + (lane & 31)]; }
;     LDS_WAIT(); asm volatile("" ::: "memory");
.LBB0_30:
	s_lshl_b32 s45, s17, 1
	s_lshl_b32 s46, s19, 1
	v_or_b32_e32 v41, s45, v1
	v_or_b32_e32 v62, s46, v0
	s_add_i32 s48, s46, 4
	s_add_i32 s47, s45, 4
	s_add_i32 s49, s45, 8
	s_add_i32 s50, s46, 8
	s_add_i32 s51, s45, 12
	s_add_i32 s53, s45, 16
	s_add_i32 s57, s45, 20
	s_add_i32 s59, s45, 24
	s_add_i32 s45, s45, 28
	v_add_lshl_u32 v6, v41, s18, 12
	v_add_lshl_u32 v44, v62, s6, 12
	v_or_b32_e32 v64, s48, v0
	s_add_i32 s52, s46, 12
	v_or_b32_e32 v63, s47, v1
	v_or_b32_e32 v65, s49, v1
	v_or_b32_e32 v66, s50, v0
	v_or_b32_e32 v67, s51, v1
	v_or_b32_e32 v69, s53, v1
	v_or_b32_e32 v71, s57, v1
	v_or_b32_e32 v73, s59, v1
	v_or_b32_e32 v75, s45, v1
	v_or_b32_e32 v42, v5, v6
	v_or_b32_e32 v6, v30, v44
	v_add_lshl_u32 v46, v64, s6, 12
	v_mov_b32_e32 v43, v7
	s_add_i32 s56, s46, 16
	v_or_b32_e32 v68, s52, v0
	v_add_lshl_u32 v44, v63, s18, 12
	v_add_lshl_u32 v48, v65, s18, 12
	v_add_lshl_u32 v77, v66, s6, 12
	v_add_lshl_u32 v50, v67, s18, 12
	v_add_lshl_u32 v52, v69, s18, 12
	v_add_lshl_u32 v54, v71, s18, 12
	v_add_lshl_u32 v56, v73, s18, 12
	v_add_lshl_u32 v60, v75, s18, 12
	s_waitcnt lgkmcnt(0)
	v_lshl_add_u64 v[58:59], v[6:7], 2, s[14:15]
	v_or_b32_e32 v6, v30, v46
	v_mov_b32_e32 v45, v7
	s_add_i32 s58, s46, 20
	v_or_b32_e32 v70, s56, v0
	v_add_lshl_u32 v78, v68, s6, 12
	v_lshl_add_u64 v[42:43], v[42:43], 2, s[14:15]
	v_or_b32_e32 v44, v5, v44
	v_or_b32_e32 v46, v5, v48
	v_or_b32_e32 v48, v5, v50
	v_or_b32_e32 v50, v5, v52
	v_or_b32_e32 v52, v5, v54
	v_or_b32_e32 v54, v5, v56
	v_or_b32_e32 v56, v5, v60
	v_lshl_add_u64 v[60:61], v[6:7], 2, s[14:15]
	v_or_b32_e32 v6, v30, v77
	s_add_i32 s60, s46, 24
	v_or_b32_e32 v72, s58, v0
	v_add_lshl_u32 v79, v70, s6, 12
	v_lshl_add_u64 v[44:45], v[44:45], 2, s[14:15]
	global_load_dword v77, v[58:59], off nt
	global_load_dword v84, v[42:43], off nt
	global_load_dword v85, v[60:61], off nt
	global_load_dword v86, v[44:45], off nt
	v_lshl_add_u64 v[42:43], v[6:7], 2, s[14:15]
	v_or_b32_e32 v6, v30, v78
	v_mov_b32_e32 v47, v7
	v_mov_b32_e32 v49, v7
	s_add_i32 s46, s46, 28
	v_or_b32_e32 v74, s60, v0
	v_add_lshl_u32 v80, v72, s6, 12
	v_lshl_add_u64 v[44:45], v[6:7], 2, s[14:15]
	v_or_b32_e32 v6, v30, v79
	v_or_b32_e32 v76, s46, v0
	v_add_lshl_u32 v81, v74, s6, 12
	v_lshl_add_u64 v[46:47], v[46:47], 2, s[14:15]
	v_lshl_add_u64 v[48:49], v[48:49], 2, s[14:15]
	global_load_dword v78, v[42:43], off nt
	global_load_dword v79, v[46:47], off nt
	global_load_dword v87, v[44:45], off nt
	global_load_dword v88, v[48:49], off nt
	v_lshl_add_u64 v[42:43], v[6:7], 2, s[14:15]
	v_or_b32_e32 v6, v30, v80
	v_mov_b32_e32 v51, v7
	v_mov_b32_e32 v53, v7
	v_add_lshl_u32 v82, v76, s6, 12
	v_lshl_add_u64 v[44:45], v[6:7], 2, s[14:15]
	v_or_b32_e32 v6, v30, v81
	v_mov_b32_e32 v55, v7
	v_mov_b32_e32 v57, v7
	v_lshl_add_u64 v[50:51], v[50:51], 2, s[14:15]
	v_lshl_add_u64 v[52:53], v[52:53], 2, s[14:15]
	global_load_dword v80, v[42:43], off nt
	global_load_dword v81, v[50:51], off nt
	global_load_dword v89, v[44:45], off nt
	global_load_dword v90, v[52:53], off nt
	v_lshl_add_u64 v[42:43], v[6:7], 2, s[14:15]
	v_or_b32_e32 v6, v30, v82
	v_lshl_add_u64 v[54:55], v[54:55], 2, s[14:15]
	v_lshl_add_u64 v[56:57], v[56:57], 2, s[14:15]
	v_lshl_add_u64 v[44:45], v[6:7], 2, s[14:15]
	global_load_dword v6, v[42:43], off nt
	global_load_dword v82, v[54:55], off nt
	global_load_dword v91, v[44:45], off nt
	global_load_dword v92, v[56:57], off nt
	s_add_i32 s19, s19, 16
	s_add_i32 s17, s17, 16
	s_add_i32 s44, s44, -16
	v_mad_u64_u32 v[42:43], s[46:47], v62, s21, v[2:3]
	s_cmp_lg_u32 s44, 0
	v_mad_u64_u32 v[44:45], s[46:47], v41, s21, v[2:3]
	v_mad_u64_u32 v[46:47], s[46:47], v64, s21, v[2:3]
	v_mad_u64_u32 v[48:49], s[46:47], v63, s21, v[2:3]
	v_mad_u64_u32 v[50:51], s[46:47], v66, s21, v[2:3]
	v_mad_u64_u32 v[52:53], s[46:47], v65, s21, v[2:3]
	v_mad_u64_u32 v[54:55], s[46:47], v68, s21, v[2:3]
	v_mad_u64_u32 v[56:57], s[46:47], v67, s21, v[2:3]
	v_mad_u64_u32 v[58:59], s[46:47], v70, s21, v[2:3]
	v_mad_u64_u32 v[60:61], s[46:47], v69, s21, v[2:3]
	v_mad_u64_u32 v[62:63], s[46:47], v72, s21, v[2:3]
	v_mad_u64_u32 v[64:65], s[46:47], v71, s21, v[2:3]
	v_mad_u64_u32 v[66:67], s[46:47], v74, s21, v[2:3]
	v_mad_u64_u32 v[68:69], s[46:47], v73, s21, v[2:3]
	v_mad_u64_u32 v[70:71], s[46:47], v76, s21, v[2:3]
	v_mad_u64_u32 v[72:73], s[46:47], v75, s21, v[2:3]
	s_waitcnt vmcnt(15)
	ds_write_b32 v42, v77
	s_waitcnt vmcnt(14)
	ds_write_b32 v44, v84
	s_waitcnt vmcnt(13)
	ds_write_b32 v46, v85
	s_waitcnt vmcnt(12)
	ds_write_b32 v48, v86
	s_waitcnt vmcnt(11)
	ds_write_b32 v50, v78
	s_waitcnt vmcnt(10)
	ds_write_b32 v52, v79
	s_waitcnt vmcnt(9)
	ds_write_b32 v54, v87
	s_waitcnt vmcnt(8)
	ds_write_b32 v56, v88
	s_waitcnt vmcnt(7)
	ds_write_b32 v58, v80
	s_waitcnt vmcnt(6)
	ds_write_b32 v60, v81
	s_waitcnt vmcnt(5)
	ds_write_b32 v62, v89
	s_waitcnt vmcnt(4)
	ds_write_b32 v64, v90
	s_waitcnt vmcnt(3)
	ds_write_b32 v66, v6
	s_waitcnt vmcnt(2)
	ds_write_b32 v68, v82
	s_waitcnt vmcnt(1)
	ds_write_b32 v70, v91
	s_waitcnt vmcnt(0)
	ds_write_b32 v72, v92
	s_cbranch_scc1 .LBB0_30
; #define LAS __attribute__((address_space(3)))
; __device__ __forceinline__ unsigned cvt_pk_bf16(float lo, float hi) { unsigned r; asm volatile("v_cvt_pk_bf16_f32 %0, %1, %2" : "=v"(r) : "v"(lo), "v"(hi)); return r; }
; #define LDS_WAIT() asm volatile("s_waitcnt lgkmcnt(0)" ::: "memory")
; __device__ __forceinline__ void transpose_item(const float* W, int ldw, int k0, int n0, bf16_t* WT, int ldt, int drow0, LAS float* scr, int lane) {
;     ...
;     const int c = lane & 7;
; #pragma unroll
;     for (int j = 0; j < 4; ++j) { const int n = (lane >> 3) + 8 * j; const LAS float* s = scr + (8 * c) * 33 + n;
;         u32x4 o; o.x = cvt_pk_bf16(s[0 * 33], s[1 * 33]); o.y = cvt_pk_bf16(s[2 * 33], s[3 * 33]); o.z = cvt_pk_bf16(s[4 * 33], s[5 * 33]); o.w = cvt_pk_bf16(s[6 * 33], s[7 * 33]);
;         *(u32x4*)(WT + (size_t)(drow0 + n) * ldt + k0 + 8 * c) = o; }
;     LDS_WAIT(); asm volatile("" ::: "memory");
	s_waitcnt lgkmcnt(0)
	ds_read2_b32 v[42:43], v32 offset1:33
	s_waitcnt lgkmcnt(0)
	v_cvt_pk_bf16_f32 v42, v42, v43
	ds_read2_b32 v[44:45], v32 offset0:66 offset1:99
	s_lshl_b32 s6, s6, 1
	v_or_b32_e32 v5, s16, v31
	s_waitcnt lgkmcnt(0)
	v_cvt_pk_bf16_f32 v43, v44, v45
	ds_read2_b32 v[44:45], v32 offset0:132 offset1:165
	v_lshl_add_u64 v[48:49], v[8:9], 0, s[6:7]
	v_lshlrev_b32_e32 v6, 15, v5
	s_waitcnt lgkmcnt(0)
	v_cvt_pk_bf16_f32 v44, v44, v45
	ds_read2_b32 v[46:47], v32 offset0:198 offset1:231
	s_waitcnt lgkmcnt(0)
	v_cvt_pk_bf16_f32 v45, v46, v47
	v_lshl_add_u64 v[50:51], v[48:49], 0, v[6:7]
	ds_read2_b32 v[46:47], v32 offset0:8 offset1:41
	global_store_dwordx4 v[50:51], v[42:45], off
	v_or_b32_e32 v5, s16, v33
	v_lshlrev_b32_e32 v6, 15, v5
	s_waitcnt lgkmcnt(0)
	v_cvt_pk_bf16_f32 v42, v46, v47
	ds_read2_b32 v[44:45], v32 offset0:74 offset1:107
	s_waitcnt lgkmcnt(0)
	v_cvt_pk_bf16_f32 v43, v44, v45
	ds_read2_b32 v[44:45], v32 offset0:140 offset1:173
	s_waitcnt lgkmcnt(0)
	v_cvt_pk_bf16_f32 v44, v44, v45
	ds_read2_b32 v[46:47], v32 offset0:206 offset1:239
	s_waitcnt lgkmcnt(0)
	v_cvt_pk_bf16_f32 v45, v46, v47
	v_lshl_add_u64 v[50:51], v[48:49], 0, v[6:7]
	ds_read2_b32 v[46:47], v32 offset0:16 offset1:49
	global_store_dwordx4 v[50:51], v[42:45], off
	v_or_b32_e32 v5, s16, v34
	v_lshlrev_b32_e32 v6, 15, v5
	s_waitcnt lgkmcnt(0)
	v_cvt_pk_bf16_f32 v42, v46, v47
	ds_read2_b32 v[44:45], v32 offset0:82 offset1:115
	s_waitcnt lgkmcnt(0)
	v_cvt_pk_bf16_f32 v43, v44, v45
	ds_read2_b32 v[44:45], v32 offset0:148 offset1:181
	s_waitcnt lgkmcnt(0)
	v_cvt_pk_bf16_f32 v44, v44, v45
	ds_read2_b32 v[46:47], v32 offset0:214 offset1:247
	s_waitcnt lgkmcnt(0)
	v_cvt_pk_bf16_f32 v45, v46, v47
	v_lshl_add_u64 v[50:51], v[48:49], 0, v[6:7]
	ds_read2_b32 v[46:47], v32 offset0:24 offset1:57
	global_store_dwordx4 v[50:51], v[42:45], off
	v_or_b32_e32 v5, s16, v35
	v_lshlrev_b32_e32 v6, 15, v5
	s_waitcnt lgkmcnt(0)
	v_cvt_pk_bf16_f32 v42, v46, v47
	ds_read2_b32 v[44:45], v32 offset0:90 offset1:123
	s_waitcnt lgkmcnt(0)
	v_cvt_pk_bf16_f32 v43, v44, v45
	ds_read2_b32 v[44:45], v32 offset0:156 offset1:189
	s_waitcnt lgkmcnt(0)
	v_cvt_pk_bf16_f32 v44, v44, v45
	ds_read2_b32 v[46:47], v32 offset0:222 offset1:255
	s_waitcnt lgkmcnt(0)
	v_cvt_pk_bf16_f32 v45, v46, v47
	v_lshl_add_u64 v[46:47], v[48:49], 0, v[6:7]
	global_store_dwordx4 v[46:47], v[42:45], off
	s_waitcnt lgkmcnt(0)
	s_mov_b64 s[14:15], 0

; #define LAS __attribute__((address_space(3)))
; #define LDS_WAIT() asm volatile("s_waitcnt lgkmcnt(0)" ::: "memory")
; __device__ __forceinline__ void transpose_item(const float* W, int ldw, int k0, int n0, bf16_t* WT, int ldt, int drow0, LAS float* scr, int lane) {
; #pragma unroll 8
;     for (int i = 0; i < 32; ++i) { const int kk = 2 * i + (lane >> 5); scr[kk * 33 + (lane & 31)] = W[(size_t)(k0 + kk) * ldw + n0 + (lane & 31)]; }
;     LDS_WAIT(); asm volatile("" ::: "memory");
.LBB0_35:
	s_lshl_b32 s45, s15, 1
	s_lshl_b32 s46, s18, 1
	v_or_b32_e32 v41, s45, v1
	v_or_b32_e32 v62, s46, v0
	s_add_i32 s48, s46, 4
	s_add_i32 s47, s45, 4
	s_add_i32 s49, s45, 8
	s_add_i32 s50, s46, 8
	s_add_i32 s51, s45, 12
	s_add_i32 s53, s45, 16
	s_add_i32 s57, s45, 20
	s_add_i32 s59, s45, 24
	s_add_i32 s45, s45, 28
	v_add_lshl_u32 v6, v41, s6, 14
	v_add_lshl_u32 v44, v62, s14, 14
	v_or_b32_e32 v64, s48, v0
	s_add_i32 s52, s46, 12
	v_or_b32_e32 v63, s47, v1
	v_or_b32_e32 v65, s49, v1
	v_or_b32_e32 v66, s50, v0
	v_or_b32_e32 v67, s51, v1
	v_or_b32_e32 v69, s53, v1
	v_or_b32_e32 v71, s57, v1
	v_or_b32_e32 v73, s59, v1
	v_or_b32_e32 v75, s45, v1
	v_or_b32_e32 v42, v5, v6
	v_or_b32_e32 v6, v30, v44
	v_add_lshl_u32 v46, v64, s14, 14
	v_mov_b32_e32 v43, v7
	s_add_i32 s56, s46, 16
	v_or_b32_e32 v68, s52, v0
	v_add_lshl_u32 v44, v63, s6, 14
	v_add_lshl_u32 v48, v65, s6, 14
	v_add_lshl_u32 v77, v66, s14, 14
	v_add_lshl_u32 v50, v67, s6, 14
	v_add_lshl_u32 v52, v69, s6, 14
	v_add_lshl_u32 v54, v71, s6, 14
	v_add_lshl_u32 v56, v73, s6, 14
	v_add_lshl_u32 v60, v75, s6, 14
	s_waitcnt lgkmcnt(0)
	v_lshl_add_u64 v[58:59], v[6:7], 2, s[16:17]
	v_or_b32_e32 v6, v30, v46
	v_mov_b32_e32 v45, v7
	s_add_i32 s58, s46, 20
	v_or_b32_e32 v70, s56, v0
	v_add_lshl_u32 v78, v68, s14, 14
	v_lshl_add_u64 v[42:43], v[42:43], 2, s[16:17]
	v_or_b32_e32 v44, v5, v44
	v_or_b32_e32 v46, v5, v48
	v_or_b32_e32 v48, v5, v50
	v_or_b32_e32 v50, v5, v52
	v_or_b32_e32 v52, v5, v54
	v_or_b32_e32 v54, v5, v56
	v_or_b32_e32 v56, v5, v60
	v_lshl_add_u64 v[60:61], v[6:7], 2, s[16:17]
	v_or_b32_e32 v6, v30, v77
	s_add_i32 s60, s46, 24
	v_or_b32_e32 v72, s58, v0
	v_add_lshl_u32 v79, v70, s14, 14
	v_lshl_add_u64 v[44:45], v[44:45], 2, s[16:17]
	global_load_dword v77, v[58:59], off nt
	global_load_dword v84, v[42:43], off nt
	global_load_dword v85, v[60:61], off nt
	global_load_dword v86, v[44:45], off nt
	v_lshl_add_u64 v[42:43], v[6:7], 2, s[16:17]
	v_or_b32_e32 v6, v30, v78
	v_mov_b32_e32 v47, v7
	v_mov_b32_e32 v49, v7
	s_add_i32 s46, s46, 28
	v_or_b32_e32 v74, s60, v0
	v_add_lshl_u32 v80, v72, s14, 14
	v_lshl_add_u64 v[44:45], v[6:7], 2, s[16:17]
	v_or_b32_e32 v6, v30, v79
	v_or_b32_e32 v76, s46, v0
	v_add_lshl_u32 v81, v74, s14, 14
	v_lshl_add_u64 v[46:47], v[46:47], 2, s[16:17]
	v_lshl_add_u64 v[48:49], v[48:49], 2, s[16:17]
	global_load_dword v78, v[42:43], off nt
	global_load_dword v79, v[46:47], off nt
	global_load_dword v87, v[44:45], off nt
	global_load_dword v88, v[48:49], off nt
	v_lshl_add_u64 v[42:43], v[6:7], 2, s[16:17]
	v_or_b32_e32 v6, v30, v80
	v_mov_b32_e32 v51, v7
	v_mov_b32_e32 v53, v7
	v_add_lshl_u32 v82, v76, s14, 14
	v_lshl_add_u64 v[44:45], v[6:7], 2, s[16:17]
	v_or_b32_e32 v6, v30, v81
	v_mov_b32_e32 v55, v7
	v_mov_b32_e32 v57, v7
	v_lshl_add_u64 v[50:51], v[50:51], 2, s[16:17]
	v_lshl_add_u64 v[52:53], v[52:53], 2, s[16:17]
	global_load_dword v80, v[42:43], off nt
	global_load_dword v81, v[50:51], off nt
	global_load_dword v89, v[44:45], off nt
	global_load_dword v90, v[52:53], off nt
	v_lshl_add_u64 v[42:43], v[6:7], 2, s[16:17]
	v_or_b32_e32 v6, v30, v82
	v_lshl_add_u64 v[54:55], v[54:55], 2, s[16:17]
	v_lshl_add_u64 v[56:57], v[56:57], 2, s[16:17]
	v_lshl_add_u64 v[44:45], v[6:7], 2, s[16:17]
	global_load_dword v6, v[42:43], off nt
	global_load_dword v82, v[54:55], off nt
	global_load_dword v91, v[44:45], off nt
	global_load_dword v92, v[56:57], off nt
	s_add_i32 s18, s18, 16
	s_add_i32 s15, s15, 16
	s_add_i32 s19, s19, -16
	v_mad_u64_u32 v[42:43], s[46:47], v62, s21, v[2:3]
	s_cmp_lg_u32 s19, 0
	v_mad_u64_u32 v[44:45], s[46:47], v41, s21, v[2:3]
	v_mad_u64_u32 v[46:47], s[46:47], v64, s21, v[2:3]
	v_mad_u64_u32 v[48:49], s[46:47], v63, s21, v[2:3]
	v_mad_u64_u32 v[50:51], s[46:47], v66, s21, v[2:3]
	v_mad_u64_u32 v[52:53], s[46:47], v65, s21, v[2:3]
	v_mad_u64_u32 v[54:55], s[46:47], v68, s21, v[2:3]
	v_mad_u64_u32 v[56:57], s[46:47], v67, s21, v[2:3]
	v_mad_u64_u32 v[58:59], s[46:47], v70, s21, v[2:3]
	v_mad_u64_u32 v[60:61], s[46:47], v69, s21, v[2:3]
	v_mad_u64_u32 v[62:63], s[46:47], v72, s21, v[2:3]
	v_mad_u64_u32 v[64:65], s[46:47], v71, s21, v[2:3]
	v_mad_u64_u32 v[66:67], s[46:47], v74, s21, v[2:3]
	v_mad_u64_u32 v[68:69], s[46:47], v73, s21, v[2:3]
	v_mad_u64_u32 v[70:71], s[46:47], v76, s21, v[2:3]
	v_mad_u64_u32 v[72:73], s[46:47], v75, s21, v[2:3]
	s_waitcnt vmcnt(15)
	ds_write_b32 v42, v77
	s_waitcnt vmcnt(14)
	ds_write_b32 v44, v84
	s_waitcnt vmcnt(13)
	ds_write_b32 v46, v85
	s_waitcnt vmcnt(12)
	ds_write_b32 v48, v86
	s_waitcnt vmcnt(11)
	ds_write_b32 v50, v78
	s_waitcnt vmcnt(10)
	ds_write_b32 v52, v79
	s_waitcnt vmcnt(9)
	ds_write_b32 v54, v87
	s_waitcnt vmcnt(8)
	ds_write_b32 v56, v88
	s_waitcnt vmcnt(7)
	ds_write_b32 v58, v80
	s_waitcnt vmcnt(6)
	ds_write_b32 v60, v81
	s_waitcnt vmcnt(5)
	ds_write_b32 v62, v89
	s_waitcnt vmcnt(4)
	ds_write_b32 v64, v90
	s_waitcnt vmcnt(3)
	ds_write_b32 v66, v6
	s_waitcnt vmcnt(2)
	ds_write_b32 v68, v82
	s_waitcnt vmcnt(1)
	ds_write_b32 v70, v91
	s_waitcnt vmcnt(0)
	ds_write_b32 v72, v92
	s_cbranch_scc1 .LBB0_35
; #define LAS __attribute__((address_space(3)))
; __device__ __forceinline__ unsigned cvt_pk_bf16(float lo, float hi) { unsigned r; asm volatile("v_cvt_pk_bf16_f32 %0, %1, %2" : "=v"(r) : "v"(lo), "v"(hi)); return r; }
; __device__ __forceinline__ void transpose_item(const float* W, int ldw, int k0, int n0, bf16_t* WT, int ldt, int drow0, LAS float* scr, int lane) {
;     ...
;     for (int j = 0; j < 4; ++j) { const int n = (lane >> 3) + 8 * j; const LAS float* s = scr + (8 * c) * 33 + n;
;         u32x4 o; o.x = cvt_pk_bf16(s[0 * 33], s[1 * 33]); o.y = cvt_pk_bf16(s[2 * 33], s[3 * 33]); o.z = cvt_pk_bf16(s[4 * 33], s[5 * 33]); o.w = cvt_pk_bf16(s[6 * 33], s[7 * 33]);
;         *(u32x4*)(WT + (size_t)(drow0 + n) * ldt + k0 + 8 * c) = o; }
; template <bool I8 = false> __device__ __forceinline__ void transpose_item_f8(const float* W, int ldw, int k0, int n0, unsigned char* WT, int ldt, int drow0, float mul, LAS float* scr, int lane) {
;     float v_[32];
; #pragma unroll
;     for (int i = 0; i < 32; ++i) { const int kk = 2 * i + (lane >> 5); v_[i] = W[(size_t)(k0 + kk) * ldw + n0 + (lane & 31)]; }
; #pragma unroll
;     for (int i = 0; i < 32; ++i) { const int kk = 2 * i + (lane >> 5); scr[kk * 33 + (lane & 31)] = v_[i]; }
	s_waitcnt lgkmcnt(0)
	ds_read2_b32 v[42:43], v32 offset1:33
	s_add_i32 s15, s44, 0xffffe000
	s_waitcnt lgkmcnt(0)
	v_cvt_pk_bf16_f32 v42, v42, v43
	ds_read2_b32 v[44:45], v32 offset0:66 offset1:99
	s_lshl_b32 s6, s14, 1
	v_or_b32_e32 v5, s15, v31
	s_waitcnt lgkmcnt(0)
	v_cvt_pk_bf16_f32 v43, v44, v45
	ds_read2_b32 v[44:45], v32 offset0:132 offset1:165
	v_lshl_add_u64 v[48:49], v[10:11], 0, s[6:7]
	v_lshlrev_b32_e32 v6, 13, v5
	s_waitcnt lgkmcnt(0)
	v_cvt_pk_bf16_f32 v44, v44, v45
	ds_read2_b32 v[46:47], v32 offset0:198 offset1:231
	s_waitcnt lgkmcnt(0)
	v_cvt_pk_bf16_f32 v45, v46, v47
	v_lshl_add_u64 v[50:51], v[48:49], 0, v[6:7]
	ds_read2_b32 v[46:47], v32 offset0:8 offset1:41
	global_store_dwordx4 v[50:51], v[42:45], off
	v_or_b32_e32 v5, s15, v33
	v_lshlrev_b32_e32 v6, 13, v5
	s_waitcnt lgkmcnt(0)
	v_cvt_pk_bf16_f32 v42, v46, v47
	ds_read2_b32 v[44:45], v32 offset0:74 offset1:107
	s_waitcnt lgkmcnt(0)
	v_cvt_pk_bf16_f32 v43, v44, v45
	ds_read2_b32 v[44:45], v32 offset0:140 offset1:173
	s_waitcnt lgkmcnt(0)
	v_cvt_pk_bf16_f32 v44, v44, v45
	ds_read2_b32 v[46:47], v32 offset0:206 offset1:239
	s_waitcnt lgkmcnt(0)
	v_cvt_pk_bf16_f32 v45, v46, v47
	v_lshl_add_u64 v[50:51], v[48:49], 0, v[6:7]
	ds_read2_b32 v[46:47], v32 offset0:16 offset1:49
	global_store_dwordx4 v[50:51], v[42:45], off
	v_or_b32_e32 v5, s15, v34
	v_lshlrev_b32_e32 v6, 13, v5
	s_waitcnt lgkmcnt(0)
	v_cvt_pk_bf16_f32 v42, v46, v47
	ds_read2_b32 v[44:45], v32 offset0:82 offset1:115
	s_waitcnt lgkmcnt(0)
	v_cvt_pk_bf16_f32 v43, v44, v45
	ds_read2_b32 v[44:45], v32 offset0:148 offset1:181
	s_waitcnt lgkmcnt(0)
	v_cvt_pk_bf16_f32 v44, v44, v45
	ds_read2_b32 v[46:47], v32 offset0:214 offset1:247
	s_waitcnt lgkmcnt(0)
	v_cvt_pk_bf16_f32 v45, v46, v47
	v_lshl_add_u64 v[50:51], v[48:49], 0, v[6:7]
	ds_read2_b32 v[46:47], v32 offset0:24 offset1:57
	global_store_dwordx4 v[50:51], v[42:45], off
	v_or_b32_e32 v5, s15, v35
	v_lshlrev_b32_e32 v6, 13, v5
	s_waitcnt lgkmcnt(0)
	v_cvt_pk_bf16_f32 v42, v46, v47
	ds_read2_b32 v[44:45], v32 offset0:90 offset1:123
	s_waitcnt lgkmcnt(0)
	v_cvt_pk_bf16_f32 v43, v44, v45
	ds_read2_b32 v[44:45], v32 offset0:156 offset1:189
	s_waitcnt lgkmcnt(0)
	v_cvt_pk_bf16_f32 v44, v44, v45
	ds_read2_b32 v[46:47], v32 offset0:222 offset1:255
	s_waitcnt lgkmcnt(0)
	v_cvt_pk_bf16_f32 v45, v46, v47
	v_lshl_add_u64 v[46:47], v[48:49], 0, v[6:7]
	global_store_dwordx4 v[46:47], v[42:45], off
	s_waitcnt lgkmcnt(0)
	s_mov_b64 s[18:19], 0
.LBB0_37:
	s_and_b64 vcc, exec, s[18:19]
	s_cbranch_vccz .LBB0_39
	s_lshl_b32 s6, s44, 2
	s_waitcnt lgkmcnt(0)
	s_add_u32 s16, s16, s6
	v_or_b32_e32 v42, s14, v0
	s_addc_u32 s17, s17, 0
	v_lshlrev_b32_e32 v6, 2, v4
	v_lshl_add_u64 v[44:45], s[16:17], 0, v[6:7]
	v_or_b32_e32 v6, 2, v42
	v_lshlrev_b64 v[48:49], 16, v[6:7]
	v_or_b32_e32 v6, 4, v42
	v_lshlrev_b64 v[50:51], 16, v[6:7]
	v_or_b32_e32 v6, 6, v42
	v_lshlrev_b64 v[52:53], 16, v[6:7]
	v_or_b32_e32 v6, 8, v42
	v_lshlrev_b64 v[54:55], 16, v[6:7]
	v_or_b32_e32 v6, 10, v42
	v_mov_b32_e32 v43, v7
	v_lshlrev_b64 v[56:57], 16, v[6:7]
	v_or_b32_e32 v6, 12, v42
	v_lshlrev_b64 v[46:47], 16, v[42:43]
	v_lshlrev_b64 v[58:59], 16, v[6:7]
	v_or_b32_e32 v6, 14, v42
	v_lshl_add_u64 v[46:47], v[44:45], 0, v[46:47]
	v_lshlrev_b64 v[60:61], 16, v[6:7]
	v_or_b32_e32 v6, 16, v42
	v_lshl_add_u64 v[48:49], v[44:45], 0, v[48:49]
	v_lshl_add_u64 v[50:51], v[44:45], 0, v[50:51]
	v_lshl_add_u64 v[52:53], v[44:45], 0, v[52:53]
	v_lshl_add_u64 v[54:55], v[44:45], 0, v[54:55]
	v_lshl_add_u64 v[56:57], v[44:45], 0, v[56:57]
	v_lshl_add_u64 v[58:59], v[44:45], 0, v[58:59]
	v_lshl_add_u64 v[60:61], v[44:45], 0, v[60:61]
	global_load_dword v5, v[46:47], off nt
	global_load_dword v30, v[48:49], off nt
	global_load_dword v41, v[50:51], off nt
	global_load_dword v62, v[52:53], off nt
	global_load_dword v63, v[54:55], off nt
	global_load_dword v64, v[56:57], off nt
	global_load_dword v65, v[58:59], off nt
	global_load_dword v66, v[60:61], off nt
	v_lshlrev_b64 v[46:47], 16, v[6:7]
	v_or_b32_e32 v6, 18, v42
	v_lshlrev_b64 v[48:49], 16, v[6:7]
	v_or_b32_e32 v6, 20, v42
	v_lshlrev_b64 v[50:51], 16, v[6:7]
	v_or_b32_e32 v6, 22, v42
	v_lshlrev_b64 v[52:53], 16, v[6:7]
	v_or_b32_e32 v6, 24, v42
	v_lshlrev_b64 v[54:55], 16, v[6:7]
	v_or_b32_e32 v6, 26, v42
	v_lshlrev_b64 v[56:57], 16, v[6:7]
	v_or_b32_e32 v6, 28, v42
	v_lshlrev_b64 v[58:59], 16, v[6:7]
	v_or_b32_e32 v6, 30, v42
	v_lshl_add_u64 v[46:47], v[44:45], 0, v[46:47]
	v_lshlrev_b64 v[60:61], 16, v[6:7]
	v_or_b32_e32 v6, 32, v42
	v_lshl_add_u64 v[48:49], v[44:45], 0, v[48:49]
	v_lshl_add_u64 v[50:51], v[44:45], 0, v[50:51]
	v_lshl_add_u64 v[52:53], v[44:45], 0, v[52:53]
	v_lshl_add_u64 v[54:55], v[44:45], 0, v[54:55]
	v_lshl_add_u64 v[56:57], v[44:45], 0, v[56:57]
	v_lshl_add_u64 v[58:59], v[44:45], 0, v[58:59]
	v_lshl_add_u64 v[60:61], v[44:45], 0, v[60:61]
	global_load_dword v67, v[46:47], off nt
	global_load_dword v68, v[48:49], off nt
	global_load_dword v69, v[50:51], off nt
	global_load_dword v70, v[52:53], off nt
	global_load_dword v71, v[54:55], off nt
	global_load_dword v72, v[56:57], off nt
	global_load_dword v73, v[58:59], off nt
	global_load_dword v74, v[60:61], off nt
	v_lshlrev_b64 v[46:47], 16, v[6:7]
	v_or_b32_e32 v6, 34, v42
	v_lshlrev_b64 v[48:49], 16, v[6:7]
	v_or_b32_e32 v6, 36, v42
	v_lshlrev_b64 v[50:51], 16, v[6:7]
	v_or_b32_e32 v6, 38, v42
	v_lshlrev_b64 v[52:53], 16, v[6:7]
	v_or_b32_e32 v6, 40, v42
	v_lshlrev_b64 v[54:55], 16, v[6:7]
	v_or_b32_e32 v6, 42, v42
	v_lshlrev_b64 v[56:57], 16, v[6:7]
	v_or_b32_e32 v6, 44, v42
	v_lshlrev_b64 v[58:59], 16, v[6:7]
	v_or_b32_e32 v6, 46, v42
	v_lshlrev_b64 v[60:61], 16, v[6:7]
; #define LAS __attribute__((address_space(3)))
; #define LDS_WAIT() asm volatile("s_waitcnt lgkmcnt(0)" ::: "memory")
; template <bool I8 = false> __device__ __forceinline__ void transpose_item_f8(const float* W, int ldw, int k0, int n0, unsigned char* WT, int ldt, int drow0, float mul, LAS float* scr, int lane) {
;     ...
;     for (int i = 0; i < 32; ++i) { const int kk = 2 * i + (lane >> 5); v_[i] = W[(size_t)(k0 + kk) * ldw + n0 + (lane & 31)]; }
; #pragma unroll
;     for (int i = 0; i < 32; ++i) { const int kk = 2 * i + (lane >> 5); scr[kk * 33 + (lane & 31)] = v_[i]; }
;     LDS_WAIT(); asm volatile("" ::: "memory");
;     const int c = lane & 7;
; #pragma unroll
;     for (int j = 0; j < 4; ++j) { const int n = (lane >> 3) + 8 * j; const LAS float* s = scr + (8 * c) * 33 + n;
;         u32x2 o; if constexpr (I8) { o.x = pk4_i8(s[0 * 33], s[1 * 33], s[2 * 33], s[3 * 33], mul); o.y = pk4_i8(s[4 * 33], s[5 * 33], s[6 * 33], s[7 * 33], mul); }
	v_lshl_add_u64 v[46:47], v[44:45], 0, v[46:47]
	v_lshl_add_u64 v[60:61], v[44:45], 0, v[60:61]
	v_or_b32_e32 v6, 48, v42
	v_lshl_add_u64 v[48:49], v[44:45], 0, v[48:49]
	v_lshl_add_u64 v[50:51], v[44:45], 0, v[50:51]
	v_lshl_add_u64 v[52:53], v[44:45], 0, v[52:53]
	v_lshl_add_u64 v[54:55], v[44:45], 0, v[54:55]
	v_lshl_add_u64 v[56:57], v[44:45], 0, v[56:57]
	v_lshl_add_u64 v[58:59], v[44:45], 0, v[58:59]
	global_load_dword v75, v[46:47], off nt
	global_load_dword v76, v[48:49], off nt
	global_load_dword v77, v[50:51], off nt
	global_load_dword v78, v[52:53], off nt
	global_load_dword v79, v[54:55], off nt
	global_load_dword v80, v[56:57], off nt
	global_load_dword v81, v[58:59], off nt
	s_nop 0
	global_load_dword v60, v[60:61], off nt
	v_lshlrev_b64 v[46:47], 16, v[6:7]
	v_or_b32_e32 v6, 50, v42
	v_lshlrev_b64 v[48:49], 16, v[6:7]
	v_or_b32_e32 v6, 52, v42
	v_lshlrev_b64 v[50:51], 16, v[6:7]
	v_or_b32_e32 v6, 54, v42
	v_lshlrev_b64 v[52:53], 16, v[6:7]
	v_or_b32_e32 v6, 56, v42
	v_lshlrev_b64 v[54:55], 16, v[6:7]
	v_or_b32_e32 v6, 58, v42
	v_lshlrev_b64 v[56:57], 16, v[6:7]
	v_or_b32_e32 v6, 60, v42
	v_lshlrev_b64 v[58:59], 16, v[6:7]
	v_or_b32_e32 v6, 62, v42
	v_lshlrev_b64 v[42:43], 16, v[6:7]
	v_lshl_add_u64 v[46:47], v[44:45], 0, v[46:47]
	v_lshl_add_u64 v[48:49], v[44:45], 0, v[48:49]
	v_lshl_add_u64 v[42:43], v[44:45], 0, v[42:43]
	v_lshl_add_u64 v[50:51], v[44:45], 0, v[50:51]
	v_lshl_add_u64 v[52:53], v[44:45], 0, v[52:53]
	v_lshl_add_u64 v[54:55], v[44:45], 0, v[54:55]
	v_lshl_add_u64 v[56:57], v[44:45], 0, v[56:57]
	v_lshl_add_u64 v[58:59], v[44:45], 0, v[58:59]
	global_load_dword v6, v[46:47], off nt
	global_load_dword v44, v[48:49], off nt
	global_load_dword v45, v[50:51], off nt
	s_nop 0
	global_load_dword v46, v[52:53], off nt
	global_load_dword v47, v[54:55], off nt
	global_load_dword v48, v[56:57], off nt
	global_load_dword v49, v[58:59], off nt
	s_nop 0
	global_load_dword v42, v[42:43], off nt
	s_waitcnt vmcnt(30)
	ds_write2_b32 v36, v5, v30 offset1:66
	s_waitcnt vmcnt(28)
	ds_write2_b32 v36, v41, v62 offset0:132 offset1:198
	v_add_u32_e32 v5, 0x400, v36
	s_waitcnt vmcnt(26)
	ds_write2_b32 v5, v63, v64 offset0:8 offset1:74
	s_waitcnt vmcnt(24)
	ds_write2_b32 v5, v65, v66 offset0:140 offset1:206
	v_add_u32_e32 v5, 0x800, v36
	s_waitcnt vmcnt(22)
	ds_write2_b32 v5, v67, v68 offset0:16 offset1:82
	s_waitcnt vmcnt(20)
	ds_write2_b32 v5, v69, v70 offset0:148 offset1:214
	v_add_u32_e32 v5, 0xc00, v36
	s_waitcnt vmcnt(18)
	ds_write2_b32 v5, v71, v72 offset0:24 offset1:90
	s_waitcnt vmcnt(16)
	ds_write2_b32 v5, v73, v74 offset0:156 offset1:222
	v_add_u32_e32 v5, 0x1000, v36
	s_waitcnt vmcnt(14)
	ds_write2_b32 v5, v75, v76 offset0:32 offset1:98
	s_waitcnt vmcnt(12)
	ds_write2_b32 v5, v77, v78 offset0:164 offset1:230
	v_add_u32_e32 v5, 0x1400, v36
	s_waitcnt vmcnt(10)
	ds_write2_b32 v5, v79, v80 offset0:40 offset1:106
	s_waitcnt vmcnt(8)
	ds_write2_b32 v5, v81, v60 offset0:172 offset1:238
	v_add_u32_e32 v5, 0x1800, v36
	s_waitcnt vmcnt(6)
	ds_write2_b32 v5, v6, v44 offset0:48 offset1:114
	s_waitcnt vmcnt(4)
	ds_write2_b32 v5, v45, v46 offset0:180 offset1:246
	v_add_u32_e32 v5, 0x1c00, v36
	s_waitcnt vmcnt(2)
	ds_write2_b32 v5, v47, v48 offset0:56 offset1:122
	s_waitcnt vmcnt(0)
	ds_write2_b32 v5, v49, v42 offset0:188 offset1:254
	s_waitcnt lgkmcnt(0)
	ds_read2_b32 v[42:43], v32 offset1:8
	ds_read2_b32 v[46:47], v32 offset0:33 offset1:41
	ds_read2_b32 v[48:49], v32 offset0:66 offset1:74
	ds_read2_b32 v[50:51], v32 offset0:99 offset1:107
	ds_read2_b32 v[52:53], v32 offset0:132 offset1:140
	ds_read2_b32 v[56:57], v32 offset0:165 offset1:173
	ds_read2_b32 v[58:59], v32 offset0:198 offset1:206
	ds_read2_b32 v[60:61], v32 offset0:231 offset1:239
	s_waitcnt lgkmcnt(6)
	v_mul_f32_e32 v6, 0x44fe0000, v46
	v_mul_f32_e32 v5, 0x44fe0000, v42
	v_med3_f32 v6, v6, s23, v40
	s_waitcnt lgkmcnt(5)
	v_mul_f32_e32 v30, 0x44fe0000, v48
	s_waitcnt lgkmcnt(4)
	v_mul_f32_e32 v41, 0x44fe0000, v50
	v_med3_f32 v5, v5, s23, v40
	v_rndne_f32_e32 v6, v6
	v_med3_f32 v30, v30, s23, v40
	v_med3_f32 v41, v41, s23, v40
	v_rndne_f32_e32 v5, v5
	v_cvt_i32_f32_e32 v6, v6
	v_rndne_f32_e32 v30, v30
	v_rndne_f32_e32 v41, v41
	v_cvt_i32_f32_e32 v5, v5
	v_cvt_i32_f32_sdwa v30, v30 dst_sel:WORD_1 dst_unused:UNUSED_PAD src0_sel:DWORD
	v_cvt_i32_f32_e32 v41, v41
	v_lshlrev_b32_e32 v6, 8, v6
	v_and_b32_e32 v6, 0xff00, v6
	v_and_b32_e32 v30, 0xff0000, v30
	v_perm_b32 v5, v41, v5, s24
	v_or3_b32 v54, v5, v6, v30
	s_waitcnt lgkmcnt(2)
	v_mul_f32_e32 v6, 0x44fe0000, v56
	v_mul_f32_e32 v5, 0x44fe0000, v52
	v_med3_f32 v6, v6, s23, v40
	s_waitcnt lgkmcnt(1)
	v_mul_f32_e32 v30, 0x44fe0000, v58
	s_waitcnt lgkmcnt(0)
; #define LAS __attribute__((address_space(3)))
; #define LDS_WAIT() asm volatile("s_waitcnt lgkmcnt(0)" ::: "memory")
; template <bool I8 = false> __device__ __forceinline__ void transpose_item_f8(const float* W, int ldw, int k0, int n0, unsigned char* WT, int ldt, int drow0, float mul, LAS float* scr, int lane) {
;     ...
; #pragma unroll
;     for (int j = 0; j < 4; ++j) { const int n = (lane >> 3) + 8 * j; const LAS float* s = scr + (8 * c) * 33 + n;
;         u32x2 o; if constexpr (I8) { o.x = pk4_i8(s[0 * 33], s[1 * 33], s[2 * 33], s[3 * 33], mul); o.y = pk4_i8(s[4 * 33], s[5 * 33], s[6 * 33], s[7 * 33], mul); }
;         else { o.x = pk4_fp8(s[0 * 33] * mul, s[1 * 33] * mul, s[2 * 33] * mul, s[3 * 33] * mul); o.y = pk4_fp8(s[4 * 33] * mul, s[5 * 33] * mul, s[6 * 33] * mul, s[7 * 33] * mul); }
;         *(u32x2*)(WT + (size_t)(drow0 + n) * ldt + k0 + 8 * c) = o; }
;     LDS_WAIT(); asm volatile("" ::: "memory");
	v_mul_f32_e32 v41, 0x44fe0000, v60
	v_med3_f32 v5, v5, s23, v40
	v_rndne_f32_e32 v6, v6
	v_med3_f32 v30, v30, s23, v40
	v_med3_f32 v41, v41, s23, v40
	v_rndne_f32_e32 v5, v5
	v_cvt_i32_f32_e32 v6, v6
	v_rndne_f32_e32 v30, v30
	v_rndne_f32_e32 v41, v41
	v_cvt_i32_f32_e32 v5, v5
	v_cvt_i32_f32_sdwa v30, v30 dst_sel:WORD_1 dst_unused:UNUSED_PAD src0_sel:DWORD
	v_cvt_i32_f32_e32 v41, v41
	v_lshlrev_b32_e32 v6, 8, v6
	v_and_b32_e32 v6, 0xff00, v6
	v_and_b32_e32 v30, 0xff0000, v30
	v_perm_b32 v5, v41, v5, s24
	s_mov_b32 s15, s7
	v_or3_b32 v55, v5, v6, v30
	v_or_b32_e32 v5, s44, v31
	v_lshl_add_u64 v[44:45], v[12:13], 0, s[14:15]
	v_lshlrev_b32_e32 v6, 12, v5
	v_lshl_add_u64 v[62:63], v[44:45], 0, v[6:7]
	v_mul_f32_e32 v6, 0x44fe0000, v47
	v_mul_f32_e32 v5, 0x44fe0000, v43
	v_med3_f32 v6, v6, s23, v40
	v_mul_f32_e32 v30, 0x44fe0000, v49
	v_mul_f32_e32 v41, 0x44fe0000, v51
	v_med3_f32 v5, v5, s23, v40
	v_rndne_f32_e32 v6, v6
	v_med3_f32 v30, v30, s23, v40
	v_med3_f32 v41, v41, s23, v40
	v_rndne_f32_e32 v5, v5
	v_cvt_i32_f32_e32 v6, v6
	v_rndne_f32_e32 v30, v30
	v_rndne_f32_e32 v41, v41
	v_cvt_i32_f32_e32 v5, v5
	v_cvt_i32_f32_sdwa v30, v30 dst_sel:WORD_1 dst_unused:UNUSED_PAD src0_sel:DWORD
	v_cvt_i32_f32_e32 v41, v41
	v_lshlrev_b32_e32 v6, 8, v6
	v_and_b32_e32 v6, 0xff00, v6
	v_and_b32_e32 v30, 0xff0000, v30
	v_perm_b32 v5, v41, v5, s24
	v_or3_b32 v42, v5, v6, v30
	v_mul_f32_e32 v6, 0x44fe0000, v57
	v_mul_f32_e32 v5, 0x44fe0000, v53
	v_med3_f32 v6, v6, s23, v40
	v_mul_f32_e32 v30, 0x44fe0000, v59
	v_mul_f32_e32 v41, 0x44fe0000, v61
	v_med3_f32 v5, v5, s23, v40
	v_rndne_f32_e32 v6, v6
	v_med3_f32 v30, v30, s23, v40
	v_med3_f32 v41, v41, s23, v40
	v_rndne_f32_e32 v5, v5
	v_cvt_i32_f32_e32 v6, v6
	v_rndne_f32_e32 v30, v30
	v_rndne_f32_e32 v41, v41
	v_cvt_i32_f32_e32 v5, v5
	v_cvt_i32_f32_sdwa v30, v30 dst_sel:WORD_1 dst_unused:UNUSED_PAD src0_sel:DWORD
	v_cvt_i32_f32_e32 v41, v41
	v_lshlrev_b32_e32 v6, 8, v6
	v_and_b32_e32 v6, 0xff00, v6
	v_and_b32_e32 v30, 0xff0000, v30
	v_perm_b32 v5, v41, v5, s24
	v_or3_b32 v43, v5, v6, v30
	v_or_b32_e32 v5, s44, v33
	v_lshlrev_b32_e32 v6, 12, v5
	v_lshl_add_u64 v[46:47], v[44:45], 0, v[6:7]
	global_store_dwordx2 v[62:63], v[54:55], off
	global_store_dwordx2 v[46:47], v[42:43], off
	ds_read2_b32 v[48:49], v32 offset0:16 offset1:24
	ds_read2_b32 v[42:43], v32 offset0:49 offset1:57
	ds_read2_b32 v[46:47], v32 offset0:82 offset1:90
	ds_read2_b32 v[50:51], v32 offset0:115 offset1:123
	ds_read2_b32 v[52:53], v32 offset0:148 offset1:156
	ds_read2_b32 v[56:57], v32 offset0:181 offset1:189
	ds_read2_b32 v[58:59], v32 offset0:214 offset1:222
	ds_read2_b32 v[60:61], v32 offset0:247 offset1:255
	s_waitcnt lgkmcnt(6)
	v_mul_f32_e32 v6, 0x44fe0000, v42
	v_mul_f32_e32 v5, 0x44fe0000, v48
	v_med3_f32 v6, v6, s23, v40
	s_waitcnt lgkmcnt(5)
	v_mul_f32_e32 v30, 0x44fe0000, v46
	s_waitcnt lgkmcnt(4)
	v_mul_f32_e32 v41, 0x44fe0000, v50
	v_med3_f32 v5, v5, s23, v40
	v_rndne_f32_e32 v6, v6
	v_med3_f32 v30, v30, s23, v40
	v_med3_f32 v41, v41, s23, v40
	v_rndne_f32_e32 v5, v5
	v_cvt_i32_f32_e32 v6, v6
	v_rndne_f32_e32 v30, v30
	v_rndne_f32_e32 v41, v41
	v_cvt_i32_f32_e32 v5, v5
	v_cvt_i32_f32_sdwa v30, v30 dst_sel:WORD_1 dst_unused:UNUSED_PAD src0_sel:DWORD
	v_cvt_i32_f32_e32 v41, v41
	v_lshlrev_b32_e32 v6, 8, v6
	v_and_b32_e32 v6, 0xff00, v6
	v_and_b32_e32 v30, 0xff0000, v30
	v_perm_b32 v5, v41, v5, s24
	v_or3_b32 v54, v5, v6, v30
	s_waitcnt lgkmcnt(2)
	v_mul_f32_e32 v6, 0x44fe0000, v56
	v_mul_f32_e32 v5, 0x44fe0000, v52
	v_med3_f32 v6, v6, s23, v40
	s_waitcnt lgkmcnt(1)
	v_mul_f32_e32 v30, 0x44fe0000, v58
	s_waitcnt lgkmcnt(0)
	v_mul_f32_e32 v41, 0x44fe0000, v60
	v_med3_f32 v5, v5, s23, v40
	v_rndne_f32_e32 v6, v6
	v_med3_f32 v30, v30, s23, v40
	v_med3_f32 v41, v41, s23, v40
	v_rndne_f32_e32 v5, v5
	v_cvt_i32_f32_e32 v6, v6
	v_rndne_f32_e32 v30, v30
	v_rndne_f32_e32 v41, v41
	v_cvt_i32_f32_e32 v5, v5
	v_cvt_i32_f32_sdwa v30, v30 dst_sel:WORD_1 dst_unused:UNUSED_PAD src0_sel:DWORD
	v_cvt_i32_f32_e32 v41, v41
	v_lshlrev_b32_e32 v6, 8, v6
	v_and_b32_e32 v6, 0xff00, v6
	v_and_b32_e32 v30, 0xff0000, v30
	v_perm_b32 v5, v41, v5, s24
	v_or3_b32 v55, v5, v6, v30
	v_or_b32_e32 v5, s44, v34
	v_lshlrev_b32_e32 v6, 12, v5
	v_lshl_add_u64 v[62:63], v[44:45], 0, v[6:7]
	v_mul_f32_e32 v6, 0x44fe0000, v43
	v_mul_f32_e32 v5, 0x44fe0000, v49
	v_med3_f32 v6, v6, s23, v40
	v_mul_f32_e32 v30, 0x44fe0000, v47
	v_mul_f32_e32 v41, 0x44fe0000, v51
	v_med3_f32 v5, v5, s23, v40
	v_rndne_f32_e32 v6, v6
	v_med3_f32 v30, v30, s23, v40
	v_med3_f32 v41, v41, s23, v40
	v_rndne_f32_e32 v5, v5
	v_cvt_i32_f32_e32 v6, v6
	v_rndne_f32_e32 v30, v30
	v_rndne_f32_e32 v41, v41
	v_cvt_i32_f32_e32 v5, v5
	v_cvt_i32_f32_sdwa v30, v30 dst_sel:WORD_1 dst_unused:UNUSED_PAD src0_sel:DWORD
	v_cvt_i32_f32_e32 v41, v41
	v_lshlrev_b32_e32 v6, 8, v6
	v_and_b32_e32 v6, 0xff00, v6
	v_and_b32_e32 v30, 0xff0000, v30
	v_perm_b32 v5, v41, v5, s24
	v_or3_b32 v42, v5, v6, v30
	v_mul_f32_e32 v6, 0x44fe0000, v57
	v_mul_f32_e32 v5, 0x44fe0000, v53
	v_med3_f32 v6, v6, s23, v40
	v_mul_f32_e32 v30, 0x44fe0000, v59
	v_mul_f32_e32 v41, 0x44fe0000, v61
	v_med3_f32 v5, v5, s23, v40
	v_rndne_f32_e32 v6, v6
	v_med3_f32 v30, v30, s23, v40
	v_med3_f32 v41, v41, s23, v40
	v_rndne_f32_e32 v5, v5
	v_cvt_i32_f32_e32 v6, v6
	v_rndne_f32_e32 v30, v30
	v_rndne_f32_e32 v41, v41
	v_cvt_i32_f32_e32 v5, v5
	v_cvt_i32_f32_sdwa v30, v30 dst_sel:WORD_1 dst_unused:UNUSED_PAD src0_sel:DWORD
	v_cvt_i32_f32_e32 v41, v41
	v_lshlrev_b32_e32 v6, 8, v6
	v_and_b32_e32 v6, 0xff00, v6
	v_and_b32_e32 v30, 0xff0000, v30
	v_perm_b32 v5, v41, v5, s24
	v_or3_b32 v43, v5, v6, v30
	v_or_b32_e32 v5, s44, v35
	v_lshlrev_b32_e32 v6, 12, v5
	v_lshl_add_u64 v[44:45], v[44:45], 0, v[6:7]
	global_store_dwordx2 v[62:63], v[54:55], off
	global_store_dwordx2 v[44:45], v[42:43], off
	s_waitcnt lgkmcnt(0)

; #define LAS __attribute__((address_space(3)))
; #define LDS_WAIT() asm volatile("s_waitcnt lgkmcnt(0)" ::: "memory")
; __device__ __forceinline__ void transpose_item_h32_i8(const float* W, int ldw, int k0, int n0, unsigned char* WT, int ldt, int drow0, float qs, LAS float* scr, int lane) {
;     float v_[32];
; #pragma unroll
;     for (int i = 0; i < 32; ++i) { const int kk = 2 * i + (lane >> 5); v_[i] = W[(size_t)(k0 + kk) * ldw + n0 + (lane & 31)]; }
; #pragma unroll
;     for (int i = 0; i < 32; ++i) { const int kk = 2 * i + (lane >> 5); scr[kk * 33 + (lane & 31)] = v_[i]; }
;     LDS_WAIT(); asm volatile("" ::: "memory");
.LBB0_40:
	s_andn2_b64 vcc, exec, s[14:15]
	s_cbranch_vccnz .LBB0_42
	s_add_i32 s6, s43, 0xffff1780
	s_waitcnt lgkmcnt(0)
	s_load_dwordx2 s[16:17], s[12:13], 0x88
	s_lshr_b32 s6, s6, 1
	s_and_b32 s6, s6, 0x7fffffc0
	s_lshl_b32 s14, s43, 5
	v_or_b32_e32 v5, s6, v0
	s_and_b32 s14, s14, 0xfe0
	v_lshlrev_b32_e32 v5, 12, v5
	v_or3_b32 v6, v4, v5, s14
	s_waitcnt lgkmcnt(0)
	v_lshl_add_u64 v[42:43], v[6:7], 2, s[16:17]
	v_add_co_u32_e32 v44, vcc, 0x8000, v42
	s_nop 1
	v_addc_co_u32_e32 v45, vcc, 0, v43, vcc
	v_add_co_u32_e32 v46, vcc, 0x10000, v42
	s_nop 1
	v_addc_co_u32_e32 v47, vcc, 0, v43, vcc
	v_add_co_u32_e32 v48, vcc, 0x18000, v42
	s_nop 1
	v_addc_co_u32_e32 v49, vcc, 0, v43, vcc
	v_add_co_u32_e32 v50, vcc, 0x20000, v42
	s_nop 1
	v_addc_co_u32_e32 v51, vcc, 0, v43, vcc
	v_add_co_u32_e32 v52, vcc, 0x28000, v42
	s_nop 1
	v_addc_co_u32_e32 v53, vcc, 0, v43, vcc
	v_add_co_u32_e32 v54, vcc, 0x30000, v42
	s_nop 1
	v_addc_co_u32_e32 v55, vcc, 0, v43, vcc
	v_add_co_u32_e32 v56, vcc, 0x38000, v42
	s_nop 1
	v_addc_co_u32_e32 v57, vcc, 0, v43, vcc
	global_load_dword v5, v[42:43], off nt
	global_load_dword v6, v[44:45], off nt
	global_load_dword v30, v[46:47], off nt
	global_load_dword v41, v[48:49], off nt
	global_load_dword v60, v[50:51], off nt
	global_load_dword v61, v[52:53], off nt
	global_load_dword v62, v[54:55], off nt
	global_load_dword v63, v[56:57], off nt
	v_add_co_u32_e32 v44, vcc, 0x40000, v42
	s_nop 1
	v_addc_co_u32_e32 v45, vcc, 0, v43, vcc
	v_add_co_u32_e32 v46, vcc, 0x48000, v42
	s_nop 1
	v_addc_co_u32_e32 v47, vcc, 0, v43, vcc
	v_add_co_u32_e32 v48, vcc, 0x50000, v42
	s_nop 1
	v_addc_co_u32_e32 v49, vcc, 0, v43, vcc
	v_add_co_u32_e32 v50, vcc, 0x58000, v42
	s_nop 1
	v_addc_co_u32_e32 v51, vcc, 0, v43, vcc
	v_add_co_u32_e32 v52, vcc, 0x60000, v42
	s_nop 1
	v_addc_co_u32_e32 v53, vcc, 0, v43, vcc
	v_add_co_u32_e32 v54, vcc, 0x68000, v42
	s_nop 1
	v_addc_co_u32_e32 v55, vcc, 0, v43, vcc
	v_add_co_u32_e32 v56, vcc, 0x70000, v42
	s_nop 1
	v_addc_co_u32_e32 v57, vcc, 0, v43, vcc
	v_add_co_u32_e32 v58, vcc, 0x78000, v42
	s_nop 1
	v_addc_co_u32_e32 v59, vcc, 0, v43, vcc
	global_load_dword v64, v[44:45], off nt
	global_load_dword v65, v[46:47], off nt
	global_load_dword v66, v[48:49], off nt
	global_load_dword v67, v[50:51], off nt
	global_load_dword v68, v[52:53], off nt
	global_load_dword v69, v[54:55], off nt
	global_load_dword v70, v[56:57], off nt
	global_load_dword v71, v[58:59], off nt
	v_add_co_u32_e32 v44, vcc, 0x80000, v42
	s_nop 1
	v_addc_co_u32_e32 v45, vcc, 0, v43, vcc
	v_add_co_u32_e32 v46, vcc, 0x88000, v42
	s_nop 1
	v_addc_co_u32_e32 v47, vcc, 0, v43, vcc
	v_add_co_u32_e32 v48, vcc, 0x90000, v42
	s_nop 1
	v_addc_co_u32_e32 v49, vcc, 0, v43, vcc
	v_add_co_u32_e32 v50, vcc, 0x98000, v42
	s_nop 1
	v_addc_co_u32_e32 v51, vcc, 0, v43, vcc
	v_add_co_u32_e32 v52, vcc, 0xa0000, v42
	s_nop 1
	v_addc_co_u32_e32 v53, vcc, 0, v43, vcc
	v_add_co_u32_e32 v54, vcc, 0xa8000, v42
	s_nop 1
	v_addc_co_u32_e32 v55, vcc, 0, v43, vcc
	v_add_co_u32_e32 v56, vcc, 0xb0000, v42
	s_nop 1
	v_addc_co_u32_e32 v57, vcc, 0, v43, vcc
	v_add_co_u32_e32 v58, vcc, 0xb8000, v42
	s_nop 1
	v_addc_co_u32_e32 v59, vcc, 0, v43, vcc
	global_load_dword v72, v[44:45], off nt
	global_load_dword v73, v[46:47], off nt
	global_load_dword v74, v[48:49], off nt
	global_load_dword v75, v[50:51], off nt
	global_load_dword v76, v[52:53], off nt
	global_load_dword v77, v[54:55], off nt
	global_load_dword v78, v[56:57], off nt
	s_nop 0
	global_load_dword v58, v[58:59], off nt
	v_add_co_u32_e32 v44, vcc, 0xc0000, v42
	s_nop 1
	v_addc_co_u32_e32 v45, vcc, 0, v43, vcc
	v_add_co_u32_e32 v46, vcc, 0xc8000, v42
	s_nop 1
	v_addc_co_u32_e32 v47, vcc, 0, v43, vcc
	v_add_co_u32_e32 v48, vcc, 0xd0000, v42
	s_nop 1
	v_addc_co_u32_e32 v49, vcc, 0, v43, vcc
	v_add_co_u32_e32 v50, vcc, 0xd8000, v42
	s_nop 1
	v_addc_co_u32_e32 v51, vcc, 0, v43, vcc
	v_add_co_u32_e32 v52, vcc, 0xe0000, v42
	s_nop 1
	v_addc_co_u32_e32 v53, vcc, 0, v43, vcc
	v_add_co_u32_e32 v54, vcc, 0xe8000, v42
	s_nop 1
	v_addc_co_u32_e32 v55, vcc, 0, v43, vcc
	v_add_co_u32_e32 v56, vcc, 0xf0000, v42
	s_nop 1
	v_addc_co_u32_e32 v57, vcc, 0, v43, vcc
	v_add_co_u32_e32 v42, vcc, 0xf8000, v42
	s_nop 1
	v_addc_co_u32_e32 v43, vcc, 0, v43, vcc
	global_load_dword v44, v[44:45], off nt
	s_nop 0
	global_load_dword v45, v[46:47], off nt
	s_nop 0
	global_load_dword v46, v[48:49], off nt
	global_load_dword v47, v[50:51], off nt
	s_nop 0
	global_load_dword v48, v[52:53], off nt
	global_load_dword v49, v[54:55], off nt
	global_load_dword v50, v[56:57], off nt
	s_nop 0
	global_load_dword v42, v[42:43], off nt
	s_waitcnt vmcnt(30)
	ds_write2_b32 v36, v5, v6 offset1:66
	s_waitcnt vmcnt(28)
	ds_write2_b32 v36, v30, v41 offset0:132 offset1:198
	v_add_u32_e32 v5, 0x400, v36
	s_waitcnt vmcnt(26)
	ds_write2_b32 v5, v60, v61 offset0:8 offset1:74
	s_waitcnt vmcnt(24)
	ds_write2_b32 v5, v62, v63 offset0:140 offset1:206
	v_add_u32_e32 v5, 0x800, v36
	s_waitcnt vmcnt(22)
	ds_write2_b32 v5, v64, v65 offset0:16 offset1:82
	s_waitcnt vmcnt(20)
	ds_write2_b32 v5, v66, v67 offset0:148 offset1:214
	v_add_u32_e32 v5, 0xc00, v36
	s_waitcnt vmcnt(18)
	ds_write2_b32 v5, v68, v69 offset0:24 offset1:90
	s_waitcnt vmcnt(16)
	ds_write2_b32 v5, v70, v71 offset0:156 offset1:222
	v_add_u32_e32 v5, 0x1000, v36
	s_waitcnt vmcnt(14)
	ds_write2_b32 v5, v72, v73 offset0:32 offset1:98
	s_waitcnt vmcnt(12)
	ds_write2_b32 v5, v74, v75 offset0:164 offset1:230
	v_add_u32_e32 v5, 0x1400, v36
	s_waitcnt vmcnt(10)
	ds_write2_b32 v5, v76, v77 offset0:40 offset1:106
	s_waitcnt vmcnt(8)
	ds_write2_b32 v5, v78, v58 offset0:172 offset1:238
	v_add_u32_e32 v5, 0x1800, v36
	s_waitcnt vmcnt(6)
; __device__ __forceinline__ void transpose_item_h32_i8(const float* W, int ldw, int k0, int n0, unsigned char* WT, int ldt, int drow0, float qs, LAS float* scr, int lane) {
;     ...
;     { const int n = lane & 31, kb = (lane >> 5) * 32;
;       float c_[32];
; #pragma unroll
;       for (int k = 0; k < 32; ++k) c_[k] = scr[(kb + k) * 33 + n];
; #pragma unroll
;       for (int s_ = 1; s_ < 32; s_ <<= 1)
; #pragma unroll
;           for (int i = 0; i < 32; ++i) if ((i & s_) == 0) { const float a = c_[i], b = c_[i | s_]; c_[i] = a + b; c_[i | s_] = a - b; }
; #pragma unroll
;       for (int k = 0; k < 32; ++k) scr[(kb + k) * 33 + n] = c_[k] * 0.17677669529663689f; }
	ds_write2_b32 v5, v44, v45 offset0:48 offset1:114
	s_waitcnt vmcnt(4)
	ds_write2_b32 v5, v46, v47 offset0:180 offset1:246
	v_add_u32_e32 v5, 0x1c00, v36
	s_waitcnt vmcnt(2)
	ds_write2_b32 v5, v48, v49 offset0:56 offset1:122
	s_waitcnt vmcnt(0)
	ds_write2_b32 v5, v50, v42 offset0:188 offset1:254
	s_waitcnt lgkmcnt(0)
	v_add_u32_e32 v5, 0x400, v38
	v_add_u32_e32 v6, 0x800, v38
	v_add_u32_e32 v30, 0xc00, v38
	ds_read2_b32 v[42:43], v38 offset1:33
	ds_read2_b32 v[44:45], v38 offset0:66 offset1:99
	ds_read2_b32 v[46:47], v38 offset0:132 offset1:165
	ds_read2_b32 v[48:49], v38 offset0:198 offset1:231
	ds_read2_b32 v[50:51], v5 offset0:8 offset1:41
	ds_read2_b32 v[52:53], v5 offset0:74 offset1:107
	ds_read2_b32 v[54:55], v5 offset0:140 offset1:173
	ds_read2_b32 v[56:57], v5 offset0:206 offset1:239
	ds_read2_b32 v[58:59], v6 offset0:16 offset1:49
	ds_read2_b32 v[60:61], v6 offset0:82 offset1:115
	ds_read2_b32 v[62:63], v6 offset0:148 offset1:181
	ds_read2_b32 v[64:65], v6 offset0:214 offset1:247
	ds_read2_b32 v[66:67], v30 offset0:24 offset1:57
	ds_read2_b32 v[68:69], v30 offset0:90 offset1:123
	ds_read2_b32 v[70:71], v30 offset0:156 offset1:189
	ds_read_b32 v41, v38 offset:3960
	ds_read_b32 v72, v39
	s_waitcnt lgkmcnt(14)
	v_add_f32_e32 v73, v42, v43
	v_add_f32_e32 v74, v44, v45
	v_add_f32_e32 v76, v46, v47
	s_waitcnt lgkmcnt(13)
	v_add_f32_e32 v77, v48, v49
	s_waitcnt lgkmcnt(12)
	v_add_f32_e32 v80, v50, v51
	s_waitcnt lgkmcnt(11)
	v_add_f32_e32 v81, v52, v53
	s_waitcnt lgkmcnt(10)
	v_add_f32_e32 v84, v54, v55
	s_waitcnt lgkmcnt(9)
	v_add_f32_e32 v85, v56, v57
	s_waitcnt lgkmcnt(8)
	v_add_f32_e32 v89, v58, v59
	s_waitcnt lgkmcnt(7)
	v_add_f32_e32 v90, v60, v61
	s_waitcnt lgkmcnt(6)
	v_add_f32_e32 v92, v62, v63
	s_waitcnt lgkmcnt(5)
	v_add_f32_e32 v93, v64, v65
	s_waitcnt lgkmcnt(4)
	v_add_f32_e32 v96, v66, v67
	s_waitcnt lgkmcnt(3)
	v_add_f32_e32 v97, v68, v69
	s_waitcnt lgkmcnt(2)
	v_add_f32_e32 v99, v70, v71
	s_waitcnt lgkmcnt(0)
	v_add_f32_e32 v100, v41, v72
	v_sub_f32_e32 v42, v42, v43
	v_sub_f32_e32 v43, v44, v45
	v_sub_f32_e32 v45, v46, v47
	v_sub_f32_e32 v46, v48, v49
	v_sub_f32_e32 v49, v50, v51
	v_sub_f32_e32 v50, v52, v53
	v_sub_f32_e32 v52, v54, v55
	v_sub_f32_e32 v53, v56, v57
	v_sub_f32_e32 v57, v58, v59
	v_sub_f32_e32 v58, v60, v61
	v_sub_f32_e32 v60, v62, v63
	v_sub_f32_e32 v61, v64, v65
	v_sub_f32_e32 v64, v66, v67
	v_sub_f32_e32 v65, v68, v69
	v_sub_f32_e32 v67, v70, v71
	v_sub_f32_e32 v41, v41, v72
	v_add_f32_e32 v75, v73, v74
	v_add_f32_e32 v78, v76, v77
	v_add_f32_e32 v82, v80, v81
	v_add_f32_e32 v86, v84, v85
	v_add_f32_e32 v91, v89, v90
	v_add_f32_e32 v94, v92, v93
	v_add_f32_e32 v98, v96, v97
	v_add_f32_e32 v101, v99, v100
	v_add_f32_e32 v44, v42, v43
	v_add_f32_e32 v47, v45, v46
	v_add_f32_e32 v51, v49, v50
	v_add_f32_e32 v54, v52, v53
	v_add_f32_e32 v59, v57, v58
	v_add_f32_e32 v62, v60, v61
	v_add_f32_e32 v66, v64, v65
	v_add_f32_e32 v68, v67, v41
	v_add_f32_e32 v79, v75, v78
	v_add_f32_e32 v87, v82, v86
	v_add_f32_e32 v95, v91, v94
	v_add_f32_e32 v102, v98, v101
	v_add_f32_e32 v48, v44, v47
	v_add_f32_e32 v55, v51, v54
	v_add_f32_e32 v63, v59, v62
	v_add_f32_e32 v69, v66, v68
	v_sub_f32_e32 v72, v73, v74
	v_sub_f32_e32 v73, v76, v77
	v_sub_f32_e32 v76, v80, v81
	v_sub_f32_e32 v77, v84, v85
	v_sub_f32_e32 v84, v89, v90
	v_sub_f32_e32 v85, v92, v93
	v_sub_f32_e32 v90, v96, v97
	v_sub_f32_e32 v92, v99, v100
	v_sub_f32_e32 v42, v42, v43
	v_sub_f32_e32 v43, v45, v46
	v_sub_f32_e32 v46, v49, v50
	v_sub_f32_e32 v49, v52, v53
	v_sub_f32_e32 v53, v57, v58
	v_sub_f32_e32 v57, v60, v61
	v_sub_f32_e32 v60, v64, v65
	v_sub_f32_e32 v41, v67, v41
	v_add_f32_e32 v88, v79, v87
	v_add_f32_e32 v103, v95, v102
	v_add_f32_e32 v56, v48, v55
	v_add_f32_e32 v70, v63, v69
	v_add_f32_e32 v74, v72, v73
	v_add_f32_e32 v80, v76, v77
	v_add_f32_e32 v89, v84, v85
	v_add_f32_e32 v93, v90, v92
	v_add_f32_e32 v45, v42, v43
	v_add_f32_e32 v50, v46, v49
	v_add_f32_e32 v58, v53, v57
	v_add_f32_e32 v61, v60, v41
	v_sub_f32_e32 v44, v44, v47
	v_sub_f32_e32 v47, v51, v54
	v_sub_f32_e32 v54, v59, v62
	v_sub_f32_e32 v59, v66, v68
	v_sub_f32_e32 v68, v72, v73
	v_sub_f32_e32 v72, v76, v77
	v_sub_f32_e32 v76, v84, v85
	v_sub_f32_e32 v77, v90, v92
	v_sub_f32_e32 v42, v42, v43
	v_sub_f32_e32 v43, v46, v49
	v_sub_f32_e32 v49, v53, v57
	v_sub_f32_e32 v41, v60, v41
	v_add_f32_e32 v104, v88, v103
	v_add_f32_e32 v71, v56, v70
	v_add_f32_e32 v81, v74, v80
	v_add_f32_e32 v96, v89, v93
	v_add_f32_e32 v52, v45, v50
	v_add_f32_e32 v64, v58, v61
	v_sub_f32_e32 v67, v75, v78
	v_sub_f32_e32 v75, v82, v86
	v_sub_f32_e32 v82, v91, v94
	v_sub_f32_e32 v86, v98, v101
	v_add_f32_e32 v51, v44, v47
	v_add_f32_e32 v62, v54, v59
	v_add_f32_e32 v73, v68, v72
	v_add_f32_e32 v46, v42, v43
	v_add_f32_e32 v53, v49, v41
	v_sub_f32_e32 v44, v44, v47
	v_sub_f32_e32 v47, v54, v59
	v_sub_f32_e32 v59, v68, v72
	v_sub_f32_e32 v68, v76, v77
	v_sub_f32_e32 v42, v42, v43
	v_sub_f32_e32 v41, v49, v41
	v_add_f32_e32 v97, v81, v96
	v_add_f32_e32 v65, v52, v64
	v_add_f32_e32 v78, v67, v75
	v_add_f32_e32 v91, v82, v86
	v_add_f32_e32 v54, v44, v47
	v_add_f32_e32 v72, v59, v68
	v_add_f32_e32 v43, v42, v41
	v_sub_f32_e32 v44, v44, v47
	v_sub_f32_e32 v47, v59, v68
	v_sub_f32_e32 v41, v42, v41
	v_mul_f32_e32 v42, 0x3e3504f3, v104
	v_mul_f32_e32 v59, 0x3e3504f3, v71
	v_add_f32_e32 v94, v78, v91
	v_add_f32_e32 v66, v51, v62
	v_add_f32_e32 v84, v76, v77
	ds_write2_b32 v38, v42, v59 offset1:33
	v_mul_f32_e32 v42, 0x3e3504f3, v97
	v_mul_f32_e32 v59, 0x3e3504f3, v65
	v_add_f32_e32 v85, v73, v84
	v_add_f32_e32 v57, v46, v53
	v_sub_f32_e32 v60, v79, v87
	v_sub_f32_e32 v79, v95, v102
	v_sub_f32_e32 v48, v48, v55
; #define LAS __attribute__((address_space(3)))
; #define LDS_WAIT() asm volatile("s_waitcnt lgkmcnt(0)" ::: "memory")
; __device__ __forceinline__ void transpose_item_h32_i8(const float* W, int ldw, int k0, int n0, unsigned char* WT, int ldt, int drow0, float qs, LAS float* scr, int lane) {
;     ...
;       for (int s_ = 1; s_ < 32; s_ <<= 1)
; #pragma unroll
;           for (int i = 0; i < 32; ++i) if ((i & s_) == 0) { const float a = c_[i], b = c_[i | s_]; c_[i] = a + b; c_[i | s_] = a - b; }
; #pragma unroll
;       for (int k = 0; k < 32; ++k) scr[(kb + k) * 33 + n] = c_[k] * 0.17677669529663689f; }
;     LDS_WAIT(); asm volatile("" ::: "memory");
;     const int c = lane & 7;
; #pragma unroll
;     for (int j = 0; j < 4; ++j) { const int n = (lane >> 3) + 8 * j; const LAS float* s = scr + (8 * c) * 33 + n;
;         u32x2 o; o.x = pk4_i8(s[0 * 33], s[1 * 33], s[2 * 33], s[3 * 33], qs); o.y = pk4_i8(s[4 * 33], s[5 * 33], s[6 * 33], s[7 * 33], qs);
	v_sub_f32_e32 v55, v63, v69
	ds_write2_b32 v38, v42, v59 offset0:66 offset1:99
	v_mul_f32_e32 v42, 0x3e3504f3, v94
	v_mul_f32_e32 v59, 0x3e3504f3, v66
	v_add_f32_e32 v87, v60, v79
	v_add_f32_e32 v63, v48, v55
	v_sub_f32_e32 v69, v74, v80
	v_sub_f32_e32 v74, v89, v93
	v_sub_f32_e32 v45, v45, v50
	v_sub_f32_e32 v50, v58, v61
	ds_write2_b32 v38, v42, v59 offset0:132 offset1:165
	v_mul_f32_e32 v42, 0x3e3504f3, v85
	v_mul_f32_e32 v57, 0x3e3504f3, v57
	v_add_f32_e32 v80, v69, v74
	v_add_f32_e32 v58, v45, v50
	v_sub_f32_e32 v61, v67, v75
	v_sub_f32_e32 v67, v82, v86
	ds_write2_b32 v38, v42, v57 offset0:198 offset1:231
	v_mul_f32_e32 v42, 0x3e3504f3, v87
	v_mul_f32_e32 v57, 0x3e3504f3, v63
	v_add_f32_e32 v75, v61, v67
	ds_write2_b32 v5, v42, v57 offset0:8 offset1:41
	v_mul_f32_e32 v42, 0x3e3504f3, v80
	v_mul_f32_e32 v57, 0x3e3504f3, v58
	ds_write2_b32 v5, v42, v57 offset0:74 offset1:107
	v_mul_f32_e32 v42, 0x3e3504f3, v75
	v_mul_f32_e32 v54, 0x3e3504f3, v54
	v_sub_f32_e32 v49, v88, v103
	v_sub_f32_e32 v56, v56, v70
	ds_write2_b32 v5, v42, v54 offset0:140 offset1:173
	v_mul_f32_e32 v42, 0x3e3504f3, v72
	v_mul_f32_e32 v43, 0x3e3504f3, v43
	v_sub_f32_e32 v70, v81, v96
	v_sub_f32_e32 v52, v52, v64
	ds_write2_b32 v5, v42, v43 offset0:206 offset1:239
	v_mul_f32_e32 v5, 0x3e3504f3, v49
	v_mul_f32_e32 v42, 0x3e3504f3, v56
	v_sub_f32_e32 v64, v78, v91
	v_sub_f32_e32 v51, v51, v62
	ds_write2_b32 v6, v5, v42 offset0:16 offset1:49
	v_mul_f32_e32 v5, 0x3e3504f3, v70
	v_mul_f32_e32 v42, 0x3e3504f3, v52
	v_sub_f32_e32 v62, v73, v84
	v_sub_f32_e32 v46, v46, v53
	ds_write2_b32 v6, v5, v42 offset0:82 offset1:115
	v_mul_f32_e32 v5, 0x3e3504f3, v64
	v_mul_f32_e32 v42, 0x3e3504f3, v51
	v_sub_f32_e32 v53, v60, v79
	v_sub_f32_e32 v48, v48, v55
	ds_write2_b32 v6, v5, v42 offset0:148 offset1:181
	v_mul_f32_e32 v5, 0x3e3504f3, v62
	v_mul_f32_e32 v42, 0x3e3504f3, v46
	v_sub_f32_e32 v55, v69, v74
	v_sub_f32_e32 v45, v45, v50
	ds_write2_b32 v6, v5, v42 offset0:214 offset1:247
	v_mul_f32_e32 v5, 0x3e3504f3, v53
	v_mul_f32_e32 v6, 0x3e3504f3, v48
	v_sub_f32_e32 v50, v61, v67
	ds_write2_b32 v30, v5, v6 offset0:24 offset1:57
	v_mul_f32_e32 v5, 0x3e3504f3, v55
	v_mul_f32_e32 v6, 0x3e3504f3, v45
	ds_write2_b32 v30, v5, v6 offset0:90 offset1:123
	v_mul_f32_e32 v5, 0x3e3504f3, v50
	v_mul_f32_e32 v6, 0x3e3504f3, v44
	ds_write2_b32 v30, v5, v6 offset0:156 offset1:189
	v_mul_f32_e32 v5, 0x3e3504f3, v47
	ds_write_b32 v38, v5 offset:3960
	v_mul_f32_e32 v5, 0x3e3504f3, v41
	ds_write_b32 v39, v5
	s_waitcnt lgkmcnt(0)
	ds_read2_b32 v[42:43], v32 offset1:8
	ds_read2_b32 v[46:47], v32 offset0:33 offset1:41
	ds_read2_b32 v[48:49], v32 offset0:66 offset1:74
	ds_read2_b32 v[50:51], v32 offset0:99 offset1:107
	ds_read2_b32 v[52:53], v32 offset0:132 offset1:140
	ds_read2_b32 v[56:57], v32 offset0:165 offset1:173
	ds_read2_b32 v[58:59], v32 offset0:198 offset1:206
	ds_read2_b32 v[60:61], v32 offset0:231 offset1:239
	s_waitcnt lgkmcnt(6)
	v_mul_f32_e32 v6, 0x44fe0000, v46
	v_mul_f32_e32 v5, 0x44fe0000, v42
	v_med3_f32 v6, v6, s23, v40
	s_waitcnt lgkmcnt(5)
	v_mul_f32_e32 v30, 0x44fe0000, v48
	s_waitcnt lgkmcnt(4)
	v_mul_f32_e32 v41, 0x44fe0000, v50
	v_med3_f32 v5, v5, s23, v40
	v_rndne_f32_e32 v6, v6
	v_med3_f32 v30, v30, s23, v40
	v_med3_f32 v41, v41, s23, v40
	v_rndne_f32_e32 v5, v5
	v_cvt_i32_f32_e32 v6, v6
	v_rndne_f32_e32 v30, v30
	v_rndne_f32_e32 v41, v41
	v_cvt_i32_f32_e32 v5, v5
	v_cvt_i32_f32_sdwa v30, v30 dst_sel:WORD_1 dst_unused:UNUSED_PAD src0_sel:DWORD
	v_cvt_i32_f32_e32 v41, v41
	v_lshlrev_b32_e32 v6, 8, v6
	v_and_b32_e32 v6, 0xff00, v6
	v_and_b32_e32 v30, 0xff0000, v30
	v_perm_b32 v5, v41, v5, s24
	v_or3_b32 v54, v5, v6, v30
	s_waitcnt lgkmcnt(2)
	v_mul_f32_e32 v6, 0x44fe0000, v56
	v_mul_f32_e32 v5, 0x44fe0000, v52
	v_med3_f32 v6, v6, s23, v40
	s_waitcnt lgkmcnt(1)
	v_mul_f32_e32 v30, 0x44fe0000, v58
	s_waitcnt lgkmcnt(0)
; #define LAS __attribute__((address_space(3)))
; #define LDS_WAIT() asm volatile("s_waitcnt lgkmcnt(0)" ::: "memory")
; __device__ __forceinline__ void transpose_item_h32_i8(const float* W, int ldw, int k0, int n0, unsigned char* WT, int ldt, int drow0, float qs, LAS float* scr, int lane) {
;     ...
;     const int c = lane & 7;
; #pragma unroll
;     for (int j = 0; j < 4; ++j) { const int n = (lane >> 3) + 8 * j; const LAS float* s = scr + (8 * c) * 33 + n;
;         u32x2 o; o.x = pk4_i8(s[0 * 33], s[1 * 33], s[2 * 33], s[3 * 33], qs); o.y = pk4_i8(s[4 * 33], s[5 * 33], s[6 * 33], s[7 * 33], qs);
;         *(u32x2*)(WT + (size_t)(drow0 + n) * ldt + k0 + 8 * c) = o; }
;     LDS_WAIT(); asm volatile("" ::: "memory");
	v_mul_f32_e32 v41, 0x44fe0000, v60
	v_med3_f32 v5, v5, s23, v40
	v_rndne_f32_e32 v6, v6
	v_med3_f32 v30, v30, s23, v40
	v_med3_f32 v41, v41, s23, v40
	v_rndne_f32_e32 v5, v5
	v_cvt_i32_f32_e32 v6, v6
	v_rndne_f32_e32 v30, v30
	v_rndne_f32_e32 v41, v41
	v_cvt_i32_f32_e32 v5, v5
	v_cvt_i32_f32_sdwa v30, v30 dst_sel:WORD_1 dst_unused:UNUSED_PAD src0_sel:DWORD
	v_cvt_i32_f32_e32 v41, v41
	v_lshlrev_b32_e32 v6, 8, v6
	v_and_b32_e32 v6, 0xff00, v6
	v_and_b32_e32 v30, 0xff0000, v30
	v_perm_b32 v5, v41, v5, s24
	v_or3_b32 v55, v5, v6, v30
	v_or_b32_e32 v5, s14, v31
	v_lshl_add_u64 v[44:45], v[14:15], 0, s[6:7]
	v_lshlrev_b32_e32 v6, 12, v5
	v_lshl_add_u64 v[62:63], v[44:45], 0, v[6:7]
	v_mul_f32_e32 v6, 0x44fe0000, v47
	v_mul_f32_e32 v5, 0x44fe0000, v43
	v_med3_f32 v6, v6, s23, v40
	v_mul_f32_e32 v30, 0x44fe0000, v49
	v_mul_f32_e32 v41, 0x44fe0000, v51
	v_med3_f32 v5, v5, s23, v40
	v_rndne_f32_e32 v6, v6
	v_med3_f32 v30, v30, s23, v40
	v_med3_f32 v41, v41, s23, v40
	v_rndne_f32_e32 v5, v5
	v_cvt_i32_f32_e32 v6, v6
	v_rndne_f32_e32 v30, v30
	v_rndne_f32_e32 v41, v41
	v_cvt_i32_f32_e32 v5, v5
	v_cvt_i32_f32_sdwa v30, v30 dst_sel:WORD_1 dst_unused:UNUSED_PAD src0_sel:DWORD
	v_cvt_i32_f32_e32 v41, v41
	v_lshlrev_b32_e32 v6, 8, v6
	v_and_b32_e32 v6, 0xff00, v6
	v_and_b32_e32 v30, 0xff0000, v30
	v_perm_b32 v5, v41, v5, s24
	v_or3_b32 v42, v5, v6, v30
	v_mul_f32_e32 v6, 0x44fe0000, v57
	v_mul_f32_e32 v5, 0x44fe0000, v53
	v_med3_f32 v6, v6, s23, v40
	v_mul_f32_e32 v30, 0x44fe0000, v59
	v_mul_f32_e32 v41, 0x44fe0000, v61
	v_med3_f32 v5, v5, s23, v40
	v_rndne_f32_e32 v6, v6
	v_med3_f32 v30, v30, s23, v40
	v_med3_f32 v41, v41, s23, v40
	v_rndne_f32_e32 v5, v5
	v_cvt_i32_f32_e32 v6, v6
	v_rndne_f32_e32 v30, v30
	v_rndne_f32_e32 v41, v41
	v_cvt_i32_f32_e32 v5, v5
	v_cvt_i32_f32_sdwa v30, v30 dst_sel:WORD_1 dst_unused:UNUSED_PAD src0_sel:DWORD
	v_cvt_i32_f32_e32 v41, v41
	v_lshlrev_b32_e32 v6, 8, v6
	v_and_b32_e32 v6, 0xff00, v6
	v_and_b32_e32 v30, 0xff0000, v30
	v_perm_b32 v5, v41, v5, s24
	v_or3_b32 v43, v5, v6, v30
	v_or_b32_e32 v5, s14, v33
	v_lshlrev_b32_e32 v6, 12, v5
	v_lshl_add_u64 v[46:47], v[44:45], 0, v[6:7]
	global_store_dwordx2 v[62:63], v[54:55], off
	global_store_dwordx2 v[46:47], v[42:43], off
	ds_read2_b32 v[48:49], v32 offset0:16 offset1:24
	ds_read2_b32 v[42:43], v32 offset0:49 offset1:57
	ds_read2_b32 v[46:47], v32 offset0:82 offset1:90
	ds_read2_b32 v[50:51], v32 offset0:115 offset1:123
	ds_read2_b32 v[52:53], v32 offset0:148 offset1:156
	ds_read2_b32 v[56:57], v32 offset0:181 offset1:189
	ds_read2_b32 v[58:59], v32 offset0:214 offset1:222
	ds_read2_b32 v[60:61], v32 offset0:247 offset1:255
	s_waitcnt lgkmcnt(6)
	v_mul_f32_e32 v6, 0x44fe0000, v42
	v_mul_f32_e32 v5, 0x44fe0000, v48
	v_med3_f32 v6, v6, s23, v40
	s_waitcnt lgkmcnt(5)
	v_mul_f32_e32 v30, 0x44fe0000, v46
	s_waitcnt lgkmcnt(4)
	v_mul_f32_e32 v41, 0x44fe0000, v50
	v_med3_f32 v5, v5, s23, v40
	v_rndne_f32_e32 v6, v6
	v_med3_f32 v30, v30, s23, v40
	v_med3_f32 v41, v41, s23, v40
	v_rndne_f32_e32 v5, v5
	v_cvt_i32_f32_e32 v6, v6
	v_rndne_f32_e32 v30, v30
	v_rndne_f32_e32 v41, v41
	v_cvt_i32_f32_e32 v5, v5
	v_cvt_i32_f32_sdwa v30, v30 dst_sel:WORD_1 dst_unused:UNUSED_PAD src0_sel:DWORD
	v_cvt_i32_f32_e32 v41, v41
	v_lshlrev_b32_e32 v6, 8, v6
	v_and_b32_e32 v6, 0xff00, v6
	v_and_b32_e32 v30, 0xff0000, v30
	v_perm_b32 v5, v41, v5, s24
	v_or3_b32 v54, v5, v6, v30
	s_waitcnt lgkmcnt(2)
	v_mul_f32_e32 v6, 0x44fe0000, v56
	v_mul_f32_e32 v5, 0x44fe0000, v52
	v_med3_f32 v6, v6, s23, v40
	s_waitcnt lgkmcnt(1)
	v_mul_f32_e32 v30, 0x44fe0000, v58
	s_waitcnt lgkmcnt(0)
	v_mul_f32_e32 v41, 0x44fe0000, v60
	v_med3_f32 v5, v5, s23, v40
	v_rndne_f32_e32 v6, v6
	v_med3_f32 v30, v30, s23, v40
	v_med3_f32 v41, v41, s23, v40
	v_rndne_f32_e32 v5, v5
	v_cvt_i32_f32_e32 v6, v6
	v_rndne_f32_e32 v30, v30
	v_rndne_f32_e32 v41, v41
	v_cvt_i32_f32_e32 v5, v5
	v_cvt_i32_f32_sdwa v30, v30 dst_sel:WORD_1 dst_unused:UNUSED_PAD src0_sel:DWORD
	v_cvt_i32_f32_e32 v41, v41
	v_lshlrev_b32_e32 v6, 8, v6
	v_and_b32_e32 v6, 0xff00, v6
	v_and_b32_e32 v30, 0xff0000, v30
	v_perm_b32 v5, v41, v5, s24
	v_or3_b32 v55, v5, v6, v30
	v_or_b32_e32 v5, s14, v34
	v_lshlrev_b32_e32 v6, 12, v5
	v_lshl_add_u64 v[62:63], v[44:45], 0, v[6:7]
	v_mul_f32_e32 v6, 0x44fe0000, v43
	v_mul_f32_e32 v5, 0x44fe0000, v49
	v_med3_f32 v6, v6, s23, v40
	v_mul_f32_e32 v30, 0x44fe0000, v47
	v_mul_f32_e32 v41, 0x44fe0000, v51
	v_med3_f32 v5, v5, s23, v40
	v_rndne_f32_e32 v6, v6
	v_med3_f32 v30, v30, s23, v40
	v_med3_f32 v41, v41, s23, v40
	v_rndne_f32_e32 v5, v5
	v_cvt_i32_f32_e32 v6, v6
	v_rndne_f32_e32 v30, v30
	v_rndne_f32_e32 v41, v41
	v_cvt_i32_f32_e32 v5, v5
	v_cvt_i32_f32_sdwa v30, v30 dst_sel:WORD_1 dst_unused:UNUSED_PAD src0_sel:DWORD
	v_cvt_i32_f32_e32 v41, v41
	v_lshlrev_b32_e32 v6, 8, v6
	v_and_b32_e32 v6, 0xff00, v6
	v_and_b32_e32 v30, 0xff0000, v30
	v_perm_b32 v5, v41, v5, s24
	v_or3_b32 v42, v5, v6, v30
	v_mul_f32_e32 v6, 0x44fe0000, v57
	v_mul_f32_e32 v5, 0x44fe0000, v53
	v_med3_f32 v6, v6, s23, v40
	v_mul_f32_e32 v30, 0x44fe0000, v59
	v_mul_f32_e32 v41, 0x44fe0000, v61
	v_med3_f32 v5, v5, s23, v40
	v_rndne_f32_e32 v6, v6
	v_med3_f32 v30, v30, s23, v40
	v_med3_f32 v41, v41, s23, v40
	v_rndne_f32_e32 v5, v5
	v_cvt_i32_f32_e32 v6, v6
	v_rndne_f32_e32 v30, v30
	v_rndne_f32_e32 v41, v41
	v_cvt_i32_f32_e32 v5, v5
	v_cvt_i32_f32_sdwa v30, v30 dst_sel:WORD_1 dst_unused:UNUSED_PAD src0_sel:DWORD
	v_cvt_i32_f32_e32 v41, v41
	v_lshlrev_b32_e32 v6, 8, v6
	v_and_b32_e32 v6, 0xff00, v6
	v_and_b32_e32 v30, 0xff0000, v30
	v_perm_b32 v5, v41, v5, s24
	v_or3_b32 v43, v5, v6, v30
	v_or_b32_e32 v5, s14, v35
	v_lshlrev_b32_e32 v6, 12, v5
	v_lshl_add_u64 v[44:45], v[44:45], 0, v[6:7]
	global_store_dwordx2 v[62:63], v[54:55], off
	global_store_dwordx2 v[44:45], v[42:43], off
	s_waitcnt lgkmcnt(0)

; #define LAS __attribute__((address_space(3)))
; #define LDS_WAIT() asm volatile("s_waitcnt lgkmcnt(0)" ::: "memory")
; template <bool I8 = false> __device__ __forceinline__ void transpose_item_f8(const float* W, int ldw, int k0, int n0, unsigned char* WT, int ldt, int drow0, float mul, LAS float* scr, int lane) {
;     float v_[32];
; #pragma unroll
;     for (int i = 0; i < 32; ++i) { const int kk = 2 * i + (lane >> 5); v_[i] = W[(size_t)(k0 + kk) * ldw + n0 + (lane & 31)]; }
; #pragma unroll
;     for (int i = 0; i < 32; ++i) { const int kk = 2 * i + (lane >> 5); scr[kk * 33 + (lane & 31)] = v_[i]; }
;     LDS_WAIT(); asm volatile("" ::: "memory");
.LBB0_43:
	s_andn2_b64 vcc, exec, s[14:15]
	s_cbranch_vccnz .LBB0_45
	s_add_i32 s6, s43, 0xffff3780
	s_waitcnt lgkmcnt(0)
	s_load_dwordx2 s[16:17], s[12:13], 0x80
	s_lshr_b32 s6, s6, 1
	s_and_b32 s6, s6, 0x7fffffc0
	s_lshl_b32 s14, s43, 5
	v_or_b32_e32 v5, s6, v0
	s_and_b32 s14, s14, 0xfe0
	v_lshlrev_b32_e32 v5, 12, v5
	v_or3_b32 v6, v4, v5, s14
	s_waitcnt lgkmcnt(0)
	v_lshl_add_u64 v[42:43], v[6:7], 2, s[16:17]
	v_add_co_u32_e32 v44, vcc, 0x8000, v42
	s_nop 1
	v_addc_co_u32_e32 v45, vcc, 0, v43, vcc
	v_add_co_u32_e32 v46, vcc, 0x10000, v42
	s_nop 1
	v_addc_co_u32_e32 v47, vcc, 0, v43, vcc
	v_add_co_u32_e32 v48, vcc, 0x18000, v42
	s_nop 1
	v_addc_co_u32_e32 v49, vcc, 0, v43, vcc
	v_add_co_u32_e32 v50, vcc, 0x20000, v42
	s_nop 1
	v_addc_co_u32_e32 v51, vcc, 0, v43, vcc
	v_add_co_u32_e32 v52, vcc, 0x28000, v42
	s_nop 1
	v_addc_co_u32_e32 v53, vcc, 0, v43, vcc
	v_add_co_u32_e32 v54, vcc, 0x30000, v42
	s_nop 1
	v_addc_co_u32_e32 v55, vcc, 0, v43, vcc
	v_add_co_u32_e32 v56, vcc, 0x38000, v42
	s_nop 1
	v_addc_co_u32_e32 v57, vcc, 0, v43, vcc
	global_load_dword v5, v[42:43], off nt
	global_load_dword v6, v[44:45], off nt
	global_load_dword v30, v[46:47], off nt
	global_load_dword v41, v[48:49], off nt
	global_load_dword v60, v[50:51], off nt
	global_load_dword v61, v[52:53], off nt
	global_load_dword v62, v[54:55], off nt
	global_load_dword v63, v[56:57], off nt
	v_add_co_u32_e32 v44, vcc, 0x40000, v42
	s_nop 1
	v_addc_co_u32_e32 v45, vcc, 0, v43, vcc
	v_add_co_u32_e32 v46, vcc, 0x48000, v42
	s_nop 1
	v_addc_co_u32_e32 v47, vcc, 0, v43, vcc
	v_add_co_u32_e32 v48, vcc, 0x50000, v42
	s_nop 1
	v_addc_co_u32_e32 v49, vcc, 0, v43, vcc
	v_add_co_u32_e32 v50, vcc, 0x58000, v42
	s_nop 1
	v_addc_co_u32_e32 v51, vcc, 0, v43, vcc
	v_add_co_u32_e32 v52, vcc, 0x60000, v42
	s_nop 1
	v_addc_co_u32_e32 v53, vcc, 0, v43, vcc
	v_add_co_u32_e32 v54, vcc, 0x68000, v42
	s_nop 1
	v_addc_co_u32_e32 v55, vcc, 0, v43, vcc
	v_add_co_u32_e32 v56, vcc, 0x70000, v42
	s_nop 1
	v_addc_co_u32_e32 v57, vcc, 0, v43, vcc
	v_add_co_u32_e32 v58, vcc, 0x78000, v42
	s_nop 1
	v_addc_co_u32_e32 v59, vcc, 0, v43, vcc
	global_load_dword v64, v[44:45], off nt
	global_load_dword v65, v[46:47], off nt
	global_load_dword v66, v[48:49], off nt
	global_load_dword v67, v[50:51], off nt
	global_load_dword v68, v[52:53], off nt
	global_load_dword v69, v[54:55], off nt
	global_load_dword v70, v[56:57], off nt
	global_load_dword v71, v[58:59], off nt
	v_add_co_u32_e32 v44, vcc, 0x80000, v42
	s_nop 1
	v_addc_co_u32_e32 v45, vcc, 0, v43, vcc
	v_add_co_u32_e32 v46, vcc, 0x88000, v42
	s_nop 1
	v_addc_co_u32_e32 v47, vcc, 0, v43, vcc
	v_add_co_u32_e32 v48, vcc, 0x90000, v42
	s_nop 1
	v_addc_co_u32_e32 v49, vcc, 0, v43, vcc
	v_add_co_u32_e32 v50, vcc, 0x98000, v42
	s_nop 1
	v_addc_co_u32_e32 v51, vcc, 0, v43, vcc
	v_add_co_u32_e32 v52, vcc, 0xa0000, v42
	s_nop 1
	v_addc_co_u32_e32 v53, vcc, 0, v43, vcc
	v_add_co_u32_e32 v54, vcc, 0xa8000, v42
	s_nop 1
	v_addc_co_u32_e32 v55, vcc, 0, v43, vcc
	v_add_co_u32_e32 v56, vcc, 0xb0000, v42
	s_nop 1
	v_addc_co_u32_e32 v57, vcc, 0, v43, vcc
	v_add_co_u32_e32 v58, vcc, 0xb8000, v42
	s_nop 1
	v_addc_co_u32_e32 v59, vcc, 0, v43, vcc
	global_load_dword v72, v[44:45], off nt
	global_load_dword v73, v[46:47], off nt
	global_load_dword v74, v[48:49], off nt
	global_load_dword v75, v[50:51], off nt
	global_load_dword v76, v[52:53], off nt
	global_load_dword v77, v[54:55], off nt
	global_load_dword v78, v[56:57], off nt
	s_nop 0
	global_load_dword v58, v[58:59], off nt
	v_add_co_u32_e32 v44, vcc, 0xc0000, v42
	s_nop 1
	v_addc_co_u32_e32 v45, vcc, 0, v43, vcc
	v_add_co_u32_e32 v46, vcc, 0xc8000, v42
	s_nop 1
	v_addc_co_u32_e32 v47, vcc, 0, v43, vcc
	v_add_co_u32_e32 v48, vcc, 0xd0000, v42
	s_nop 1
	v_addc_co_u32_e32 v49, vcc, 0, v43, vcc
	v_add_co_u32_e32 v50, vcc, 0xd8000, v42
	s_nop 1
	v_addc_co_u32_e32 v51, vcc, 0, v43, vcc
	v_add_co_u32_e32 v52, vcc, 0xe0000, v42
	s_nop 1
	v_addc_co_u32_e32 v53, vcc, 0, v43, vcc
	v_add_co_u32_e32 v54, vcc, 0xe8000, v42
	s_nop 1
	v_addc_co_u32_e32 v55, vcc, 0, v43, vcc
	v_add_co_u32_e32 v56, vcc, 0xf0000, v42
	s_nop 1
	v_addc_co_u32_e32 v57, vcc, 0, v43, vcc
	v_add_co_u32_e32 v42, vcc, 0xf8000, v42
	s_nop 1
	v_addc_co_u32_e32 v43, vcc, 0, v43, vcc
	global_load_dword v44, v[44:45], off nt
	s_nop 0
	global_load_dword v45, v[46:47], off nt
	s_nop 0
	global_load_dword v46, v[48:49], off nt
	global_load_dword v47, v[50:51], off nt
	s_nop 0
	global_load_dword v48, v[52:53], off nt
	global_load_dword v49, v[54:55], off nt
	global_load_dword v50, v[56:57], off nt
	s_nop 0
	global_load_dword v42, v[42:43], off nt
	s_waitcnt vmcnt(30)
	ds_write2_b32 v36, v5, v6 offset1:66
	s_waitcnt vmcnt(28)
	ds_write2_b32 v36, v30, v41 offset0:132 offset1:198
	v_add_u32_e32 v5, 0x400, v36
	s_waitcnt vmcnt(26)
; #define LAS __attribute__((address_space(3)))
; #define LDS_WAIT() asm volatile("s_waitcnt lgkmcnt(0)" ::: "memory")
; template <bool I8 = false> __device__ __forceinline__ void transpose_item_f8(const float* W, int ldw, int k0, int n0, unsigned char* WT, int ldt, int drow0, float mul, LAS float* scr, int lane) {
;     ...
;     for (int i = 0; i < 32; ++i) { const int kk = 2 * i + (lane >> 5); scr[kk * 33 + (lane & 31)] = v_[i]; }
;     LDS_WAIT(); asm volatile("" ::: "memory");
;     const int c = lane & 7;
; #pragma unroll
;     for (int j = 0; j < 4; ++j) { const int n = (lane >> 3) + 8 * j; const LAS float* s = scr + (8 * c) * 33 + n;
;         u32x2 o; if constexpr (I8) { o.x = pk4_i8(s[0 * 33], s[1 * 33], s[2 * 33], s[3 * 33], mul); o.y = pk4_i8(s[4 * 33], s[5 * 33], s[6 * 33], s[7 * 33], mul); }
;         else { o.x = pk4_fp8(s[0 * 33] * mul, s[1 * 33] * mul, s[2 * 33] * mul, s[3 * 33] * mul); o.y = pk4_fp8(s[4 * 33] * mul, s[5 * 33] * mul, s[6 * 33] * mul, s[7 * 33] * mul); }
;         *(u32x2*)(WT + (size_t)(drow0 + n) * ldt + k0 + 8 * c) = o; }
;     LDS_WAIT(); asm volatile("" ::: "memory");
	ds_write2_b32 v5, v60, v61 offset0:8 offset1:74
	s_waitcnt vmcnt(24)
	ds_write2_b32 v5, v62, v63 offset0:140 offset1:206
	v_add_u32_e32 v5, 0x800, v36
	s_waitcnt vmcnt(22)
	ds_write2_b32 v5, v64, v65 offset0:16 offset1:82
	s_waitcnt vmcnt(20)
	ds_write2_b32 v5, v66, v67 offset0:148 offset1:214
	v_add_u32_e32 v5, 0xc00, v36
	s_waitcnt vmcnt(18)
	ds_write2_b32 v5, v68, v69 offset0:24 offset1:90
	s_waitcnt vmcnt(16)
	ds_write2_b32 v5, v70, v71 offset0:156 offset1:222
	v_add_u32_e32 v5, 0x1000, v36
	s_waitcnt vmcnt(14)
	ds_write2_b32 v5, v72, v73 offset0:32 offset1:98
	s_waitcnt vmcnt(12)
	ds_write2_b32 v5, v74, v75 offset0:164 offset1:230
	v_add_u32_e32 v5, 0x1400, v36
	s_waitcnt vmcnt(10)
	ds_write2_b32 v5, v76, v77 offset0:40 offset1:106
	s_waitcnt vmcnt(8)
	ds_write2_b32 v5, v78, v58 offset0:172 offset1:238
	v_add_u32_e32 v5, 0x1800, v36
	s_waitcnt vmcnt(6)
	ds_write2_b32 v5, v44, v45 offset0:48 offset1:114
	s_waitcnt vmcnt(4)
	ds_write2_b32 v5, v46, v47 offset0:180 offset1:246
	v_add_u32_e32 v5, 0x1c00, v36
	s_waitcnt vmcnt(2)
	ds_write2_b32 v5, v48, v49 offset0:56 offset1:122
	s_waitcnt vmcnt(0)
	ds_write2_b32 v5, v50, v42 offset0:188 offset1:254
	s_waitcnt lgkmcnt(0)
	ds_read2_b32 v[42:43], v32 offset1:8
	ds_read2_b32 v[44:45], v32 offset0:33 offset1:41
	ds_read2_b32 v[46:47], v32 offset0:66 offset1:74
	ds_read2_b32 v[48:49], v32 offset0:99 offset1:107
	ds_read2_b32 v[54:55], v32 offset0:132 offset1:140
	ds_read2_b32 v[56:57], v32 offset0:165 offset1:173
	ds_read2_b32 v[58:59], v32 offset0:198 offset1:206
	ds_read2_b32 v[60:61], v32 offset0:231 offset1:239
	s_waitcnt lgkmcnt(7)
	v_mul_f32_e32 v5, 0x42800000, v42
	s_waitcnt lgkmcnt(6)
	v_mul_f32_e32 v6, 0x42800000, v44
	v_cvt_pk_fp8_f32 v52, v5, v6
	s_waitcnt lgkmcnt(3)
	v_mul_f32_e32 v5, 0x42800000, v54
	s_waitcnt lgkmcnt(2)
	v_mul_f32_e32 v6, 0x42800000, v56
	v_cvt_pk_fp8_f32 v53, v5, v6
	v_or_b32_e32 v5, s14, v31
	v_lshl_add_u64 v[50:51], v[16:17], 0, s[6:7]
	v_lshlrev_b32_e32 v6, 12, v5
	v_mul_f32_e32 v5, 0x42800000, v43
	v_lshl_add_u64 v[62:63], v[50:51], 0, v[6:7]
	v_mul_f32_e32 v6, 0x42800000, v45
	v_cvt_pk_fp8_f32 v42, v5, v6
	v_mul_f32_e32 v5, 0x42800000, v55
	v_mul_f32_e32 v30, 0x42800000, v46
	v_mul_f32_e32 v41, 0x42800000, v48
	v_mul_f32_e32 v6, 0x42800000, v57
	v_cvt_pk_fp8_f32 v43, v5, v6
	v_or_b32_e32 v5, s14, v33
	v_cvt_pk_fp8_f32 v52, v30, v41 op_sel:[0,0,1]
	s_waitcnt lgkmcnt(1)
	v_mul_f32_e32 v30, 0x42800000, v58
	s_waitcnt lgkmcnt(0)
	v_mul_f32_e32 v41, 0x42800000, v60
	v_lshlrev_b32_e32 v6, 12, v5
	v_cvt_pk_fp8_f32 v53, v30, v41 op_sel:[0,0,1]
	global_store_dwordx2 v[62:63], v[52:53], off
	v_mul_f32_e32 v30, 0x42800000, v47
	v_mul_f32_e32 v41, 0x42800000, v49
	v_lshl_add_u64 v[44:45], v[50:51], 0, v[6:7]
	v_cvt_pk_fp8_f32 v42, v30, v41 op_sel:[0,0,1]
	v_mul_f32_e32 v30, 0x42800000, v59
	v_mul_f32_e32 v41, 0x42800000, v61
	v_cvt_pk_fp8_f32 v43, v30, v41 op_sel:[0,0,1]
	ds_read2_b32 v[46:47], v32 offset0:16 offset1:24
	ds_read2_b32 v[48:49], v32 offset0:49 offset1:57
	ds_read2_b32 v[52:53], v32 offset0:82 offset1:90
	ds_read2_b32 v[54:55], v32 offset0:115 offset1:123
	global_store_dwordx2 v[44:45], v[42:43], off
	ds_read2_b32 v[44:45], v32 offset0:148 offset1:156
	ds_read2_b32 v[56:57], v32 offset0:181 offset1:189
	ds_read2_b32 v[58:59], v32 offset0:214 offset1:222
	ds_read2_b32 v[60:61], v32 offset0:247 offset1:255
	s_waitcnt lgkmcnt(7)
	v_mul_f32_e32 v5, 0x42800000, v46
	s_waitcnt lgkmcnt(6)
	v_mul_f32_e32 v6, 0x42800000, v48
	v_cvt_pk_fp8_f32 v42, v5, v6
	s_waitcnt lgkmcnt(3)
	v_mul_f32_e32 v5, 0x42800000, v44
	s_waitcnt lgkmcnt(2)
	v_mul_f32_e32 v6, 0x42800000, v56
	v_cvt_pk_fp8_f32 v43, v5, v6
	v_or_b32_e32 v5, s14, v34
	v_lshlrev_b32_e32 v6, 12, v5
	v_mul_f32_e32 v30, 0x42800000, v52
	v_mul_f32_e32 v41, 0x42800000, v54
	v_cvt_pk_fp8_f32 v42, v30, v41 op_sel:[0,0,1]
	v_lshl_add_u64 v[62:63], v[50:51], 0, v[6:7]
	v_mul_f32_e32 v5, 0x42800000, v47
	s_waitcnt lgkmcnt(1)
	v_mul_f32_e32 v30, 0x42800000, v58
	s_waitcnt lgkmcnt(0)
	v_mul_f32_e32 v41, 0x42800000, v60
	v_cvt_pk_fp8_f32 v43, v30, v41 op_sel:[0,0,1]
	global_store_dwordx2 v[62:63], v[42:43], off
	v_mul_f32_e32 v6, 0x42800000, v49
	v_cvt_pk_fp8_f32 v42, v5, v6
	v_mul_f32_e32 v5, 0x42800000, v45
	v_mul_f32_e32 v6, 0x42800000, v57
	v_cvt_pk_fp8_f32 v43, v5, v6
	v_or_b32_e32 v5, s14, v35
	v_lshlrev_b32_e32 v6, 12, v5
	v_mul_f32_e32 v30, 0x42800000, v53
	v_mul_f32_e32 v41, 0x42800000, v55
	v_lshl_add_u64 v[44:45], v[50:51], 0, v[6:7]
	v_cvt_pk_fp8_f32 v42, v30, v41 op_sel:[0,0,1]
	v_mul_f32_e32 v30, 0x42800000, v59
	v_mul_f32_e32 v41, 0x42800000, v61
	v_cvt_pk_fp8_f32 v43, v30, v41 op_sel:[0,0,1]
	global_store_dwordx2 v[44:45], v[42:43], off
	s_waitcnt lgkmcnt(0)

; #define LAS __attribute__((address_space(3)))
; #define LDS_WAIT() asm volatile("s_waitcnt lgkmcnt(0)" ::: "memory")
; __device__ __forceinline__ void transpose_item_h64_i8(const float* W, int ldw, int k0, int n0, unsigned char* WT, int ldt, int drow0, float qs, LAS float* scr, int lane) {
;     float v_[32];
; #pragma unroll
;     for (int i = 0; i < 32; ++i) { const int kk = 2 * i + (lane >> 5); v_[i] = W[(size_t)(k0 + kk) * ldw + n0 + (lane & 31)]; }
; #pragma unroll
;     for (int i = 0; i < 32; ++i) { const int kk = 2 * i + (lane >> 5); scr[kk * 33 + (lane & 31)] = v_[i]; }
;     LDS_WAIT(); asm volatile("" ::: "memory");
;     if (lane < 32) {
.LBB0_46:
	s_andn2_b64 vcc, exec, s[14:15]
	s_cbranch_vccnz .LBB0_50
	s_add_i32 s6, s43, 0xffff5780
	s_load_dwordx2 s[14:15], s[12:13], 0x78
	s_lshr_b32 s6, s6, 1
	s_and_b32 s6, s6, 0x7fffffc0
	s_waitcnt lgkmcnt(0)
	s_lshl_b32 s16, s43, 5
	v_or_b32_e32 v5, s6, v0
	s_and_b32 s16, s16, 0xfe0
	v_lshlrev_b32_e32 v5, 12, v5
	v_or3_b32 v6, v4, v5, s16
	v_lshl_add_u64 v[42:43], v[6:7], 2, s[14:15]
	v_add_co_u32_e32 v44, vcc, 0x8000, v42
	s_nop 1
	v_addc_co_u32_e32 v45, vcc, 0, v43, vcc
	v_add_co_u32_e32 v46, vcc, 0x10000, v42
	s_nop 1
	v_addc_co_u32_e32 v47, vcc, 0, v43, vcc
	v_add_co_u32_e32 v48, vcc, 0x18000, v42
	s_nop 1
	v_addc_co_u32_e32 v49, vcc, 0, v43, vcc
	v_add_co_u32_e32 v50, vcc, 0x20000, v42
	s_nop 1
	v_addc_co_u32_e32 v51, vcc, 0, v43, vcc
	v_add_co_u32_e32 v52, vcc, 0x28000, v42
	s_nop 1
	v_addc_co_u32_e32 v53, vcc, 0, v43, vcc
	v_add_co_u32_e32 v54, vcc, 0x30000, v42
	s_nop 1
	v_addc_co_u32_e32 v55, vcc, 0, v43, vcc
	v_add_co_u32_e32 v56, vcc, 0x38000, v42
	s_nop 1
	v_addc_co_u32_e32 v57, vcc, 0, v43, vcc
	global_load_dword v5, v[42:43], off nt
	global_load_dword v6, v[44:45], off nt
	global_load_dword v30, v[46:47], off nt
	global_load_dword v41, v[48:49], off nt
	global_load_dword v60, v[50:51], off nt
	global_load_dword v61, v[52:53], off nt
	global_load_dword v62, v[54:55], off nt
	global_load_dword v63, v[56:57], off nt
	v_add_co_u32_e32 v44, vcc, 0x40000, v42
	s_nop 1
	v_addc_co_u32_e32 v45, vcc, 0, v43, vcc
	v_add_co_u32_e32 v46, vcc, 0x48000, v42
	s_nop 1
	v_addc_co_u32_e32 v47, vcc, 0, v43, vcc
	v_add_co_u32_e32 v48, vcc, 0x50000, v42
	s_nop 1
	v_addc_co_u32_e32 v49, vcc, 0, v43, vcc
	v_add_co_u32_e32 v50, vcc, 0x58000, v42
	s_nop 1
	v_addc_co_u32_e32 v51, vcc, 0, v43, vcc
	v_add_co_u32_e32 v52, vcc, 0x60000, v42
	s_nop 1
	v_addc_co_u32_e32 v53, vcc, 0, v43, vcc
	v_add_co_u32_e32 v54, vcc, 0x68000, v42
	s_nop 1
	v_addc_co_u32_e32 v55, vcc, 0, v43, vcc
	v_add_co_u32_e32 v56, vcc, 0x70000, v42
	s_nop 1
	v_addc_co_u32_e32 v57, vcc, 0, v43, vcc
	v_add_co_u32_e32 v58, vcc, 0x78000, v42
	s_nop 1
	v_addc_co_u32_e32 v59, vcc, 0, v43, vcc
	global_load_dword v64, v[44:45], off nt
	global_load_dword v65, v[46:47], off nt
	global_load_dword v66, v[48:49], off nt
	global_load_dword v67, v[50:51], off nt
	global_load_dword v68, v[52:53], off nt
	global_load_dword v69, v[54:55], off nt
	global_load_dword v70, v[56:57], off nt
	global_load_dword v71, v[58:59], off nt
	v_add_co_u32_e32 v44, vcc, 0x80000, v42
	s_nop 1
	v_addc_co_u32_e32 v45, vcc, 0, v43, vcc
	v_add_co_u32_e32 v46, vcc, 0x88000, v42
	s_nop 1
	v_addc_co_u32_e32 v47, vcc, 0, v43, vcc
	v_add_co_u32_e32 v48, vcc, 0x90000, v42
	s_nop 1
	v_addc_co_u32_e32 v49, vcc, 0, v43, vcc
	v_add_co_u32_e32 v50, vcc, 0x98000, v42
	s_nop 1
	v_addc_co_u32_e32 v51, vcc, 0, v43, vcc
	v_add_co_u32_e32 v52, vcc, 0xa0000, v42
	s_nop 1
	v_addc_co_u32_e32 v53, vcc, 0, v43, vcc
	v_add_co_u32_e32 v54, vcc, 0xa8000, v42
	s_nop 1
	v_addc_co_u32_e32 v55, vcc, 0, v43, vcc
	v_add_co_u32_e32 v56, vcc, 0xb0000, v42
	s_nop 1
	v_addc_co_u32_e32 v57, vcc, 0, v43, vcc
	v_add_co_u32_e32 v58, vcc, 0xb8000, v42
	s_nop 1
	v_addc_co_u32_e32 v59, vcc, 0, v43, vcc
	global_load_dword v72, v[44:45], off nt
	global_load_dword v73, v[46:47], off nt
	global_load_dword v74, v[48:49], off nt
	global_load_dword v75, v[50:51], off nt
	global_load_dword v76, v[52:53], off nt
	global_load_dword v77, v[54:55], off nt
	global_load_dword v78, v[56:57], off nt
	s_nop 0
	global_load_dword v58, v[58:59], off nt
	v_add_co_u32_e32 v44, vcc, 0xc0000, v42
	s_nop 1
	v_addc_co_u32_e32 v45, vcc, 0, v43, vcc
	v_add_co_u32_e32 v46, vcc, 0xc8000, v42
	s_nop 1
	v_addc_co_u32_e32 v47, vcc, 0, v43, vcc
	v_add_co_u32_e32 v48, vcc, 0xd0000, v42
	s_nop 1
	v_addc_co_u32_e32 v49, vcc, 0, v43, vcc
	v_add_co_u32_e32 v50, vcc, 0xd8000, v42
	s_nop 1
	v_addc_co_u32_e32 v51, vcc, 0, v43, vcc
	v_add_co_u32_e32 v52, vcc, 0xe0000, v42
	s_nop 1
	v_addc_co_u32_e32 v53, vcc, 0, v43, vcc
	v_add_co_u32_e32 v54, vcc, 0xe8000, v42
	s_nop 1
	v_addc_co_u32_e32 v55, vcc, 0, v43, vcc
	v_add_co_u32_e32 v56, vcc, 0xf0000, v42
	s_nop 1
	v_addc_co_u32_e32 v57, vcc, 0, v43, vcc
	v_add_co_u32_e32 v42, vcc, 0xf8000, v42
	s_nop 1
	v_addc_co_u32_e32 v43, vcc, 0, v43, vcc
	global_load_dword v44, v[44:45], off nt
	s_nop 0
	global_load_dword v45, v[46:47], off nt
	s_nop 0
	global_load_dword v46, v[48:49], off nt
	global_load_dword v47, v[50:51], off nt
	s_nop 0
	global_load_dword v48, v[52:53], off nt
	global_load_dword v49, v[54:55], off nt
	global_load_dword v50, v[56:57], off nt
	s_nop 0
	global_load_dword v42, v[42:43], off nt
	s_waitcnt vmcnt(30)
	ds_write2_b32 v36, v5, v6 offset1:66
	s_waitcnt vmcnt(28)
	ds_write2_b32 v36, v30, v41 offset0:132 offset1:198
	v_add_u32_e32 v5, 0x400, v36
	s_waitcnt vmcnt(26)
	ds_write2_b32 v5, v60, v61 offset0:8 offset1:74
	s_waitcnt vmcnt(24)
	ds_write2_b32 v5, v62, v63 offset0:140 offset1:206
	v_add_u32_e32 v5, 0x800, v36
	s_waitcnt vmcnt(22)
	ds_write2_b32 v5, v64, v65 offset0:16 offset1:82
	s_waitcnt vmcnt(20)
	ds_write2_b32 v5, v66, v67 offset0:148 offset1:214
	v_add_u32_e32 v5, 0xc00, v36
	s_waitcnt vmcnt(18)
	ds_write2_b32 v5, v68, v69 offset0:24 offset1:90
	s_waitcnt vmcnt(16)
	ds_write2_b32 v5, v70, v71 offset0:156 offset1:222
	v_add_u32_e32 v5, 0x1000, v36
	s_waitcnt vmcnt(14)
	ds_write2_b32 v5, v72, v73 offset0:32 offset1:98
	s_waitcnt vmcnt(12)
	ds_write2_b32 v5, v74, v75 offset0:164 offset1:230
	v_add_u32_e32 v5, 0x1400, v36
	s_waitcnt vmcnt(10)
	ds_write2_b32 v5, v76, v77 offset0:40 offset1:106
	s_waitcnt vmcnt(8)
	ds_write2_b32 v5, v78, v58 offset0:172 offset1:238
	v_add_u32_e32 v5, 0x1800, v36
	s_waitcnt vmcnt(6)
	ds_write2_b32 v5, v44, v45 offset0:48 offset1:114
	s_waitcnt vmcnt(4)
	ds_write2_b32 v5, v46, v47 offset0:180 offset1:246
	v_add_u32_e32 v5, 0x1c00, v36
	s_waitcnt vmcnt(2)
	ds_write2_b32 v5, v48, v49 offset0:56 offset1:122
	s_waitcnt vmcnt(0)
	ds_write2_b32 v5, v50, v42 offset0:188 offset1:254
	s_waitcnt lgkmcnt(0)
	s_and_saveexec_b64 s[14:15], s[4:5]
	s_cbranch_execz .LBB0_49
; __device__ __forceinline__ void fwht64(float (&v)[64]) {
; #pragma unroll
;     for (int s_ = 1; s_ < 64; s_ <<= 1)
; #pragma unroll
;         for (int i = 0; i < 64; ++i) if ((i & s_) == 0) { const float a = v[i], b = v[i | s_]; v[i] = a + b; v[i | s_] = a - b; }
; __device__ __forceinline__ void transpose_item_h64_i8(const float* W, int ldw, int k0, int n0, unsigned char* WT, int ldt, int drow0, float qs, LAS float* scr, int lane) {
;     ...
;     if (lane < 32) {
;         float c_[64];
; #pragma unroll
;         for (int k = 0; k < 64; ++k) c_[k] = scr[k * 33 + lane];
;         fwht64(c_);
	v_add_u32_e32 v5, 0x400, v37
	v_add_u32_e32 v6, 0x800, v37
	v_add_u32_e32 v30, 0xc00, v37
	v_add_u32_e32 v41, 0x1000, v37
	v_add_u32_e32 v82, 0x1200, v37
	v_add_u32_e32 v108, 0x1400, v37
	v_add_u32_e32 v109, 0x1600, v37
	v_add_u32_e32 v110, 0x1800, v37
	v_add_u32_e32 v111, 0x1a00, v37
	v_add_u32_e32 v112, 0x1c00, v37
	v_add_u32_e32 v113, 0x1e00, v37
	ds_read2_b32 v[42:43], v37 offset1:33
	ds_read2_b32 v[44:45], v37 offset0:66 offset1:99
	ds_read2_b32 v[46:47], v37 offset0:132 offset1:165
	ds_read2_b32 v[48:49], v37 offset0:198 offset1:231
	ds_read2_b32 v[50:51], v5 offset0:8 offset1:41
	ds_read2_b32 v[52:53], v5 offset0:74 offset1:107
	ds_read2_b32 v[54:55], v5 offset0:140 offset1:173
	ds_read2_b32 v[56:57], v5 offset0:206 offset1:239
	ds_read2_b32 v[58:59], v6 offset0:16 offset1:49
	ds_read2_b32 v[60:61], v6 offset0:82 offset1:115
	ds_read2_b32 v[62:63], v6 offset0:148 offset1:181
	ds_read2_b32 v[64:65], v6 offset0:214 offset1:247
	ds_read2_b32 v[66:67], v30 offset0:24 offset1:57
	ds_read2_b32 v[68:69], v30 offset0:90 offset1:123
	ds_read2_b32 v[70:71], v30 offset0:156 offset1:189
	ds_read2_b32 v[72:73], v30 offset0:222 offset1:255
	ds_read2_b32 v[74:75], v41 offset0:32 offset1:65
	ds_read2_b32 v[76:77], v41 offset0:98 offset1:131
	ds_read2_b32 v[78:79], v41 offset0:164 offset1:197
	ds_read2_b32 v[80:81], v82 offset0:102 offset1:135
	ds_read2_b32 v[84:85], v108 offset0:40 offset1:73
	ds_read2_b32 v[86:87], v108 offset0:106 offset1:139
	ds_read2_b32 v[88:89], v108 offset0:172 offset1:205
	ds_read2_b32 v[90:91], v109 offset0:110 offset1:143
	ds_read2_b32 v[92:93], v110 offset0:48 offset1:81
	ds_read2_b32 v[94:95], v110 offset0:114 offset1:147
	ds_read2_b32 v[96:97], v110 offset0:180 offset1:213
	ds_read2_b32 v[98:99], v111 offset0:118 offset1:151
	ds_read2_b32 v[100:101], v112 offset0:56 offset1:89
	ds_read2_b32 v[102:103], v112 offset0:122 offset1:155
	ds_read2_b32 v[104:105], v112 offset0:188 offset1:221
	ds_read2_b32 v[106:107], v113 offset0:126 offset1:159
	s_waitcnt lgkmcnt(14)
	v_add_f32_e32 v114, v42, v43
	v_sub_f32_e32 v42, v42, v43
	v_add_f32_e32 v43, v44, v45
	v_sub_f32_e32 v44, v44, v45
	v_add_f32_e32 v45, v46, v47
	v_sub_f32_e32 v46, v46, v47
	v_add_f32_e32 v47, v48, v49
	v_sub_f32_e32 v48, v48, v49
	v_add_f32_e32 v49, v50, v51
	v_sub_f32_e32 v50, v50, v51
	v_add_f32_e32 v51, v52, v53
	v_sub_f32_e32 v52, v52, v53
	v_add_f32_e32 v53, v54, v55
	v_sub_f32_e32 v54, v54, v55
	v_add_f32_e32 v55, v56, v57
	v_sub_f32_e32 v56, v56, v57
	v_add_f32_e32 v57, v58, v59
	v_sub_f32_e32 v58, v58, v59
	v_add_f32_e32 v59, v60, v61
	v_sub_f32_e32 v60, v60, v61
	v_add_f32_e32 v61, v62, v63
	v_sub_f32_e32 v62, v62, v63
	v_add_f32_e32 v63, v64, v65
	v_sub_f32_e32 v64, v64, v65
	v_add_f32_e32 v65, v66, v67
	v_sub_f32_e32 v66, v66, v67
	v_add_f32_e32 v67, v68, v69
	v_sub_f32_e32 v68, v68, v69
	v_add_f32_e32 v69, v70, v71
	v_sub_f32_e32 v70, v70, v71
	v_add_f32_e32 v71, v72, v73
	v_sub_f32_e32 v72, v72, v73
	v_add_f32_e32 v73, v74, v75
	v_sub_f32_e32 v74, v74, v75
	v_add_f32_e32 v75, v76, v77
	v_sub_f32_e32 v76, v76, v77
	s_waitcnt lgkmcnt(13)
	v_add_f32_e32 v77, v78, v79
	v_sub_f32_e32 v78, v78, v79
	s_waitcnt lgkmcnt(12)
	v_add_f32_e32 v79, v80, v81
	v_sub_f32_e32 v80, v80, v81
	s_waitcnt lgkmcnt(11)
	v_add_f32_e32 v81, v84, v85
	v_sub_f32_e32 v84, v84, v85
	s_waitcnt lgkmcnt(10)
	v_add_f32_e32 v85, v86, v87
	v_sub_f32_e32 v86, v86, v87
	s_waitcnt lgkmcnt(9)
	v_add_f32_e32 v87, v88, v89
	v_sub_f32_e32 v88, v88, v89
	s_waitcnt lgkmcnt(8)
	v_add_f32_e32 v89, v90, v91
	v_sub_f32_e32 v90, v90, v91
	s_waitcnt lgkmcnt(7)
	v_add_f32_e32 v91, v92, v93
	v_sub_f32_e32 v92, v92, v93
	s_waitcnt lgkmcnt(6)
	v_add_f32_e32 v93, v94, v95
	v_sub_f32_e32 v94, v94, v95
	s_waitcnt lgkmcnt(5)
	v_add_f32_e32 v95, v96, v97
	v_sub_f32_e32 v96, v96, v97
	s_waitcnt lgkmcnt(4)
	v_add_f32_e32 v97, v98, v99
	v_sub_f32_e32 v98, v98, v99
	s_waitcnt lgkmcnt(3)
	v_add_f32_e32 v99, v100, v101
	v_sub_f32_e32 v100, v100, v101
	s_waitcnt lgkmcnt(2)
	v_add_f32_e32 v101, v102, v103
	v_sub_f32_e32 v102, v102, v103
	s_waitcnt lgkmcnt(1)
	v_add_f32_e32 v103, v104, v105
	v_sub_f32_e32 v104, v104, v105
	s_waitcnt lgkmcnt(0)
	v_add_f32_e32 v105, v106, v107
	v_sub_f32_e32 v106, v106, v107
	v_add_f32_e32 v107, v114, v43
	v_sub_f32_e32 v43, v114, v43
	v_add_f32_e32 v114, v42, v44
	v_sub_f32_e32 v42, v42, v44
	v_add_f32_e32 v44, v45, v47
	v_sub_f32_e32 v45, v45, v47
	v_add_f32_e32 v47, v46, v48
	v_sub_f32_e32 v46, v46, v48
	v_add_f32_e32 v48, v49, v51
	v_sub_f32_e32 v49, v49, v51
	v_add_f32_e32 v51, v50, v52
	v_sub_f32_e32 v50, v50, v52
	v_add_f32_e32 v52, v53, v55
	v_sub_f32_e32 v53, v53, v55
	v_add_f32_e32 v55, v54, v56
	v_sub_f32_e32 v54, v54, v56
	v_add_f32_e32 v56, v57, v59
	v_sub_f32_e32 v57, v57, v59
	v_add_f32_e32 v59, v58, v60
	v_sub_f32_e32 v58, v58, v60
	v_add_f32_e32 v60, v61, v63
	v_sub_f32_e32 v61, v61, v63
	v_add_f32_e32 v63, v62, v64
	v_sub_f32_e32 v62, v62, v64
	v_add_f32_e32 v64, v65, v67
	v_sub_f32_e32 v65, v65, v67
	v_add_f32_e32 v67, v66, v68
	v_sub_f32_e32 v66, v66, v68
	v_add_f32_e32 v68, v69, v71
	v_sub_f32_e32 v69, v69, v71
	v_add_f32_e32 v71, v70, v72
	v_sub_f32_e32 v70, v70, v72
	v_add_f32_e32 v72, v73, v75
	v_sub_f32_e32 v73, v73, v75
	v_add_f32_e32 v75, v74, v76
	v_sub_f32_e32 v74, v74, v76
	v_add_f32_e32 v76, v77, v79
	v_sub_f32_e32 v77, v77, v79
	v_add_f32_e32 v79, v78, v80
	v_sub_f32_e32 v78, v78, v80
	v_add_f32_e32 v80, v81, v85
	v_sub_f32_e32 v81, v81, v85
	v_add_f32_e32 v85, v84, v86
	v_sub_f32_e32 v84, v84, v86
	v_add_f32_e32 v86, v87, v89
	v_sub_f32_e32 v87, v87, v89
	v_add_f32_e32 v89, v88, v90
	v_sub_f32_e32 v88, v88, v90
	v_add_f32_e32 v90, v91, v93
; __device__ __forceinline__ void fwht64(float (&v)[64]) {
; #pragma unroll
;     for (int s_ = 1; s_ < 64; s_ <<= 1)
; #pragma unroll
;         for (int i = 0; i < 64; ++i) if ((i & s_) == 0) { const float a = v[i], b = v[i | s_]; v[i] = a + b; v[i | s_] = a - b; }
; #pragma unroll
;     for (int i = 0; i < 64; ++i) v[i] *= 0.125f;
	v_sub_f32_e32 v91, v91, v93
	v_add_f32_e32 v93, v92, v94
	v_sub_f32_e32 v92, v92, v94
	v_add_f32_e32 v94, v95, v97
	v_sub_f32_e32 v95, v95, v97
	v_add_f32_e32 v97, v96, v98
	v_sub_f32_e32 v96, v96, v98
	v_add_f32_e32 v98, v99, v101
	v_sub_f32_e32 v99, v99, v101
	v_add_f32_e32 v101, v100, v102
	v_sub_f32_e32 v100, v100, v102
	v_add_f32_e32 v102, v103, v105
	v_sub_f32_e32 v103, v103, v105
	v_add_f32_e32 v105, v104, v106
	v_sub_f32_e32 v104, v104, v106
	v_add_f32_e32 v106, v107, v44
	v_sub_f32_e32 v44, v107, v44
	v_add_f32_e32 v107, v114, v47
	v_sub_f32_e32 v47, v114, v47
	v_add_f32_e32 v114, v43, v45
	v_sub_f32_e32 v43, v43, v45
	v_add_f32_e32 v45, v42, v46
	v_sub_f32_e32 v42, v42, v46
	v_add_f32_e32 v46, v48, v52
	v_sub_f32_e32 v48, v48, v52
	v_add_f32_e32 v52, v51, v55
	v_sub_f32_e32 v51, v51, v55
	v_add_f32_e32 v55, v49, v53
	v_sub_f32_e32 v49, v49, v53
	v_add_f32_e32 v53, v50, v54
	v_sub_f32_e32 v50, v50, v54
	v_add_f32_e32 v54, v56, v60
	v_sub_f32_e32 v56, v56, v60
	v_add_f32_e32 v60, v59, v63
	v_sub_f32_e32 v59, v59, v63
	v_add_f32_e32 v63, v57, v61
	v_sub_f32_e32 v57, v57, v61
	v_add_f32_e32 v61, v58, v62
	v_sub_f32_e32 v58, v58, v62
	v_add_f32_e32 v62, v64, v68
	v_sub_f32_e32 v64, v64, v68
	v_add_f32_e32 v68, v67, v71
	v_sub_f32_e32 v67, v67, v71
	v_add_f32_e32 v71, v65, v69
	v_sub_f32_e32 v65, v65, v69
	v_add_f32_e32 v69, v66, v70
	v_sub_f32_e32 v66, v66, v70
	v_add_f32_e32 v70, v72, v76
	v_sub_f32_e32 v72, v72, v76
	v_add_f32_e32 v76, v75, v79
	v_sub_f32_e32 v75, v75, v79
	v_add_f32_e32 v79, v73, v77
	v_sub_f32_e32 v73, v73, v77
	v_add_f32_e32 v77, v74, v78
	v_sub_f32_e32 v74, v74, v78
	v_add_f32_e32 v78, v80, v86
	v_sub_f32_e32 v80, v80, v86
	v_add_f32_e32 v86, v85, v89
	v_sub_f32_e32 v85, v85, v89
	v_add_f32_e32 v89, v81, v87
	v_sub_f32_e32 v81, v81, v87
	v_add_f32_e32 v87, v84, v88
	v_sub_f32_e32 v84, v84, v88
	v_add_f32_e32 v88, v90, v94
	v_sub_f32_e32 v90, v90, v94
	v_add_f32_e32 v94, v93, v97
	v_sub_f32_e32 v93, v93, v97
	v_add_f32_e32 v97, v91, v95
	v_sub_f32_e32 v91, v91, v95
	v_add_f32_e32 v95, v92, v96
	v_sub_f32_e32 v92, v92, v96
	v_add_f32_e32 v96, v98, v102
	v_sub_f32_e32 v98, v98, v102
	v_add_f32_e32 v102, v101, v105
	v_sub_f32_e32 v101, v101, v105
	v_add_f32_e32 v105, v99, v103
	v_sub_f32_e32 v99, v99, v103
	v_add_f32_e32 v103, v100, v104
	v_sub_f32_e32 v100, v100, v104
	v_add_f32_e32 v104, v106, v46
	v_sub_f32_e32 v46, v106, v46
	v_add_f32_e32 v106, v107, v52
	v_sub_f32_e32 v52, v107, v52
	v_add_f32_e32 v107, v114, v55
	v_sub_f32_e32 v55, v114, v55
	v_add_f32_e32 v114, v45, v53
	v_sub_f32_e32 v45, v45, v53
	v_add_f32_e32 v53, v44, v48
	v_sub_f32_e32 v44, v44, v48
	v_add_f32_e32 v48, v47, v51
	v_sub_f32_e32 v47, v47, v51
	v_add_f32_e32 v51, v43, v49
	v_sub_f32_e32 v43, v43, v49
	v_add_f32_e32 v49, v42, v50
	v_sub_f32_e32 v42, v42, v50
	v_add_f32_e32 v50, v54, v62
	v_sub_f32_e32 v54, v54, v62
	v_add_f32_e32 v62, v60, v68
	v_sub_f32_e32 v60, v60, v68
	v_add_f32_e32 v68, v63, v71
	v_sub_f32_e32 v63, v63, v71
	v_add_f32_e32 v71, v61, v69
	v_sub_f32_e32 v61, v61, v69
	v_add_f32_e32 v69, v56, v64
	v_sub_f32_e32 v56, v56, v64
	v_add_f32_e32 v64, v59, v67
	v_sub_f32_e32 v59, v59, v67
	v_add_f32_e32 v67, v57, v65
	v_sub_f32_e32 v57, v57, v65
	v_add_f32_e32 v65, v58, v66
	v_sub_f32_e32 v58, v58, v66
	v_add_f32_e32 v66, v70, v78
	v_sub_f32_e32 v70, v70, v78
	v_add_f32_e32 v78, v76, v86
	v_sub_f32_e32 v76, v76, v86
	v_add_f32_e32 v86, v79, v89
	v_sub_f32_e32 v79, v79, v89
	v_add_f32_e32 v89, v77, v87
	v_sub_f32_e32 v77, v77, v87
	v_add_f32_e32 v87, v72, v80
	v_sub_f32_e32 v72, v72, v80
	v_add_f32_e32 v80, v75, v85
	v_sub_f32_e32 v75, v75, v85
	v_add_f32_e32 v85, v73, v81
	v_sub_f32_e32 v73, v73, v81
	v_add_f32_e32 v81, v74, v84
	v_sub_f32_e32 v74, v74, v84
	v_add_f32_e32 v84, v88, v96
	v_sub_f32_e32 v88, v88, v96
	v_add_f32_e32 v96, v94, v102
	v_sub_f32_e32 v94, v94, v102
	v_add_f32_e32 v102, v97, v105
	v_sub_f32_e32 v97, v97, v105
	v_add_f32_e32 v105, v95, v103
	v_sub_f32_e32 v95, v95, v103
	v_add_f32_e32 v103, v90, v98
	v_sub_f32_e32 v90, v90, v98
	v_add_f32_e32 v98, v93, v101
	v_sub_f32_e32 v93, v93, v101
	v_add_f32_e32 v101, v91, v99
	v_sub_f32_e32 v91, v91, v99
	v_add_f32_e32 v99, v92, v100
	v_sub_f32_e32 v92, v92, v100
	v_add_f32_e32 v100, v104, v50
	v_sub_f32_e32 v50, v104, v50
	v_add_f32_e32 v104, v106, v62
	v_sub_f32_e32 v62, v106, v62
	v_add_f32_e32 v106, v107, v68
	v_sub_f32_e32 v68, v107, v68
	v_add_f32_e32 v107, v114, v71
	v_sub_f32_e32 v71, v114, v71
	v_add_f32_e32 v114, v53, v69
	v_sub_f32_e32 v53, v53, v69
	v_add_f32_e32 v69, v48, v64
	v_sub_f32_e32 v48, v48, v64
	v_add_f32_e32 v64, v51, v67
	v_sub_f32_e32 v51, v51, v67
	v_add_f32_e32 v67, v49, v65
	v_sub_f32_e32 v49, v49, v65
	v_add_f32_e32 v65, v46, v54
	v_sub_f32_e32 v46, v46, v54
	v_add_f32_e32 v54, v52, v60
	v_sub_f32_e32 v52, v52, v60
	v_add_f32_e32 v60, v55, v63
	v_sub_f32_e32 v55, v55, v63
	v_add_f32_e32 v63, v45, v61
	v_sub_f32_e32 v45, v45, v61
	v_add_f32_e32 v61, v44, v56
	v_sub_f32_e32 v44, v44, v56
	v_add_f32_e32 v56, v47, v59
	v_sub_f32_e32 v47, v47, v59
	v_add_f32_e32 v59, v43, v57
	v_sub_f32_e32 v43, v43, v57
	v_add_f32_e32 v57, v42, v58
	v_sub_f32_e32 v42, v42, v58
	v_add_f32_e32 v58, v66, v84
	v_sub_f32_e32 v66, v66, v84
	v_add_f32_e32 v84, v78, v96
	v_sub_f32_e32 v78, v78, v96
	v_add_f32_e32 v96, v86, v102
	v_sub_f32_e32 v86, v86, v102
	v_add_f32_e32 v102, v89, v105
	v_sub_f32_e32 v89, v89, v105
	v_add_f32_e32 v105, v87, v103
	v_sub_f32_e32 v87, v87, v103
	v_add_f32_e32 v103, v80, v98
	v_sub_f32_e32 v80, v80, v98
	v_add_f32_e32 v98, v85, v101
	v_sub_f32_e32 v85, v85, v101
	v_add_f32_e32 v101, v81, v99
	v_sub_f32_e32 v81, v81, v99
; __device__ __forceinline__ void fwht64(float (&v)[64]) {
; #pragma unroll
;     for (int s_ = 1; s_ < 64; s_ <<= 1)
; #pragma unroll
;         for (int i = 0; i < 64; ++i) if ((i & s_) == 0) { const float a = v[i], b = v[i | s_]; v[i] = a + b; v[i | s_] = a - b; }
; #pragma unroll
;     for (int i = 0; i < 64; ++i) v[i] *= 0.125f;
; }
; __device__ __forceinline__ void transpose_item_h64_i8(const float* W, int ldw, int k0, int n0, unsigned char* WT, int ldt, int drow0, float qs, LAS float* scr, int lane) {
;     ...
;         for (int k = 0; k < 64; ++k) c_[k] = scr[k * 33 + lane];
;         fwht64(c_);
; #pragma unroll
;         for (int k = 0; k < 64; ++k) scr[k * 33 + lane] = c_[k];
;     }
	v_add_f32_e32 v99, v70, v88
	v_sub_f32_e32 v70, v70, v88
	v_add_f32_e32 v88, v76, v94
	v_sub_f32_e32 v76, v76, v94
	v_add_f32_e32 v94, v79, v97
	v_sub_f32_e32 v79, v79, v97
	v_add_f32_e32 v97, v77, v95
	v_sub_f32_e32 v77, v77, v95
	v_add_f32_e32 v95, v72, v90
	v_sub_f32_e32 v72, v72, v90
	v_add_f32_e32 v90, v75, v93
	v_sub_f32_e32 v75, v75, v93
	v_add_f32_e32 v93, v73, v91
	v_sub_f32_e32 v73, v73, v91
	v_add_f32_e32 v91, v74, v92
	v_sub_f32_e32 v74, v74, v92
	v_add_f32_e32 v92, v100, v58
	v_sub_f32_e32 v58, v100, v58
	v_add_f32_e32 v100, v104, v84
	v_sub_f32_e32 v84, v104, v84
	v_add_f32_e32 v104, v106, v96
	v_sub_f32_e32 v96, v106, v96
	v_add_f32_e32 v106, v107, v102
	v_sub_f32_e32 v102, v107, v102
	v_add_f32_e32 v107, v114, v105
	v_sub_f32_e32 v105, v114, v105
	v_add_f32_e32 v114, v69, v103
	v_sub_f32_e32 v69, v69, v103
	v_add_f32_e32 v103, v64, v98
	v_sub_f32_e32 v64, v64, v98
	v_add_f32_e32 v98, v67, v101
	v_sub_f32_e32 v67, v67, v101
	v_add_f32_e32 v101, v65, v99
	v_sub_f32_e32 v65, v65, v99
	v_add_f32_e32 v99, v54, v88
	v_sub_f32_e32 v54, v54, v88
	v_add_f32_e32 v88, v60, v94
	v_sub_f32_e32 v60, v60, v94
	v_add_f32_e32 v94, v63, v97
	v_sub_f32_e32 v63, v63, v97
	v_add_f32_e32 v97, v61, v95
	v_sub_f32_e32 v61, v61, v95
	v_add_f32_e32 v95, v56, v90
	v_sub_f32_e32 v56, v56, v90
	v_add_f32_e32 v90, v59, v93
	v_sub_f32_e32 v59, v59, v93
	v_add_f32_e32 v93, v57, v91
	v_sub_f32_e32 v57, v57, v91
	v_add_f32_e32 v91, v50, v66
	v_sub_f32_e32 v50, v50, v66
	v_add_f32_e32 v66, v62, v78
	v_sub_f32_e32 v62, v62, v78
	v_add_f32_e32 v78, v68, v86
	v_sub_f32_e32 v68, v68, v86
	v_add_f32_e32 v86, v71, v89
	v_sub_f32_e32 v71, v71, v89
	v_add_f32_e32 v89, v53, v87
	v_sub_f32_e32 v53, v53, v87
	v_add_f32_e32 v87, v48, v80
	v_sub_f32_e32 v48, v48, v80
	v_add_f32_e32 v80, v51, v85
	v_sub_f32_e32 v51, v51, v85
	v_add_f32_e32 v85, v49, v81
	v_sub_f32_e32 v49, v49, v81
	v_add_f32_e32 v81, v46, v70
	v_sub_f32_e32 v46, v46, v70
	v_add_f32_e32 v70, v52, v76
	v_sub_f32_e32 v52, v52, v76
	v_add_f32_e32 v76, v55, v79
	v_sub_f32_e32 v55, v55, v79
	v_add_f32_e32 v79, v45, v77
	v_sub_f32_e32 v45, v45, v77
	v_add_f32_e32 v77, v44, v72
	v_sub_f32_e32 v44, v44, v72
	v_add_f32_e32 v72, v47, v75
	v_sub_f32_e32 v47, v47, v75
	v_add_f32_e32 v75, v43, v73
	v_sub_f32_e32 v43, v43, v73
	v_add_f32_e32 v73, v42, v74
	v_sub_f32_e32 v42, v42, v74
	v_mul_f32_e32 v74, 0x3e000000, v92
	v_mul_f32_e32 v92, 0x3e000000, v100
	v_mul_f32_e32 v100, 0x3e000000, v104
	v_mul_f32_e32 v104, 0x3e000000, v106
	v_mul_f32_e32 v106, 0x3e000000, v107
	v_mul_f32_e32 v107, 0x3e000000, v114
	v_mul_f32_e32 v103, 0x3e000000, v103
	v_mul_f32_e32 v98, 0x3e000000, v98
	v_mul_f32_e32 v101, 0x3e000000, v101
	v_mul_f32_e32 v99, 0x3e000000, v99
	v_mul_f32_e32 v88, 0x3e000000, v88
	v_mul_f32_e32 v94, 0x3e000000, v94
	v_mul_f32_e32 v97, 0x3e000000, v97
	v_mul_f32_e32 v95, 0x3e000000, v95
	v_mul_f32_e32 v90, 0x3e000000, v90
	v_mul_f32_e32 v93, 0x3e000000, v93
	v_mul_f32_e32 v91, 0x3e000000, v91
	v_mul_f32_e32 v66, 0x3e000000, v66
	v_mul_f32_e32 v78, 0x3e000000, v78
	v_mul_f32_e32 v86, 0x3e000000, v86
	v_mul_f32_e32 v89, 0x3e000000, v89
	v_mul_f32_e32 v87, 0x3e000000, v87
	v_mul_f32_e32 v80, 0x3e000000, v80
	v_mul_f32_e32 v85, 0x3e000000, v85
	v_mul_f32_e32 v81, 0x3e000000, v81
	v_mul_f32_e32 v70, 0x3e000000, v70
	v_mul_f32_e32 v76, 0x3e000000, v76
	v_mul_f32_e32 v79, 0x3e000000, v79
	v_mul_f32_e32 v77, 0x3e000000, v77
	v_mul_f32_e32 v72, 0x3e000000, v72
	v_mul_f32_e32 v75, 0x3e000000, v75
	v_mul_f32_e32 v73, 0x3e000000, v73
	v_mul_f32_e32 v58, 0x3e000000, v58
	v_mul_f32_e32 v84, 0x3e000000, v84
	v_mul_f32_e32 v96, 0x3e000000, v96
	v_mul_f32_e32 v102, 0x3e000000, v102
	v_mul_f32_e32 v105, 0x3e000000, v105
	v_mul_f32_e32 v69, 0x3e000000, v69
	v_mul_f32_e32 v64, 0x3e000000, v64
	v_mul_f32_e32 v67, 0x3e000000, v67
	v_mul_f32_e32 v65, 0x3e000000, v65
	v_mul_f32_e32 v54, 0x3e000000, v54
	v_mul_f32_e32 v60, 0x3e000000, v60
	v_mul_f32_e32 v63, 0x3e000000, v63
	v_mul_f32_e32 v61, 0x3e000000, v61
	v_mul_f32_e32 v56, 0x3e000000, v56
	v_mul_f32_e32 v59, 0x3e000000, v59
	v_mul_f32_e32 v57, 0x3e000000, v57
	v_mul_f32_e32 v50, 0x3e000000, v50
	v_mul_f32_e32 v62, 0x3e000000, v62
	v_mul_f32_e32 v68, 0x3e000000, v68
	v_mul_f32_e32 v71, 0x3e000000, v71
	v_mul_f32_e32 v53, 0x3e000000, v53
	v_mul_f32_e32 v48, 0x3e000000, v48
	v_mul_f32_e32 v51, 0x3e000000, v51
	v_mul_f32_e32 v49, 0x3e000000, v49
	v_mul_f32_e32 v46, 0x3e000000, v46
	v_mul_f32_e32 v52, 0x3e000000, v52
	v_mul_f32_e32 v55, 0x3e000000, v55
	v_mul_f32_e32 v45, 0x3e000000, v45
	v_mul_f32_e32 v44, 0x3e000000, v44
	v_mul_f32_e32 v47, 0x3e000000, v47
	v_mul_f32_e32 v43, 0x3e000000, v43
	v_mul_f32_e32 v42, 0x3e000000, v42
	ds_write2_b32 v37, v74, v92 offset1:33
	ds_write2_b32 v37, v100, v104 offset0:66 offset1:99
	ds_write2_b32 v37, v106, v107 offset0:132 offset1:165
	ds_write2_b32 v37, v103, v98 offset0:198 offset1:231
	ds_write2_b32 v5, v101, v99 offset0:8 offset1:41
	ds_write2_b32 v5, v88, v94 offset0:74 offset1:107
	ds_write2_b32 v5, v97, v95 offset0:140 offset1:173
	ds_write2_b32 v5, v90, v93 offset0:206 offset1:239
	ds_write2_b32 v6, v91, v66 offset0:16 offset1:49
	ds_write2_b32 v6, v78, v86 offset0:82 offset1:115
	ds_write2_b32 v6, v89, v87 offset0:148 offset1:181
	ds_write2_b32 v6, v80, v85 offset0:214 offset1:247
	ds_write2_b32 v30, v81, v70 offset0:24 offset1:57
	ds_write2_b32 v30, v76, v79 offset0:90 offset1:123
	ds_write2_b32 v30, v77, v72 offset0:156 offset1:189
	ds_write2_b32 v30, v75, v73 offset0:222 offset1:255
	ds_write2_b32 v41, v58, v84 offset0:32 offset1:65
	ds_write2_b32 v41, v96, v102 offset0:98 offset1:131
	ds_write2_b32 v41, v105, v69 offset0:164 offset1:197
	ds_write2_b32 v82, v64, v67 offset0:102 offset1:135
	ds_write2_b32 v108, v65, v54 offset0:40 offset1:73
	ds_write2_b32 v108, v60, v63 offset0:106 offset1:139
	ds_write2_b32 v108, v61, v56 offset0:172 offset1:205
	ds_write2_b32 v109, v59, v57 offset0:110 offset1:143
	ds_write2_b32 v110, v50, v62 offset0:48 offset1:81
	ds_write2_b32 v110, v68, v71 offset0:114 offset1:147
	ds_write2_b32 v110, v53, v48 offset0:180 offset1:213
	ds_write2_b32 v111, v51, v49 offset0:118 offset1:151
	ds_write2_b32 v112, v46, v52 offset0:56 offset1:89
	ds_write2_b32 v112, v55, v45 offset0:122 offset1:155
	ds_write2_b32 v112, v44, v47 offset0:188 offset1:221
	ds_write2_b32 v113, v43, v42 offset0:126 offset1:159

; #define LAS __attribute__((address_space(3)))
; #define LDS_WAIT() asm volatile("s_waitcnt lgkmcnt(0)" ::: "memory")
; template <bool I8 = false> __device__ __forceinline__ void transpose_item_f8(const float* W, int ldw, int k0, int n0, unsigned char* WT, int ldt, int drow0, float mul, LAS float* scr, int lane) {
;     float v_[32];
; #pragma unroll
;     for (int i = 0; i < 32; ++i) { const int kk = 2 * i + (lane >> 5); v_[i] = W[(size_t)(k0 + kk) * ldw + n0 + (lane & 31)]; }
; #pragma unroll
;     for (int i = 0; i < 32; ++i) { const int kk = 2 * i + (lane >> 5); scr[kk * 33 + (lane & 31)] = v_[i]; }
;     LDS_WAIT(); asm volatile("" ::: "memory");
; __global__ void __launch_bounds__(NWAVES * 64, 2) fwd(Args args) {
;     ...
;             if (r < I_KV) { const int nblk = NKV / 32, kb = r / nblk, nb = r % nblk; transpose_item_f8(kp->w_kv_up, NKV, 64 * kb, 32 * nb, (unsigned char*)(ws + WS_WKV), 512, 32 * nb, 64.0f, scr, lane); continue; } r -= I_KV;
.LBB0_51:
	s_andn2_b64 vcc, exec, s[14:15]
	s_cbranch_vccnz .LBB0_53
	s_add_i32 s14, s43, 0xffff5f80
	s_waitcnt lgkmcnt(0)
	s_load_dwordx2 s[16:17], s[12:13], 0x70
	s_lshr_b32 s6, s14, 2
	s_and_b32 s6, s6, 0x3fffffc0
	s_lshl_b32 s14, s14, 5
	v_or_b32_e32 v5, s6, v0
	s_and_b32 s14, s14, 0x1fe0
	v_lshlrev_b32_e32 v5, 13, v5
	v_or3_b32 v6, v4, v5, s14
	s_waitcnt lgkmcnt(0)
	v_lshl_add_u64 v[42:43], v[6:7], 2, s[16:17]
	v_add_co_u32_e32 v44, vcc, 0x10000, v42
	s_nop 1
	v_addc_co_u32_e32 v45, vcc, 0, v43, vcc
	v_add_co_u32_e32 v46, vcc, 0x20000, v42
	s_nop 1
	v_addc_co_u32_e32 v47, vcc, 0, v43, vcc
	v_add_co_u32_e32 v48, vcc, 0x30000, v42
	s_nop 1
	v_addc_co_u32_e32 v49, vcc, 0, v43, vcc
	v_add_co_u32_e32 v50, vcc, 0x40000, v42
	s_nop 1
	v_addc_co_u32_e32 v51, vcc, 0, v43, vcc
	v_add_co_u32_e32 v52, vcc, 0x50000, v42
	s_nop 1
	v_addc_co_u32_e32 v53, vcc, 0, v43, vcc
	v_add_co_u32_e32 v54, vcc, 0x60000, v42
	s_nop 1
	v_addc_co_u32_e32 v55, vcc, 0, v43, vcc
	v_add_co_u32_e32 v56, vcc, 0x70000, v42
	s_nop 1
	v_addc_co_u32_e32 v57, vcc, 0, v43, vcc
	global_load_dword v5, v[42:43], off nt
	global_load_dword v6, v[44:45], off nt
	global_load_dword v30, v[46:47], off nt
	global_load_dword v41, v[48:49], off nt
	global_load_dword v60, v[50:51], off nt
	global_load_dword v61, v[52:53], off nt
	global_load_dword v62, v[54:55], off nt
	global_load_dword v63, v[56:57], off nt
	v_add_co_u32_e32 v44, vcc, 0x80000, v42
	s_nop 1
	v_addc_co_u32_e32 v45, vcc, 0, v43, vcc
	v_add_co_u32_e32 v46, vcc, 0x90000, v42
	s_nop 1
	v_addc_co_u32_e32 v47, vcc, 0, v43, vcc
	v_add_co_u32_e32 v48, vcc, 0xa0000, v42
	s_nop 1
	v_addc_co_u32_e32 v49, vcc, 0, v43, vcc
	v_add_co_u32_e32 v50, vcc, 0xb0000, v42
	s_nop 1
	v_addc_co_u32_e32 v51, vcc, 0, v43, vcc
	v_add_co_u32_e32 v52, vcc, 0xc0000, v42
	s_nop 1
	v_addc_co_u32_e32 v53, vcc, 0, v43, vcc
	v_add_co_u32_e32 v54, vcc, 0xd0000, v42
	s_nop 1
	v_addc_co_u32_e32 v55, vcc, 0, v43, vcc
	v_add_co_u32_e32 v56, vcc, 0xe0000, v42
	s_nop 1
	v_addc_co_u32_e32 v57, vcc, 0, v43, vcc
	v_add_co_u32_e32 v58, vcc, 0xf0000, v42
	s_nop 1
	v_addc_co_u32_e32 v59, vcc, 0, v43, vcc
	global_load_dword v64, v[44:45], off nt
	global_load_dword v65, v[46:47], off nt
	global_load_dword v66, v[48:49], off nt
	global_load_dword v67, v[50:51], off nt
	global_load_dword v68, v[52:53], off nt
	global_load_dword v69, v[54:55], off nt
	global_load_dword v70, v[56:57], off nt
	global_load_dword v71, v[58:59], off nt
	v_add_co_u32_e32 v44, vcc, 0x100000, v42
	s_nop 1
	v_addc_co_u32_e32 v45, vcc, 0, v43, vcc
	v_add_co_u32_e32 v46, vcc, 0x110000, v42
	s_nop 1
	v_addc_co_u32_e32 v47, vcc, 0, v43, vcc
	v_add_co_u32_e32 v48, vcc, 0x120000, v42
	s_nop 1
	v_addc_co_u32_e32 v49, vcc, 0, v43, vcc
	v_add_co_u32_e32 v50, vcc, 0x130000, v42
	s_nop 1
	v_addc_co_u32_e32 v51, vcc, 0, v43, vcc
	v_add_co_u32_e32 v52, vcc, 0x140000, v42
	s_nop 1
	v_addc_co_u32_e32 v53, vcc, 0, v43, vcc
	v_add_co_u32_e32 v54, vcc, 0x150000, v42
	s_nop 1
	v_addc_co_u32_e32 v55, vcc, 0, v43, vcc
	v_add_co_u32_e32 v56, vcc, 0x160000, v42
	s_nop 1
	v_addc_co_u32_e32 v57, vcc, 0, v43, vcc
	v_add_co_u32_e32 v58, vcc, 0x170000, v42
	s_nop 1
	v_addc_co_u32_e32 v59, vcc, 0, v43, vcc
	global_load_dword v72, v[44:45], off nt
	global_load_dword v73, v[46:47], off nt
	global_load_dword v74, v[48:49], off nt
	global_load_dword v75, v[50:51], off nt
	global_load_dword v76, v[52:53], off nt
	global_load_dword v77, v[54:55], off nt
	global_load_dword v78, v[56:57], off nt
	s_nop 0
	global_load_dword v58, v[58:59], off nt
	v_add_co_u32_e32 v44, vcc, 0x180000, v42
	s_nop 1
	v_addc_co_u32_e32 v45, vcc, 0, v43, vcc
	v_add_co_u32_e32 v46, vcc, 0x190000, v42
	s_nop 1
	v_addc_co_u32_e32 v47, vcc, 0, v43, vcc
	v_add_co_u32_e32 v48, vcc, 0x1a0000, v42
	s_nop 1
	v_addc_co_u32_e32 v49, vcc, 0, v43, vcc
	v_add_co_u32_e32 v50, vcc, 0x1b0000, v42
	s_nop 1
	v_addc_co_u32_e32 v51, vcc, 0, v43, vcc
	v_add_co_u32_e32 v52, vcc, 0x1c0000, v42
	s_nop 1
	v_addc_co_u32_e32 v53, vcc, 0, v43, vcc
	v_add_co_u32_e32 v54, vcc, 0x1d0000, v42
	s_nop 1
	v_addc_co_u32_e32 v55, vcc, 0, v43, vcc
	v_add_co_u32_e32 v56, vcc, 0x1e0000, v42
	s_nop 1
	v_addc_co_u32_e32 v57, vcc, 0, v43, vcc
	v_add_co_u32_e32 v42, vcc, 0x1f0000, v42
	s_nop 1
	v_addc_co_u32_e32 v43, vcc, 0, v43, vcc
	global_load_dword v44, v[44:45], off nt
	s_nop 0
	global_load_dword v45, v[46:47], off nt
	s_nop 0
	global_load_dword v46, v[48:49], off nt
	global_load_dword v47, v[50:51], off nt
	s_nop 0
	global_load_dword v48, v[52:53], off nt
	global_load_dword v49, v[54:55], off nt
	global_load_dword v50, v[56:57], off nt
	s_nop 0
	global_load_dword v42, v[42:43], off nt
	s_waitcnt vmcnt(30)
	ds_write2_b32 v36, v5, v6 offset1:66
	s_waitcnt vmcnt(28)
; #define LAS __attribute__((address_space(3)))
; #define LDS_WAIT() asm volatile("s_waitcnt lgkmcnt(0)" ::: "memory")
; template <bool I8 = false> __device__ __forceinline__ void transpose_item_f8(const float* W, int ldw, int k0, int n0, unsigned char* WT, int ldt, int drow0, float mul, LAS float* scr, int lane) {
;     ...
;     for (int i = 0; i < 32; ++i) { const int kk = 2 * i + (lane >> 5); scr[kk * 33 + (lane & 31)] = v_[i]; }
;     LDS_WAIT(); asm volatile("" ::: "memory");
;     const int c = lane & 7;
; #pragma unroll
;     for (int j = 0; j < 4; ++j) { const int n = (lane >> 3) + 8 * j; const LAS float* s = scr + (8 * c) * 33 + n;
;         u32x2 o; if constexpr (I8) { o.x = pk4_i8(s[0 * 33], s[1 * 33], s[2 * 33], s[3 * 33], mul); o.y = pk4_i8(s[4 * 33], s[5 * 33], s[6 * 33], s[7 * 33], mul); }
;         else { o.x = pk4_fp8(s[0 * 33] * mul, s[1 * 33] * mul, s[2 * 33] * mul, s[3 * 33] * mul); o.y = pk4_fp8(s[4 * 33] * mul, s[5 * 33] * mul, s[6 * 33] * mul, s[7 * 33] * mul); }
;         *(u32x2*)(WT + (size_t)(drow0 + n) * ldt + k0 + 8 * c) = o; }
;     LDS_WAIT(); asm volatile("" ::: "memory");
	ds_write2_b32 v36, v30, v41 offset0:132 offset1:198
	v_add_u32_e32 v5, 0x400, v36
	s_waitcnt vmcnt(26)
	ds_write2_b32 v5, v60, v61 offset0:8 offset1:74
	s_waitcnt vmcnt(24)
	ds_write2_b32 v5, v62, v63 offset0:140 offset1:206
	v_add_u32_e32 v5, 0x800, v36
	s_waitcnt vmcnt(22)
	ds_write2_b32 v5, v64, v65 offset0:16 offset1:82
	s_waitcnt vmcnt(20)
	ds_write2_b32 v5, v66, v67 offset0:148 offset1:214
	v_add_u32_e32 v5, 0xc00, v36
	s_waitcnt vmcnt(18)
	ds_write2_b32 v5, v68, v69 offset0:24 offset1:90
	s_waitcnt vmcnt(16)
	ds_write2_b32 v5, v70, v71 offset0:156 offset1:222
	v_add_u32_e32 v5, 0x1000, v36
	s_waitcnt vmcnt(14)
	ds_write2_b32 v5, v72, v73 offset0:32 offset1:98
	s_waitcnt vmcnt(12)
	ds_write2_b32 v5, v74, v75 offset0:164 offset1:230
	v_add_u32_e32 v5, 0x1400, v36
	s_waitcnt vmcnt(10)
	ds_write2_b32 v5, v76, v77 offset0:40 offset1:106
	s_waitcnt vmcnt(8)
	ds_write2_b32 v5, v78, v58 offset0:172 offset1:238
	v_add_u32_e32 v5, 0x1800, v36
	s_waitcnt vmcnt(6)
	ds_write2_b32 v5, v44, v45 offset0:48 offset1:114
	s_waitcnt vmcnt(4)
	ds_write2_b32 v5, v46, v47 offset0:180 offset1:246
	v_add_u32_e32 v5, 0x1c00, v36
	s_waitcnt vmcnt(2)
	ds_write2_b32 v5, v48, v49 offset0:56 offset1:122
	s_waitcnt vmcnt(0)
	ds_write2_b32 v5, v50, v42 offset0:188 offset1:254
	s_waitcnt lgkmcnt(0)
	ds_read2_b32 v[42:43], v32 offset1:8
	ds_read2_b32 v[44:45], v32 offset0:33 offset1:41
	ds_read2_b32 v[46:47], v32 offset0:66 offset1:74
	ds_read2_b32 v[48:49], v32 offset0:99 offset1:107
	ds_read2_b32 v[54:55], v32 offset0:132 offset1:140
	ds_read2_b32 v[56:57], v32 offset0:165 offset1:173
	ds_read2_b32 v[58:59], v32 offset0:198 offset1:206
	ds_read2_b32 v[60:61], v32 offset0:231 offset1:239
	s_waitcnt lgkmcnt(7)
	v_mul_f32_e32 v5, 0x42800000, v42
	s_waitcnt lgkmcnt(6)
	v_mul_f32_e32 v6, 0x42800000, v44
	v_cvt_pk_fp8_f32 v52, v5, v6
	s_waitcnt lgkmcnt(3)
	v_mul_f32_e32 v5, 0x42800000, v54
	s_waitcnt lgkmcnt(2)
	v_mul_f32_e32 v6, 0x42800000, v56
	v_cvt_pk_fp8_f32 v53, v5, v6
	v_or_b32_e32 v5, s14, v31
	v_lshl_add_u64 v[50:51], v[20:21], 0, s[6:7]
	v_lshlrev_b32_e32 v6, 9, v5
	v_mul_f32_e32 v5, 0x42800000, v43
	v_lshl_add_u64 v[62:63], v[50:51], 0, v[6:7]
	v_mul_f32_e32 v6, 0x42800000, v45
	v_cvt_pk_fp8_f32 v42, v5, v6
	v_mul_f32_e32 v5, 0x42800000, v55
	v_mul_f32_e32 v30, 0x42800000, v46
	v_mul_f32_e32 v41, 0x42800000, v48
	v_mul_f32_e32 v6, 0x42800000, v57
	v_cvt_pk_fp8_f32 v43, v5, v6
	v_or_b32_e32 v5, s14, v33
	v_cvt_pk_fp8_f32 v52, v30, v41 op_sel:[0,0,1]
	s_waitcnt lgkmcnt(1)
	v_mul_f32_e32 v30, 0x42800000, v58
	s_waitcnt lgkmcnt(0)
	v_mul_f32_e32 v41, 0x42800000, v60
	v_lshlrev_b32_e32 v6, 9, v5
	v_cvt_pk_fp8_f32 v53, v30, v41 op_sel:[0,0,1]
	global_store_dwordx2 v[62:63], v[52:53], off
	v_mul_f32_e32 v30, 0x42800000, v47
	v_mul_f32_e32 v41, 0x42800000, v49
	v_lshl_add_u64 v[44:45], v[50:51], 0, v[6:7]
	v_cvt_pk_fp8_f32 v42, v30, v41 op_sel:[0,0,1]
	v_mul_f32_e32 v30, 0x42800000, v59
	v_mul_f32_e32 v41, 0x42800000, v61
	v_cvt_pk_fp8_f32 v43, v30, v41 op_sel:[0,0,1]
	ds_read2_b32 v[46:47], v32 offset0:16 offset1:24
	ds_read2_b32 v[48:49], v32 offset0:49 offset1:57
	ds_read2_b32 v[52:53], v32 offset0:82 offset1:90
	ds_read2_b32 v[54:55], v32 offset0:115 offset1:123
	global_store_dwordx2 v[44:45], v[42:43], off
	ds_read2_b32 v[44:45], v32 offset0:148 offset1:156
	ds_read2_b32 v[56:57], v32 offset0:181 offset1:189
	ds_read2_b32 v[58:59], v32 offset0:214 offset1:222
	ds_read2_b32 v[60:61], v32 offset0:247 offset1:255
	s_waitcnt lgkmcnt(7)
	v_mul_f32_e32 v5, 0x42800000, v46
	s_waitcnt lgkmcnt(6)
	v_mul_f32_e32 v6, 0x42800000, v48
	v_cvt_pk_fp8_f32 v42, v5, v6
	s_waitcnt lgkmcnt(3)
	v_mul_f32_e32 v5, 0x42800000, v44
	s_waitcnt lgkmcnt(2)
	v_mul_f32_e32 v6, 0x42800000, v56
	v_cvt_pk_fp8_f32 v43, v5, v6
	v_or_b32_e32 v5, s14, v34
	v_lshlrev_b32_e32 v6, 9, v5
	v_mul_f32_e32 v30, 0x42800000, v52
	v_mul_f32_e32 v41, 0x42800000, v54
	v_cvt_pk_fp8_f32 v42, v30, v41 op_sel:[0,0,1]
	v_lshl_add_u64 v[62:63], v[50:51], 0, v[6:7]
	v_mul_f32_e32 v5, 0x42800000, v47
	s_waitcnt lgkmcnt(1)
	v_mul_f32_e32 v30, 0x42800000, v58
	s_waitcnt lgkmcnt(0)
	v_mul_f32_e32 v41, 0x42800000, v60
	v_cvt_pk_fp8_f32 v43, v30, v41 op_sel:[0,0,1]
	global_store_dwordx2 v[62:63], v[42:43], off
	v_mul_f32_e32 v6, 0x42800000, v49
	v_cvt_pk_fp8_f32 v42, v5, v6
	v_mul_f32_e32 v5, 0x42800000, v45
	v_mul_f32_e32 v6, 0x42800000, v57
	v_cvt_pk_fp8_f32 v43, v5, v6
	v_or_b32_e32 v5, s14, v35
	v_lshlrev_b32_e32 v6, 9, v5
	v_mul_f32_e32 v30, 0x42800000, v53
	v_mul_f32_e32 v41, 0x42800000, v55
	v_lshl_add_u64 v[44:45], v[50:51], 0, v[6:7]
	v_cvt_pk_fp8_f32 v42, v30, v41 op_sel:[0,0,1]
	v_mul_f32_e32 v30, 0x42800000, v59
	v_mul_f32_e32 v41, 0x42800000, v61
	v_cvt_pk_fp8_f32 v43, v30, v41 op_sel:[0,0,1]
	global_store_dwordx2 v[44:45], v[42:43], off
	s_waitcnt lgkmcnt(0)

; #define LAS __attribute__((address_space(3)))
; #define LDS_WAIT() asm volatile("s_waitcnt lgkmcnt(0)" ::: "memory")
; template <bool I8 = false> __device__ __forceinline__ void transpose_item_f8(const float* W, int ldw, int k0, int n0, unsigned char* WT, int ldt, int drow0, float mul, LAS float* scr, int lane) {
;     float v_[32];
; #pragma unroll
;     for (int i = 0; i < 32; ++i) { const int kk = 2 * i + (lane >> 5); v_[i] = W[(size_t)(k0 + kk) * ldw + n0 + (lane & 31)]; }
; #pragma unroll
;     for (int i = 0; i < 32; ++i) { const int kk = 2 * i + (lane >> 5); scr[kk * 33 + (lane & 31)] = v_[i]; }
;     LDS_WAIT(); asm volatile("" ::: "memory");
; __global__ void __launch_bounds__(NWAVES * 64, 2) fwd(Args args) {
;     ...
;             if (r < I_Q) { const int nblk = NQ / 32, kb = r / nblk, nb = r % nblk; transpose_item_f8(kp->w_q_up, NQ, 64 * kb, 32 * nb, (unsigned char*)(ws + WS_WQ), 1024, 32 * nb, 64.0f, scr, lane); continue; } r -= I_Q;
.LBB0_54:
	s_andn2_b64 vcc, exec, s[14:15]
	s_cbranch_vccnz .LBB0_56
	s_add_i32 s6, s43, 0x6b80
	s_and_b32 s14, s6, 0xffff
	s_mul_i32 s14, s14, 0xaaab
	s_waitcnt lgkmcnt(0)
	s_lshr_b32 s16, s14, 23
	s_mul_i32 s14, s16, 0xc0
	s_sub_i32 s17, s6, s14
	s_load_dwordx2 s[14:15], s[12:13], 0x60
	s_lshl_b32 s6, s16, 6
	s_lshl_b32 s16, s17, 5
	s_and_b32 s16, s16, 0xffe0
	v_or_b32_e32 v5, s6, v0
	v_or_b32_e32 v6, s16, v4
	v_mul_u32_u24_e32 v5, 0x1800, v5
	v_add_lshl_u32 v6, v5, v6, 2
	s_waitcnt lgkmcnt(0)
	v_lshl_add_u64 v[42:43], s[14:15], 0, v[6:7]
	v_add_co_u32_e32 v44, vcc, s25, v42
	v_add_u32_e32 v30, 0x18000, v6
	s_nop 0
	v_addc_co_u32_e32 v45, vcc, 0, v43, vcc
	v_add_co_u32_e32 v46, vcc, s26, v42
	v_add_u32_e32 v41, 0x30000, v6
	s_nop 0
	v_addc_co_u32_e32 v47, vcc, 0, v43, vcc
	v_add_co_u32_e32 v48, vcc, s27, v42
	v_add_u32_e32 v52, 0x48000, v6
	s_nop 0
	v_addc_co_u32_e32 v49, vcc, 0, v43, vcc
	v_add_co_u32_e32 v50, vcc, s28, v42
	v_add_u32_e32 v53, 0x60000, v6
	s_nop 0
	v_addc_co_u32_e32 v51, vcc, 0, v43, vcc
	global_load_dword v5, v6, s[14:15] nt
	global_load_dword v54, v[44:45], off nt
	s_nop 0
	global_load_dword v30, v30, s[14:15] nt
	s_nop 0
	global_load_dword v55, v[46:47], off nt
	s_nop 0
	global_load_dword v41, v41, s[14:15] nt
	s_nop 0
	global_load_dword v56, v[48:49], off nt
	s_nop 0
	global_load_dword v52, v52, s[14:15] nt
	s_nop 0
	global_load_dword v57, v[50:51], off nt
	s_nop 0
	global_load_dword v53, v53, s[14:15] nt
	v_add_co_u32_e32 v44, vcc, s29, v42
	v_add_u32_e32 v58, 0x78000, v6
	s_nop 0
	v_addc_co_u32_e32 v45, vcc, 0, v43, vcc
	v_add_co_u32_e32 v46, vcc, s30, v42
	v_add_u32_e32 v59, 0x90000, v6
	s_nop 0
	v_addc_co_u32_e32 v47, vcc, 0, v43, vcc
	v_add_co_u32_e32 v48, vcc, s31, v42
	v_add_u32_e32 v60, 0xa8000, v6
	s_nop 0
	v_addc_co_u32_e32 v49, vcc, 0, v43, vcc
	v_add_co_u32_e32 v50, vcc, s33, v42
	v_add_u32_e32 v61, 0xc0000, v6
	s_nop 0
	v_addc_co_u32_e32 v51, vcc, 0, v43, vcc
	global_load_dword v62, v[44:45], off nt
	s_nop 0
	global_load_dword v58, v58, s[14:15] nt
	s_nop 0
	global_load_dword v63, v[46:47], off nt
	s_nop 0
	global_load_dword v59, v59, s[14:15] nt
	s_nop 0
	global_load_dword v64, v[48:49], off nt
	s_nop 0
	global_load_dword v60, v60, s[14:15] nt
	s_nop 0
	global_load_dword v65, v[50:51], off nt
	s_nop 0
	global_load_dword v61, v61, s[14:15] nt
	v_add_co_u32_e32 v44, vcc, s34, v42
	v_add_u32_e32 v66, 0xd8000, v6
	s_nop 0
	v_addc_co_u32_e32 v45, vcc, 0, v43, vcc
	v_add_co_u32_e32 v46, vcc, s35, v42
	v_add_u32_e32 v67, 0xf0000, v6
	s_nop 0
	v_addc_co_u32_e32 v47, vcc, 0, v43, vcc
	v_add_co_u32_e32 v48, vcc, s36, v42
	v_add_u32_e32 v68, 0x108000, v6
	s_nop 0
	v_addc_co_u32_e32 v49, vcc, 0, v43, vcc
	v_add_co_u32_e32 v50, vcc, s37, v42
	v_add_u32_e32 v69, 0x120000, v6
	s_nop 0
	v_addc_co_u32_e32 v51, vcc, 0, v43, vcc
	global_load_dword v70, v[44:45], off nt
	s_nop 0
	global_load_dword v66, v66, s[14:15] nt
	s_nop 0
	global_load_dword v71, v[46:47], off nt
	s_nop 0
	global_load_dword v67, v67, s[14:15] nt
	s_nop 0
	global_load_dword v72, v[48:49], off nt
	s_nop 0
	global_load_dword v68, v68, s[14:15] nt
	s_nop 0
	global_load_dword v50, v[50:51], off nt
	s_nop 0
	global_load_dword v51, v69, s[14:15] nt
	v_add_co_u32_e32 v44, vcc, s38, v42
	v_add_u32_e32 v69, 0x138000, v6
	s_nop 0
	v_addc_co_u32_e32 v45, vcc, 0, v43, vcc
	v_add_co_u32_e32 v46, vcc, s39, v42
	v_add_u32_e32 v73, 0x150000, v6
	s_nop 0
	v_addc_co_u32_e32 v47, vcc, 0, v43, vcc
	v_add_co_u32_e32 v48, vcc, s40, v42
	v_add_u32_e32 v6, 0x168000, v6
	s_nop 0
	v_addc_co_u32_e32 v49, vcc, 0, v43, vcc
	v_add_co_u32_e32 v42, vcc, s41, v42
	s_nop 1
	v_addc_co_u32_e32 v43, vcc, 0, v43, vcc
	global_load_dword v44, v[44:45], off nt
	s_nop 0
	global_load_dword v45, v69, s[14:15] nt
	s_nop 0
	global_load_dword v46, v[46:47], off nt
	s_nop 0
	global_load_dword v47, v73, s[14:15] nt
	s_nop 0
	global_load_dword v48, v[48:49], off nt
	s_nop 0
	global_load_dword v6, v6, s[14:15] nt
	s_nop 0
	global_load_dword v42, v[42:43], off nt
	s_waitcnt vmcnt(30)
	ds_write2_b32 v36, v5, v54 offset1:66
	s_waitcnt vmcnt(28)
	ds_write2_b32 v36, v30, v55 offset0:132 offset1:198
	v_add_u32_e32 v5, 0x400, v36
	s_waitcnt vmcnt(26)
	ds_write2_b32 v5, v41, v56 offset0:8 offset1:74
	s_waitcnt vmcnt(24)
	ds_write2_b32 v5, v52, v57 offset0:140 offset1:206
	v_add_u32_e32 v5, 0x800, v36
	s_waitcnt vmcnt(22)
	ds_write2_b32 v5, v53, v62 offset0:16 offset1:82
	s_waitcnt vmcnt(20)
; #define LAS __attribute__((address_space(3)))
; #define LDS_WAIT() asm volatile("s_waitcnt lgkmcnt(0)" ::: "memory")
; template <bool I8 = false> __device__ __forceinline__ void transpose_item_f8(const float* W, int ldw, int k0, int n0, unsigned char* WT, int ldt, int drow0, float mul, LAS float* scr, int lane) {
;     ...
;     for (int i = 0; i < 32; ++i) { const int kk = 2 * i + (lane >> 5); scr[kk * 33 + (lane & 31)] = v_[i]; }
;     LDS_WAIT(); asm volatile("" ::: "memory");
;     const int c = lane & 7;
; #pragma unroll
;     for (int j = 0; j < 4; ++j) { const int n = (lane >> 3) + 8 * j; const LAS float* s = scr + (8 * c) * 33 + n;
;         u32x2 o; if constexpr (I8) { o.x = pk4_i8(s[0 * 33], s[1 * 33], s[2 * 33], s[3 * 33], mul); o.y = pk4_i8(s[4 * 33], s[5 * 33], s[6 * 33], s[7 * 33], mul); }
;         else { o.x = pk4_fp8(s[0 * 33] * mul, s[1 * 33] * mul, s[2 * 33] * mul, s[3 * 33] * mul); o.y = pk4_fp8(s[4 * 33] * mul, s[5 * 33] * mul, s[6 * 33] * mul, s[7 * 33] * mul); }
;         *(u32x2*)(WT + (size_t)(drow0 + n) * ldt + k0 + 8 * c) = o; }
;     LDS_WAIT(); asm volatile("" ::: "memory");
	ds_write2_b32 v5, v58, v63 offset0:148 offset1:214
	v_add_u32_e32 v5, 0xc00, v36
	s_waitcnt vmcnt(18)
	ds_write2_b32 v5, v59, v64 offset0:24 offset1:90
	s_waitcnt vmcnt(16)
	ds_write2_b32 v5, v60, v65 offset0:156 offset1:222
	v_add_u32_e32 v5, 0x1000, v36
	s_waitcnt vmcnt(14)
	ds_write2_b32 v5, v61, v70 offset0:32 offset1:98
	s_waitcnt vmcnt(12)
	ds_write2_b32 v5, v66, v71 offset0:164 offset1:230
	v_add_u32_e32 v5, 0x1400, v36
	s_waitcnt vmcnt(10)
	ds_write2_b32 v5, v67, v72 offset0:40 offset1:106
	s_waitcnt vmcnt(8)
	ds_write2_b32 v5, v68, v50 offset0:172 offset1:238
	v_add_u32_e32 v5, 0x1800, v36
	s_waitcnt vmcnt(6)
	ds_write2_b32 v5, v51, v44 offset0:48 offset1:114
	s_waitcnt vmcnt(4)
	ds_write2_b32 v5, v45, v46 offset0:180 offset1:246
	v_add_u32_e32 v5, 0x1c00, v36
	s_waitcnt vmcnt(2)
	ds_write2_b32 v5, v47, v48 offset0:56 offset1:122
	s_waitcnt vmcnt(0)
	ds_write2_b32 v5, v6, v42 offset0:188 offset1:254
	s_waitcnt lgkmcnt(0)
	ds_read2_b32 v[42:43], v32 offset1:8
	ds_read2_b32 v[44:45], v32 offset0:33 offset1:41
	ds_read2_b32 v[46:47], v32 offset0:66 offset1:74
	ds_read2_b32 v[48:49], v32 offset0:99 offset1:107
	ds_read2_b32 v[54:55], v32 offset0:132 offset1:140
	ds_read2_b32 v[56:57], v32 offset0:165 offset1:173
	ds_read2_b32 v[58:59], v32 offset0:198 offset1:206
	ds_read2_b32 v[60:61], v32 offset0:231 offset1:239
	s_waitcnt lgkmcnt(7)
	v_mul_f32_e32 v5, 0x42800000, v42
	s_waitcnt lgkmcnt(6)
	v_mul_f32_e32 v6, 0x42800000, v44
	v_cvt_pk_fp8_f32 v52, v5, v6
	s_waitcnt lgkmcnt(3)
	v_mul_f32_e32 v5, 0x42800000, v54
	s_waitcnt lgkmcnt(2)
	v_mul_f32_e32 v6, 0x42800000, v56
	v_cvt_pk_fp8_f32 v53, v5, v6
	v_or_b32_e32 v5, s16, v31
	v_lshl_add_u64 v[50:51], v[22:23], 0, s[6:7]
	v_lshlrev_b32_e32 v6, 10, v5
	v_mul_f32_e32 v5, 0x42800000, v43
	v_lshl_add_u64 v[62:63], v[50:51], 0, v[6:7]
	v_mul_f32_e32 v6, 0x42800000, v45
	v_cvt_pk_fp8_f32 v42, v5, v6
	v_mul_f32_e32 v5, 0x42800000, v55
	v_mul_f32_e32 v30, 0x42800000, v46
	v_mul_f32_e32 v41, 0x42800000, v48
	v_mul_f32_e32 v6, 0x42800000, v57
	v_cvt_pk_fp8_f32 v43, v5, v6
	v_or_b32_e32 v5, s16, v33
	v_cvt_pk_fp8_f32 v52, v30, v41 op_sel:[0,0,1]
	s_waitcnt lgkmcnt(1)
	v_mul_f32_e32 v30, 0x42800000, v58
	s_waitcnt lgkmcnt(0)
	v_mul_f32_e32 v41, 0x42800000, v60
	v_lshlrev_b32_e32 v6, 10, v5
	v_cvt_pk_fp8_f32 v53, v30, v41 op_sel:[0,0,1]
	global_store_dwordx2 v[62:63], v[52:53], off
	v_mul_f32_e32 v30, 0x42800000, v47
	v_mul_f32_e32 v41, 0x42800000, v49
	v_lshl_add_u64 v[44:45], v[50:51], 0, v[6:7]
	v_cvt_pk_fp8_f32 v42, v30, v41 op_sel:[0,0,1]
	v_mul_f32_e32 v30, 0x42800000, v59
	v_mul_f32_e32 v41, 0x42800000, v61
	v_cvt_pk_fp8_f32 v43, v30, v41 op_sel:[0,0,1]
	ds_read2_b32 v[46:47], v32 offset0:16 offset1:24
	ds_read2_b32 v[48:49], v32 offset0:49 offset1:57
	ds_read2_b32 v[52:53], v32 offset0:82 offset1:90
	ds_read2_b32 v[54:55], v32 offset0:115 offset1:123
	global_store_dwordx2 v[44:45], v[42:43], off
	ds_read2_b32 v[44:45], v32 offset0:148 offset1:156
	ds_read2_b32 v[56:57], v32 offset0:181 offset1:189
	ds_read2_b32 v[58:59], v32 offset0:214 offset1:222
	ds_read2_b32 v[60:61], v32 offset0:247 offset1:255
	s_waitcnt lgkmcnt(7)
	v_mul_f32_e32 v5, 0x42800000, v46
	s_waitcnt lgkmcnt(6)
	v_mul_f32_e32 v6, 0x42800000, v48
	v_cvt_pk_fp8_f32 v42, v5, v6
	s_waitcnt lgkmcnt(3)
	v_mul_f32_e32 v5, 0x42800000, v44
	s_waitcnt lgkmcnt(2)
	v_mul_f32_e32 v6, 0x42800000, v56
	v_cvt_pk_fp8_f32 v43, v5, v6
	v_or_b32_e32 v5, s16, v34
	v_lshlrev_b32_e32 v6, 10, v5
	v_mul_f32_e32 v30, 0x42800000, v52
	v_mul_f32_e32 v41, 0x42800000, v54
	v_cvt_pk_fp8_f32 v42, v30, v41 op_sel:[0,0,1]
	v_lshl_add_u64 v[62:63], v[50:51], 0, v[6:7]
	v_mul_f32_e32 v5, 0x42800000, v47
	s_waitcnt lgkmcnt(1)
	v_mul_f32_e32 v30, 0x42800000, v58
	s_waitcnt lgkmcnt(0)
	v_mul_f32_e32 v41, 0x42800000, v60
	v_cvt_pk_fp8_f32 v43, v30, v41 op_sel:[0,0,1]
	global_store_dwordx2 v[62:63], v[42:43], off
	v_mul_f32_e32 v6, 0x42800000, v49
	v_cvt_pk_fp8_f32 v42, v5, v6
	v_mul_f32_e32 v5, 0x42800000, v45
	v_mul_f32_e32 v6, 0x42800000, v57
	v_cvt_pk_fp8_f32 v43, v5, v6
	v_or_b32_e32 v5, s16, v35
	v_lshlrev_b32_e32 v6, 10, v5
	v_mul_f32_e32 v30, 0x42800000, v53
	v_mul_f32_e32 v41, 0x42800000, v55
	v_lshl_add_u64 v[44:45], v[50:51], 0, v[6:7]
	v_cvt_pk_fp8_f32 v42, v30, v41 op_sel:[0,0,1]
	v_mul_f32_e32 v30, 0x42800000, v59
	v_mul_f32_e32 v41, 0x42800000, v61
	v_cvt_pk_fp8_f32 v43, v30, v41 op_sel:[0,0,1]
	global_store_dwordx2 v[44:45], v[42:43], off
	s_waitcnt lgkmcnt(0)

; __device__ __forceinline__ void transpose_item(const float* W, int ldw, int k0, int n0, bf16_t* WT, int ldt, int drow0, LAS float* scr, int lane) {
; #pragma unroll 8
;     for (int i = 0; i < 32; ++i) { const int kk = 2 * i + (lane >> 5); scr[kk * 33 + (lane & 31)] = W[(size_t)(k0 + kk) * ldw + n0 + (lane & 31)]; }
; __global__ void __launch_bounds__(NWAVES * 64, 2) fwd(Args args) {
;     ...
;             if (r < I_G) { const int mat = r >> 5, sub = r & 31, kb = sub >> 3, nb = sub & 7;
;                 const int isx = mat & 1, hb = (mat >> 1) & 15, dir = mat >> 5; const float* W = (isx ? kp->lru_wx : kp->lru_wa) + (size_t)(dir * 16 + hb) * 65536;
;                 transpose_item(W, 256, 64 * kb, 32 * nb, WG_T, 256, (hb * 4 + dir * 2 + (nb >> 2)) * 256 + isx * 128 + (nb & 3) * 32, scr, lane); continue; } r -= I_G;
.LBB0_59:
	s_lshl_b32 s47, s45, 1
	s_lshl_b32 s48, s19, 1
	v_or_b32_e32 v5, s47, v1
	v_or_b32_e32 v30, s48, v0
	s_add_i32 s50, s48, 4
	s_add_i32 s49, s47, 4
	s_add_i32 s51, s47, 8
	s_add_i32 s52, s48, 8
	s_add_i32 s53, s47, 12
	s_add_i32 s57, s47, 16
	s_add_i32 s59, s47, 20
	s_add_i32 s61, s47, 24
	s_add_i32 s47, s47, 28
	v_add_lshl_u32 v6, v5, s44, 8
	v_add_lshl_u32 v41, v30, s6, 8
	v_or_b32_e32 v63, s50, v0
	s_add_i32 s56, s48, 12
	v_or_b32_e32 v62, s49, v1
	v_or_b32_e32 v64, s51, v1
	v_or_b32_e32 v65, s52, v0
	v_or_b32_e32 v66, s53, v1
	v_or_b32_e32 v68, s57, v1
	v_or_b32_e32 v70, s59, v1
	v_or_b32_e32 v72, s61, v1
	v_or_b32_e32 v74, s47, v1
	v_or_b32_e32 v42, v3, v6
	v_or_b32_e32 v6, v28, v41
	v_add_lshl_u32 v46, v63, s6, 8
	v_mov_b32_e32 v43, v7
	s_add_i32 s58, s48, 16
	v_or_b32_e32 v67, s56, v0
	v_add_lshl_u32 v41, v62, s44, 8
	v_add_lshl_u32 v48, v64, s44, 8
	v_add_lshl_u32 v76, v65, s6, 8
	v_add_lshl_u32 v50, v66, s44, 8
	v_add_lshl_u32 v52, v68, s44, 8
	v_add_lshl_u32 v54, v70, s44, 8
	v_add_lshl_u32 v56, v72, s44, 8
	v_add_lshl_u32 v60, v74, s44, 8
	v_lshl_add_u64 v[58:59], v[6:7], 2, s[14:15]
	v_or_b32_e32 v6, v28, v46
	v_mov_b32_e32 v45, v7
	s_add_i32 s60, s48, 20
	v_or_b32_e32 v69, s58, v0
	v_add_lshl_u32 v77, v67, s6, 8
	v_lshl_add_u64 v[42:43], v[42:43], 2, s[14:15]
	v_or_b32_e32 v44, v3, v41
	v_or_b32_e32 v46, v3, v48
	v_or_b32_e32 v48, v3, v50
	v_or_b32_e32 v50, v3, v52
	v_or_b32_e32 v52, v3, v54
	v_or_b32_e32 v54, v3, v56
	v_or_b32_e32 v56, v3, v60
	v_lshl_add_u64 v[60:61], v[6:7], 2, s[14:15]
	v_or_b32_e32 v6, v28, v76
	s_add_i32 s62, s48, 24
	v_or_b32_e32 v71, s60, v0
	v_add_lshl_u32 v78, v69, s6, 8
	v_lshl_add_u64 v[44:45], v[44:45], 2, s[14:15]
	global_load_dword v41, v[58:59], off nt
	global_load_dword v76, v[42:43], off nt
	global_load_dword v82, v[60:61], off nt
	global_load_dword v84, v[44:45], off nt
	v_lshl_add_u64 v[42:43], v[6:7], 2, s[14:15]
	v_or_b32_e32 v6, v28, v77
	v_mov_b32_e32 v47, v7
	v_mov_b32_e32 v49, v7
	s_add_i32 s48, s48, 28
	v_or_b32_e32 v73, s62, v0
	v_add_lshl_u32 v79, v71, s6, 8
	v_lshl_add_u64 v[44:45], v[6:7], 2, s[14:15]
	v_or_b32_e32 v6, v28, v78
	v_or_b32_e32 v75, s48, v0
	v_add_lshl_u32 v80, v73, s6, 8
	v_lshl_add_u64 v[46:47], v[46:47], 2, s[14:15]
	v_lshl_add_u64 v[48:49], v[48:49], 2, s[14:15]
	global_load_dword v77, v[42:43], off nt
	global_load_dword v78, v[46:47], off nt
	global_load_dword v85, v[44:45], off nt
	global_load_dword v86, v[48:49], off nt
	v_lshl_add_u64 v[42:43], v[6:7], 2, s[14:15]
	v_or_b32_e32 v6, v28, v79
	v_mov_b32_e32 v51, v7
	v_mov_b32_e32 v53, v7
	v_add_lshl_u32 v81, v75, s6, 8
	v_lshl_add_u64 v[44:45], v[6:7], 2, s[14:15]
	v_or_b32_e32 v6, v28, v80
	v_mov_b32_e32 v55, v7
	v_mov_b32_e32 v57, v7
	v_lshl_add_u64 v[50:51], v[50:51], 2, s[14:15]
	v_lshl_add_u64 v[52:53], v[52:53], 2, s[14:15]
	global_load_dword v79, v[42:43], off nt
	global_load_dword v80, v[50:51], off nt
	global_load_dword v87, v[44:45], off nt
	global_load_dword v88, v[52:53], off nt
	v_lshl_add_u64 v[42:43], v[6:7], 2, s[14:15]
	v_or_b32_e32 v6, v28, v81
	v_lshl_add_u64 v[54:55], v[54:55], 2, s[14:15]
	v_lshl_add_u64 v[56:57], v[56:57], 2, s[14:15]
	v_lshl_add_u64 v[44:45], v[6:7], 2, s[14:15]
	global_load_dword v6, v[42:43], off nt
	global_load_dword v81, v[54:55], off nt
	global_load_dword v89, v[44:45], off nt
	global_load_dword v90, v[56:57], off nt
	s_add_i32 s19, s19, 16
	s_add_i32 s45, s45, 16
	s_add_i32 s46, s46, -16
	v_mad_u64_u32 v[42:43], s[48:49], v30, s21, v[2:3]
	s_cmp_lg_u32 s46, 0
	v_mad_u64_u32 v[44:45], s[48:49], v5, s21, v[2:3]
	v_mad_u64_u32 v[46:47], s[48:49], v63, s21, v[2:3]
	v_mad_u64_u32 v[48:49], s[48:49], v62, s21, v[2:3]
	v_mad_u64_u32 v[50:51], s[48:49], v65, s21, v[2:3]
	v_mad_u64_u32 v[52:53], s[48:49], v64, s21, v[2:3]
	v_mad_u64_u32 v[54:55], s[48:49], v67, s21, v[2:3]
	v_mad_u64_u32 v[56:57], s[48:49], v66, s21, v[2:3]
	v_mad_u64_u32 v[58:59], s[48:49], v69, s21, v[2:3]
	v_mad_u64_u32 v[60:61], s[48:49], v68, s21, v[2:3]
	v_mad_u64_u32 v[62:63], s[48:49], v71, s21, v[2:3]
	v_mad_u64_u32 v[64:65], s[48:49], v70, s21, v[2:3]
	v_mad_u64_u32 v[66:67], s[48:49], v73, s21, v[2:3]
	v_mad_u64_u32 v[68:69], s[48:49], v72, s21, v[2:3]
	v_mad_u64_u32 v[70:71], s[48:49], v75, s21, v[2:3]
	v_mad_u64_u32 v[72:73], s[48:49], v74, s21, v[2:3]
	s_waitcnt vmcnt(15)
	ds_write_b32 v42, v41
	s_waitcnt vmcnt(14)
	ds_write_b32 v44, v76
	s_waitcnt vmcnt(13)
	ds_write_b32 v46, v82
	s_waitcnt vmcnt(12)
	ds_write_b32 v48, v84
	s_waitcnt vmcnt(11)
	ds_write_b32 v50, v77
	s_waitcnt vmcnt(10)
	ds_write_b32 v52, v78
	s_waitcnt vmcnt(9)
	ds_write_b32 v54, v85
	s_waitcnt vmcnt(8)
	ds_write_b32 v56, v86
	s_waitcnt vmcnt(7)
	ds_write_b32 v58, v79
	s_waitcnt vmcnt(6)
	ds_write_b32 v60, v80
	s_waitcnt vmcnt(5)
	ds_write_b32 v62, v87
	s_waitcnt vmcnt(4)
	ds_write_b32 v64, v88
	s_waitcnt vmcnt(3)
	ds_write_b32 v66, v6
	s_waitcnt vmcnt(2)
	ds_write_b32 v68, v81
	s_waitcnt vmcnt(1)
	ds_write_b32 v70, v89
	s_waitcnt vmcnt(0)
	ds_write_b32 v72, v90
	s_cbranch_scc1 .LBB0_59
; #define LAS __attribute__((address_space(3)))
; __device__ __forceinline__ unsigned cvt_pk_bf16(float lo, float hi) { unsigned r; asm volatile("v_cvt_pk_bf16_f32 %0, %1, %2" : "=v"(r) : "v"(lo), "v"(hi)); return r; }
; #define LDS_WAIT() asm volatile("s_waitcnt lgkmcnt(0)" ::: "memory")
; __device__ __forceinline__ void transpose_item(const float* W, int ldw, int k0, int n0, bf16_t* WT, int ldt, int drow0, LAS float* scr, int lane) {
;     ...
;     LDS_WAIT(); asm volatile("" ::: "memory");
;     const int c = lane & 7;
; #pragma unroll
;     for (int j = 0; j < 4; ++j) { const int n = (lane >> 3) + 8 * j; const LAS float* s = scr + (8 * c) * 33 + n;
;         u32x4 o; o.x = cvt_pk_bf16(s[0 * 33], s[1 * 33]); o.y = cvt_pk_bf16(s[2 * 33], s[3 * 33]); o.z = cvt_pk_bf16(s[4 * 33], s[5 * 33]); o.w = cvt_pk_bf16(s[6 * 33], s[7 * 33]);
;         *(u32x4*)(WT + (size_t)(drow0 + n) * ldt + k0 + 8 * c) = o; }
;     LDS_WAIT(); asm volatile("" ::: "memory");
	s_lshl_b32 s14, s17, 2
	s_lshl_b32 s15, s18, 1
	s_lshl_b32 s6, s6, 1
	s_add_i32 s14, s14, s15
	v_lshl_add_u64 v[46:47], v[24:25], 0, s[6:7]
	s_or_b32 s6, s14, s22
	s_waitcnt lgkmcnt(0)
	s_lshl_b32 s16, s16, 7
	s_lshl_b32 s17, s43, 5
	s_lshl_b32 s6, s6, 8
	s_and_b32 s15, s17, 0x60
	s_or_b32 s6, s6, s16
	ds_read2_b32 v[42:43], v32 offset1:33
	s_or_b32 s6, s6, s15
	s_waitcnt lgkmcnt(0)
	v_cvt_pk_bf16_f32 v42, v42, v43
	ds_read2_b32 v[44:45], v32 offset0:66 offset1:99
	v_or_b32_e32 v5, s6, v31
	s_waitcnt lgkmcnt(0)
	v_cvt_pk_bf16_f32 v43, v44, v45
	ds_read2_b32 v[44:45], v32 offset0:132 offset1:165
	v_lshlrev_b32_e32 v6, 9, v5
	s_waitcnt lgkmcnt(0)
	v_cvt_pk_bf16_f32 v44, v44, v45
	ds_read2_b32 v[48:49], v32 offset0:198 offset1:231
	s_waitcnt lgkmcnt(0)
	v_cvt_pk_bf16_f32 v45, v48, v49
	v_lshl_add_u64 v[50:51], v[46:47], 0, v[6:7]
	ds_read2_b32 v[48:49], v32 offset0:8 offset1:41
	global_store_dwordx4 v[50:51], v[42:45], off
	v_or_b32_e32 v5, s6, v33
	v_lshlrev_b32_e32 v6, 9, v5
	s_waitcnt lgkmcnt(0)
	v_cvt_pk_bf16_f32 v42, v48, v49
	ds_read2_b32 v[44:45], v32 offset0:74 offset1:107
	s_waitcnt lgkmcnt(0)
	v_cvt_pk_bf16_f32 v43, v44, v45
	ds_read2_b32 v[44:45], v32 offset0:140 offset1:173
	s_waitcnt lgkmcnt(0)
	v_cvt_pk_bf16_f32 v44, v44, v45
	ds_read2_b32 v[48:49], v32 offset0:206 offset1:239
	s_waitcnt lgkmcnt(0)
	v_cvt_pk_bf16_f32 v45, v48, v49
	v_lshl_add_u64 v[50:51], v[46:47], 0, v[6:7]
	ds_read2_b32 v[48:49], v32 offset0:16 offset1:49
	global_store_dwordx4 v[50:51], v[42:45], off
	v_or_b32_e32 v5, s6, v34
	v_lshlrev_b32_e32 v6, 9, v5
	s_waitcnt lgkmcnt(0)
	v_cvt_pk_bf16_f32 v42, v48, v49
	ds_read2_b32 v[44:45], v32 offset0:82 offset1:115
	s_waitcnt lgkmcnt(0)
	v_cvt_pk_bf16_f32 v43, v44, v45
	ds_read2_b32 v[44:45], v32 offset0:148 offset1:181
	s_waitcnt lgkmcnt(0)
	v_cvt_pk_bf16_f32 v44, v44, v45
	ds_read2_b32 v[48:49], v32 offset0:214 offset1:247
	s_waitcnt lgkmcnt(0)
	v_cvt_pk_bf16_f32 v45, v48, v49
	v_lshl_add_u64 v[50:51], v[46:47], 0, v[6:7]
	v_or_b32_e32 v5, s6, v35
	ds_read2_b32 v[48:49], v32 offset0:24 offset1:57
	global_store_dwordx4 v[50:51], v[42:45], off
	v_lshlrev_b32_e32 v6, 9, v5
	v_lshl_add_u64 v[46:47], v[46:47], 0, v[6:7]
	s_waitcnt lgkmcnt(0)
	v_cvt_pk_bf16_f32 v42, v48, v49
	ds_read2_b32 v[44:45], v32 offset0:90 offset1:123
	s_waitcnt lgkmcnt(0)
	v_cvt_pk_bf16_f32 v43, v44, v45
	ds_read2_b32 v[44:45], v32 offset0:156 offset1:189
	s_waitcnt lgkmcnt(0)
	v_cvt_pk_bf16_f32 v44, v44, v45
	ds_read2_b32 v[48:49], v32 offset0:222 offset1:255
	s_waitcnt lgkmcnt(0)
	v_cvt_pk_bf16_f32 v45, v48, v49
	global_store_dwordx4 v[46:47], v[42:45], off
	s_waitcnt lgkmcnt(0)

; #define LAS __attribute__((address_space(3)))
; #define LDS_WAIT() asm volatile("s_waitcnt lgkmcnt(0)" ::: "memory")
; template <bool I8 = false> __device__ __forceinline__ void transpose_item_f8(const float* W, int ldw, int k0, int n0, unsigned char* WT, int ldt, int drow0, float mul, LAS float* scr, int lane) {
;     float v_[32];
; #pragma unroll
;     for (int i = 0; i < 32; ++i) { const int kk = 2 * i + (lane >> 5); v_[i] = W[(size_t)(k0 + kk) * ldw + n0 + (lane & 31)]; }
; #pragma unroll
;     for (int i = 0; i < 32; ++i) { const int kk = 2 * i + (lane >> 5); scr[kk * 33 + (lane & 31)] = v_[i]; }
;     LDS_WAIT(); asm volatile("" ::: "memory");
; __global__ void __launch_bounds__(NWAVES * 64, 2) fwd(Args args) {
;     ...
;             if (r < I_IN) { const int nblk = IN_COLS / 32, kb = r / nblk, nb = r % nblk, n0 = 32 * nb;
;                 transpose_item_f8<true>(kp->w_in, IN_COLS, 64 * kb, n0, (unsigned char*)WIN_T, D, n0 < SRC_GATE ? n0 : n0 + 192, WIN_QS, scr, lane);
.LBB0_62:
	s_mul_hi_i32 s6, s43, 0x749cb29
	s_lshr_b32 s14, s6, 31
	s_ashr_i32 s6, s6, 4
	s_add_i32 s6, s6, s14
	s_mul_i32 s14, s6, 0x232
	s_sub_i32 s15, s43, s14
	s_waitcnt lgkmcnt(0)
	s_lshl_b32 s16, s15, 5
	s_load_dwordx2 s[18:19], s[12:13], 0x18
	s_lshl_b32 s14, s6, 6
	s_add_i32 s6, s16, 0xc0
	s_cmpk_lt_i32 s15, 0x132
	s_cselect_b32 s6, s16, s6
	s_ashr_i32 s17, s16, 31
	s_lshl_b64 s[16:17], s[16:17], 2
	s_waitcnt lgkmcnt(0)
	s_add_u32 s16, s18, s16
	v_or_b32_e32 v5, s14, v0
	s_addc_u32 s17, s19, s17
	v_lshlrev_b32_e32 v6, 2, v4
	v_lshl_add_u64 v[42:43], s[16:17], 0, v[6:7]
	v_or_b32_e32 v6, 2, v5
	v_mad_i64_i32 v[46:47], s[16:17], v6, s42, v[42:43]
	v_or_b32_e32 v6, 4, v5
	v_mad_i64_i32 v[48:49], s[16:17], v6, s42, v[42:43]
	v_or_b32_e32 v6, 6, v5
	v_mad_i64_i32 v[50:51], s[16:17], v6, s42, v[42:43]
	v_or_b32_e32 v6, 8, v5
	v_mad_i64_i32 v[52:53], s[16:17], v6, s42, v[42:43]
	v_or_b32_e32 v6, 10, v5
	v_mad_i64_i32 v[54:55], s[16:17], v6, s42, v[42:43]
	v_or_b32_e32 v6, 12, v5
	v_mad_i64_i32 v[56:57], s[16:17], v6, s42, v[42:43]
	v_or_b32_e32 v6, 14, v5
	v_mad_i64_i32 v[44:45], s[16:17], v5, s42, v[42:43]
	v_mad_i64_i32 v[58:59], s[16:17], v6, s42, v[42:43]
	global_load_dword v6, v[44:45], off nt
	global_load_dword v30, v[46:47], off nt
	global_load_dword v41, v[48:49], off nt
	global_load_dword v60, v[50:51], off nt
	global_load_dword v61, v[52:53], off nt
	global_load_dword v62, v[54:55], off nt
	global_load_dword v63, v[56:57], off nt
	global_load_dword v64, v[58:59], off nt
	v_or_b32_e32 v44, 16, v5
	v_or_b32_e32 v46, 18, v5
	v_or_b32_e32 v48, 20, v5
	v_or_b32_e32 v50, 22, v5
	v_or_b32_e32 v52, 24, v5
	v_or_b32_e32 v54, 26, v5
	v_or_b32_e32 v56, 28, v5
	v_or_b32_e32 v58, 30, v5
	v_mad_i64_i32 v[44:45], s[16:17], v44, s42, v[42:43]
	v_mad_i64_i32 v[46:47], s[16:17], v46, s42, v[42:43]
	v_mad_i64_i32 v[48:49], s[16:17], v48, s42, v[42:43]
	v_mad_i64_i32 v[50:51], s[16:17], v50, s42, v[42:43]
	v_mad_i64_i32 v[52:53], s[16:17], v52, s42, v[42:43]
	v_mad_i64_i32 v[54:55], s[16:17], v54, s42, v[42:43]
	v_mad_i64_i32 v[56:57], s[16:17], v56, s42, v[42:43]
	v_mad_i64_i32 v[58:59], s[16:17], v58, s42, v[42:43]
	global_load_dword v65, v[44:45], off nt
	global_load_dword v66, v[46:47], off nt
	global_load_dword v67, v[48:49], off nt
	global_load_dword v68, v[50:51], off nt
	global_load_dword v69, v[52:53], off nt
	global_load_dword v70, v[54:55], off nt
	global_load_dword v71, v[56:57], off nt
	global_load_dword v72, v[58:59], off nt
	v_or_b32_e32 v44, 32, v5
	v_or_b32_e32 v46, 34, v5
	v_or_b32_e32 v48, 36, v5
	v_or_b32_e32 v50, 38, v5
	v_or_b32_e32 v52, 40, v5
	v_or_b32_e32 v54, 42, v5
	v_or_b32_e32 v56, 44, v5
	v_or_b32_e32 v58, 46, v5
	v_mad_i64_i32 v[44:45], s[16:17], v44, s42, v[42:43]
	v_mad_i64_i32 v[46:47], s[16:17], v46, s42, v[42:43]
	v_mad_i64_i32 v[48:49], s[16:17], v48, s42, v[42:43]
	v_mad_i64_i32 v[50:51], s[16:17], v50, s42, v[42:43]
	v_mad_i64_i32 v[52:53], s[16:17], v52, s42, v[42:43]
	v_mad_i64_i32 v[54:55], s[16:17], v54, s42, v[42:43]
	v_mad_i64_i32 v[56:57], s[16:17], v56, s42, v[42:43]
	v_mad_i64_i32 v[58:59], s[16:17], v58, s42, v[42:43]
	global_load_dword v73, v[44:45], off nt
	global_load_dword v74, v[46:47], off nt
	global_load_dword v75, v[48:49], off nt
	global_load_dword v76, v[50:51], off nt
	global_load_dword v77, v[52:53], off nt
	global_load_dword v78, v[54:55], off nt
	global_load_dword v79, v[56:57], off nt
	s_nop 0
	global_load_dword v58, v[58:59], off nt
	v_or_b32_e32 v44, 48, v5
	v_or_b32_e32 v46, 50, v5
	v_or_b32_e32 v48, 52, v5
	v_or_b32_e32 v50, 54, v5
	v_or_b32_e32 v52, 56, v5
	v_or_b32_e32 v54, 58, v5
	v_or_b32_e32 v56, 60, v5
	v_or_b32_e32 v5, 62, v5
	v_mad_i64_i32 v[44:45], s[16:17], v44, s42, v[42:43]
	v_mad_i64_i32 v[46:47], s[16:17], v46, s42, v[42:43]
	v_mad_i64_i32 v[48:49], s[16:17], v48, s42, v[42:43]
	v_mad_i64_i32 v[50:51], s[16:17], v50, s42, v[42:43]
	v_mad_i64_i32 v[52:53], s[16:17], v52, s42, v[42:43]
	v_mad_i64_i32 v[54:55], s[16:17], v54, s42, v[42:43]
	v_mad_i64_i32 v[56:57], s[16:17], v56, s42, v[42:43]
	v_mad_i64_i32 v[42:43], s[16:17], v5, s42, v[42:43]
	global_load_dword v5, v[44:45], off nt
	s_nop 0
	global_load_dword v44, v[46:47], off nt
	global_load_dword v45, v[48:49], off nt
	s_nop 0
	global_load_dword v46, v[50:51], off nt
	global_load_dword v47, v[52:53], off nt
	global_load_dword v48, v[54:55], off nt
	global_load_dword v49, v[56:57], off nt
	s_nop 0
	global_load_dword v42, v[42:43], off nt
	s_waitcnt vmcnt(30)
	ds_write2_b32 v36, v6, v30 offset1:66
	s_waitcnt vmcnt(28)
	ds_write2_b32 v36, v41, v60 offset0:132 offset1:198
	v_add_u32_e32 v6, 0x400, v36
	s_waitcnt vmcnt(26)
	ds_write2_b32 v6, v61, v62 offset0:8 offset1:74
	s_waitcnt vmcnt(24)
	ds_write2_b32 v6, v63, v64 offset0:140 offset1:206
	v_add_u32_e32 v6, 0x800, v36
	s_waitcnt vmcnt(22)
	ds_write2_b32 v6, v65, v66 offset0:16 offset1:82
	s_waitcnt vmcnt(20)
	ds_write2_b32 v6, v67, v68 offset0:148 offset1:214
	v_add_u32_e32 v6, 0xc00, v36
	s_waitcnt vmcnt(18)
	ds_write2_b32 v6, v69, v70 offset0:24 offset1:90
	s_waitcnt vmcnt(16)
	ds_write2_b32 v6, v71, v72 offset0:156 offset1:222
	v_add_u32_e32 v6, 0x1000, v36
	s_waitcnt vmcnt(14)
	ds_write2_b32 v6, v73, v74 offset0:32 offset1:98
	s_waitcnt vmcnt(12)
	ds_write2_b32 v6, v75, v76 offset0:164 offset1:230
	v_add_u32_e32 v6, 0x1400, v36
	s_waitcnt vmcnt(10)
	ds_write2_b32 v6, v77, v78 offset0:40 offset1:106
	s_waitcnt vmcnt(8)
	ds_write2_b32 v6, v79, v58 offset0:172 offset1:238
	v_add_u32_e32 v6, 0x1800, v36
	s_waitcnt vmcnt(6)
	ds_write2_b32 v6, v5, v44 offset0:48 offset1:114
	s_waitcnt vmcnt(4)
	ds_write2_b32 v6, v45, v46 offset0:180 offset1:246
	v_add_u32_e32 v5, 0x1c00, v36
	s_waitcnt vmcnt(2)
; #define LAS __attribute__((address_space(3)))
; #define LDS_WAIT() asm volatile("s_waitcnt lgkmcnt(0)" ::: "memory")
; __device__ __forceinline__ unsigned pk4_i8(float a, float b, float c, float d, float qs) {
;     const int q0 = (int)__builtin_rintf(fminf(fmaxf(a * qs, -127.f), 127.f)), q1 = (int)__builtin_rintf(fminf(fmaxf(b * qs, -127.f), 127.f));
;     const int q2 = (int)__builtin_rintf(fminf(fmaxf(c * qs, -127.f), 127.f)), q3 = (int)__builtin_rintf(fminf(fmaxf(d * qs, -127.f), 127.f));
;     return ((unsigned)q0 & 0xffu) | (((unsigned)q1 & 0xffu) << 8) | (((unsigned)q2 & 0xffu) << 16) | ((unsigned)q3 << 24);
; }
; template <bool I8 = false> __device__ __forceinline__ void transpose_item_f8(const float* W, int ldw, int k0, int n0, unsigned char* WT, int ldt, int drow0, float mul, LAS float* scr, int lane) {
;     ...
;     const int c = lane & 7;
; #pragma unroll
;     for (int j = 0; j < 4; ++j) { const int n = (lane >> 3) + 8 * j; const LAS float* s = scr + (8 * c) * 33 + n;
;         u32x2 o; if constexpr (I8) { o.x = pk4_i8(s[0 * 33], s[1 * 33], s[2 * 33], s[3 * 33], mul); o.y = pk4_i8(s[4 * 33], s[5 * 33], s[6 * 33], s[7 * 33], mul); }
;         else { o.x = pk4_fp8(s[0 * 33] * mul, s[1 * 33] * mul, s[2 * 33] * mul, s[3 * 33] * mul); o.y = pk4_fp8(s[4 * 33] * mul, s[5 * 33] * mul, s[6 * 33] * mul, s[7 * 33] * mul); }
;         *(u32x2*)(WT + (size_t)(drow0 + n) * ldt + k0 + 8 * c) = o; }
;     LDS_WAIT(); asm volatile("" ::: "memory");
	ds_write2_b32 v5, v47, v48 offset0:56 offset1:122
	s_waitcnt vmcnt(0)
	ds_write2_b32 v5, v49, v42 offset0:188 offset1:254
	s_waitcnt lgkmcnt(0)
	ds_read2_b32 v[42:43], v32 offset1:8
	ds_read2_b32 v[46:47], v32 offset0:33 offset1:41
	ds_read2_b32 v[48:49], v32 offset0:66 offset1:74
	ds_read2_b32 v[50:51], v32 offset0:99 offset1:107
	ds_read2_b32 v[52:53], v32 offset0:132 offset1:140
	ds_read2_b32 v[56:57], v32 offset0:165 offset1:173
	ds_read2_b32 v[58:59], v32 offset0:198 offset1:206
	ds_read2_b32 v[60:61], v32 offset0:231 offset1:239
	s_waitcnt lgkmcnt(6)
	v_mul_f32_e32 v6, 0x44fe0000, v46
	v_mul_f32_e32 v5, 0x44fe0000, v42
	v_med3_f32 v6, v6, s23, v40
	s_waitcnt lgkmcnt(5)
	v_mul_f32_e32 v30, 0x44fe0000, v48
	s_waitcnt lgkmcnt(4)
	v_mul_f32_e32 v41, 0x44fe0000, v50
	v_med3_f32 v5, v5, s23, v40
	v_rndne_f32_e32 v6, v6
	v_med3_f32 v30, v30, s23, v40
	v_med3_f32 v41, v41, s23, v40
	v_rndne_f32_e32 v5, v5
	v_cvt_i32_f32_e32 v6, v6
	v_rndne_f32_e32 v30, v30
	v_rndne_f32_e32 v41, v41
	v_cvt_i32_f32_e32 v5, v5
	v_cvt_i32_f32_sdwa v30, v30 dst_sel:WORD_1 dst_unused:UNUSED_PAD src0_sel:DWORD
	v_cvt_i32_f32_e32 v41, v41
	v_lshlrev_b32_e32 v6, 8, v6
	v_and_b32_e32 v6, 0xff00, v6
	v_and_b32_e32 v30, 0xff0000, v30
	v_perm_b32 v5, v41, v5, s24
	v_or3_b32 v54, v5, v6, v30
	s_waitcnt lgkmcnt(2)
	v_mul_f32_e32 v6, 0x44fe0000, v56
	v_mul_f32_e32 v5, 0x44fe0000, v52
	v_med3_f32 v6, v6, s23, v40
	s_waitcnt lgkmcnt(1)
	v_mul_f32_e32 v30, 0x44fe0000, v58
	s_waitcnt lgkmcnt(0)
	v_mul_f32_e32 v41, 0x44fe0000, v60
	v_med3_f32 v5, v5, s23, v40
	v_rndne_f32_e32 v6, v6
	v_med3_f32 v30, v30, s23, v40
	v_med3_f32 v41, v41, s23, v40
	v_rndne_f32_e32 v5, v5
	v_cvt_i32_f32_e32 v6, v6
	v_rndne_f32_e32 v30, v30
	v_rndne_f32_e32 v41, v41
	v_cvt_i32_f32_e32 v5, v5
	v_cvt_i32_f32_sdwa v30, v30 dst_sel:WORD_1 dst_unused:UNUSED_PAD src0_sel:DWORD
	v_cvt_i32_f32_e32 v41, v41
	v_lshlrev_b32_e32 v6, 8, v6
	v_and_b32_e32 v6, 0xff00, v6
	v_and_b32_e32 v30, 0xff0000, v30
	v_perm_b32 v5, v41, v5, s24
	v_or3_b32 v55, v5, v6, v30
	v_mul_f32_e32 v6, 0x44fe0000, v47
	v_mul_f32_e32 v5, 0x44fe0000, v43
	v_med3_f32 v6, v6, s23, v40
	v_mul_f32_e32 v30, 0x44fe0000, v49
	v_mul_f32_e32 v41, 0x44fe0000, v51
	v_med3_f32 v5, v5, s23, v40
	v_rndne_f32_e32 v6, v6
	v_med3_f32 v30, v30, s23, v40
	v_med3_f32 v41, v41, s23, v40
	v_rndne_f32_e32 v5, v5
	v_cvt_i32_f32_e32 v6, v6
	v_rndne_f32_e32 v30, v30
	v_rndne_f32_e32 v41, v41
	v_cvt_i32_f32_e32 v5, v5
	v_cvt_i32_f32_sdwa v30, v30 dst_sel:WORD_1 dst_unused:UNUSED_PAD src0_sel:DWORD
	v_cvt_i32_f32_e32 v41, v41
	v_lshlrev_b32_e32 v6, 8, v6
	v_and_b32_e32 v6, 0xff00, v6
	v_and_b32_e32 v30, 0xff0000, v30
	v_perm_b32 v5, v41, v5, s24
	v_or3_b32 v42, v5, v6, v30
	v_mul_f32_e32 v6, 0x44fe0000, v57
	v_mul_f32_e32 v5, 0x44fe0000, v53
	v_med3_f32 v6, v6, s23, v40
	v_mul_f32_e32 v30, 0x44fe0000, v59
	v_mul_f32_e32 v41, 0x44fe0000, v61
	v_med3_f32 v5, v5, s23, v40
	v_rndne_f32_e32 v6, v6
	v_med3_f32 v30, v30, s23, v40
	v_med3_f32 v41, v41, s23, v40
	v_rndne_f32_e32 v5, v5
	v_cvt_i32_f32_e32 v6, v6
	v_rndne_f32_e32 v30, v30
	v_rndne_f32_e32 v41, v41
	v_cvt_i32_f32_e32 v5, v5
	v_cvt_i32_f32_sdwa v30, v30 dst_sel:WORD_1 dst_unused:UNUSED_PAD src0_sel:DWORD
	v_cvt_i32_f32_e32 v41, v41
	v_or_b32_e32 v62, s6, v31
	v_or_b32_e32 v46, s6, v33
	s_ashr_i32 s15, s14, 31
	v_ashrrev_i32_e32 v63, 31, v62
	v_lshlrev_b32_e32 v6, 8, v6
	v_ashrrev_i32_e32 v47, 31, v46
	v_lshl_add_u64 v[44:45], v[26:27], 0, s[14:15]
	v_lshlrev_b64 v[62:63], 12, v[62:63]
	v_and_b32_e32 v6, 0xff00, v6
	v_and_b32_e32 v30, 0xff0000, v30
	v_perm_b32 v5, v41, v5, s24
	v_lshlrev_b64 v[46:47], 12, v[46:47]
	v_lshl_add_u64 v[62:63], v[44:45], 0, v[62:63]
	v_or3_b32 v43, v5, v6, v30
	v_lshl_add_u64 v[46:47], v[44:45], 0, v[46:47]
	global_store_dwordx2 v[62:63], v[54:55], off
	global_store_dwordx2 v[46:47], v[42:43], off
	ds_read2_b32 v[48:49], v32 offset0:16 offset1:24
	ds_read2_b32 v[42:43], v32 offset0:49 offset1:57
	ds_read2_b32 v[46:47], v32 offset0:82 offset1:90
	ds_read2_b32 v[50:51], v32 offset0:115 offset1:123
	ds_read2_b32 v[52:53], v32 offset0:148 offset1:156
	ds_read2_b32 v[56:57], v32 offset0:181 offset1:189
	ds_read2_b32 v[58:59], v32 offset0:214 offset1:222
	ds_read2_b32 v[60:61], v32 offset0:247 offset1:255
	s_waitcnt lgkmcnt(6)
; #define LAS __attribute__((address_space(3)))
; #define LDS_WAIT() asm volatile("s_waitcnt lgkmcnt(0)" ::: "memory")
; __device__ __forceinline__ unsigned pk4_i8(float a, float b, float c, float d, float qs) {
;     const int q0 = (int)__builtin_rintf(fminf(fmaxf(a * qs, -127.f), 127.f)), q1 = (int)__builtin_rintf(fminf(fmaxf(b * qs, -127.f), 127.f));
;     const int q2 = (int)__builtin_rintf(fminf(fmaxf(c * qs, -127.f), 127.f)), q3 = (int)__builtin_rintf(fminf(fmaxf(d * qs, -127.f), 127.f));
;     return ((unsigned)q0 & 0xffu) | (((unsigned)q1 & 0xffu) << 8) | (((unsigned)q2 & 0xffu) << 16) | ((unsigned)q3 << 24);
; }
; template <bool I8 = false> __device__ __forceinline__ void transpose_item_f8(const float* W, int ldw, int k0, int n0, unsigned char* WT, int ldt, int drow0, float mul, LAS float* scr, int lane) {
;     ...
;     const int c = lane & 7;
; #pragma unroll
;     for (int j = 0; j < 4; ++j) { const int n = (lane >> 3) + 8 * j; const LAS float* s = scr + (8 * c) * 33 + n;
;         u32x2 o; if constexpr (I8) { o.x = pk4_i8(s[0 * 33], s[1 * 33], s[2 * 33], s[3 * 33], mul); o.y = pk4_i8(s[4 * 33], s[5 * 33], s[6 * 33], s[7 * 33], mul); }
;         else { o.x = pk4_fp8(s[0 * 33] * mul, s[1 * 33] * mul, s[2 * 33] * mul, s[3 * 33] * mul); o.y = pk4_fp8(s[4 * 33] * mul, s[5 * 33] * mul, s[6 * 33] * mul, s[7 * 33] * mul); }
;         *(u32x2*)(WT + (size_t)(drow0 + n) * ldt + k0 + 8 * c) = o; }
;     LDS_WAIT(); asm volatile("" ::: "memory");
	v_mul_f32_e32 v6, 0x44fe0000, v42
	v_mul_f32_e32 v5, 0x44fe0000, v48
	v_med3_f32 v6, v6, s23, v40
	s_waitcnt lgkmcnt(5)
	v_mul_f32_e32 v30, 0x44fe0000, v46
	s_waitcnt lgkmcnt(4)
	v_mul_f32_e32 v41, 0x44fe0000, v50
	v_med3_f32 v5, v5, s23, v40
	v_rndne_f32_e32 v6, v6
	v_med3_f32 v30, v30, s23, v40
	v_med3_f32 v41, v41, s23, v40
	v_rndne_f32_e32 v5, v5
	v_cvt_i32_f32_e32 v6, v6
	v_rndne_f32_e32 v30, v30
	v_rndne_f32_e32 v41, v41
	v_cvt_i32_f32_e32 v5, v5
	v_cvt_i32_f32_sdwa v30, v30 dst_sel:WORD_1 dst_unused:UNUSED_PAD src0_sel:DWORD
	v_cvt_i32_f32_e32 v41, v41
	v_lshlrev_b32_e32 v6, 8, v6
	v_and_b32_e32 v6, 0xff00, v6
	v_and_b32_e32 v30, 0xff0000, v30
	v_perm_b32 v5, v41, v5, s24
	v_or3_b32 v54, v5, v6, v30
	s_waitcnt lgkmcnt(2)
	v_mul_f32_e32 v6, 0x44fe0000, v56
	v_mul_f32_e32 v5, 0x44fe0000, v52
	v_med3_f32 v6, v6, s23, v40
	s_waitcnt lgkmcnt(1)
	v_mul_f32_e32 v30, 0x44fe0000, v58
	s_waitcnt lgkmcnt(0)
	v_mul_f32_e32 v41, 0x44fe0000, v60
	v_med3_f32 v5, v5, s23, v40
	v_rndne_f32_e32 v6, v6
	v_med3_f32 v30, v30, s23, v40
	v_med3_f32 v41, v41, s23, v40
	v_rndne_f32_e32 v5, v5
	v_cvt_i32_f32_e32 v6, v6
	v_rndne_f32_e32 v30, v30
	v_rndne_f32_e32 v41, v41
	v_cvt_i32_f32_e32 v5, v5
	v_cvt_i32_f32_sdwa v30, v30 dst_sel:WORD_1 dst_unused:UNUSED_PAD src0_sel:DWORD
	v_cvt_i32_f32_e32 v41, v41
	v_lshlrev_b32_e32 v6, 8, v6
	v_and_b32_e32 v6, 0xff00, v6
	v_and_b32_e32 v30, 0xff0000, v30
	v_perm_b32 v5, v41, v5, s24
	v_or3_b32 v55, v5, v6, v30
	v_mul_f32_e32 v6, 0x44fe0000, v43
	v_mul_f32_e32 v5, 0x44fe0000, v49
	v_med3_f32 v6, v6, s23, v40
	v_mul_f32_e32 v30, 0x44fe0000, v47
	v_mul_f32_e32 v41, 0x44fe0000, v51
	v_med3_f32 v5, v5, s23, v40
	v_rndne_f32_e32 v6, v6
	v_med3_f32 v30, v30, s23, v40
	v_med3_f32 v41, v41, s23, v40
	v_rndne_f32_e32 v5, v5
	v_cvt_i32_f32_e32 v6, v6
	v_rndne_f32_e32 v30, v30
	v_rndne_f32_e32 v41, v41
	v_cvt_i32_f32_e32 v5, v5
	v_cvt_i32_f32_sdwa v30, v30 dst_sel:WORD_1 dst_unused:UNUSED_PAD src0_sel:DWORD
	v_cvt_i32_f32_e32 v41, v41
	v_lshlrev_b32_e32 v6, 8, v6
	v_and_b32_e32 v6, 0xff00, v6
	v_and_b32_e32 v30, 0xff0000, v30
	v_perm_b32 v5, v41, v5, s24
	v_or3_b32 v42, v5, v6, v30
	v_mul_f32_e32 v6, 0x44fe0000, v57
	v_mul_f32_e32 v5, 0x44fe0000, v53
	v_med3_f32 v6, v6, s23, v40
	v_mul_f32_e32 v30, 0x44fe0000, v59
	v_mul_f32_e32 v41, 0x44fe0000, v61
	v_med3_f32 v5, v5, s23, v40
	v_rndne_f32_e32 v6, v6
	v_med3_f32 v30, v30, s23, v40
	v_med3_f32 v41, v41, s23, v40
	v_rndne_f32_e32 v5, v5
	v_cvt_i32_f32_e32 v6, v6
	v_rndne_f32_e32 v30, v30
	v_rndne_f32_e32 v41, v41
	v_cvt_i32_f32_e32 v5, v5
	v_cvt_i32_f32_sdwa v30, v30 dst_sel:WORD_1 dst_unused:UNUSED_PAD src0_sel:DWORD
	v_cvt_i32_f32_e32 v41, v41
	v_or_b32_e32 v62, s6, v34
	v_or_b32_e32 v46, s6, v35
	v_ashrrev_i32_e32 v63, 31, v62
	v_lshlrev_b32_e32 v6, 8, v6
	v_ashrrev_i32_e32 v47, 31, v46
	v_lshlrev_b64 v[62:63], 12, v[62:63]
	v_and_b32_e32 v6, 0xff00, v6
	v_and_b32_e32 v30, 0xff0000, v30
	v_perm_b32 v5, v41, v5, s24
	v_lshlrev_b64 v[46:47], 12, v[46:47]
	v_lshl_add_u64 v[62:63], v[44:45], 0, v[62:63]
	v_or3_b32 v43, v5, v6, v30
	v_lshl_add_u64 v[44:45], v[44:45], 0, v[46:47]
	global_store_dwordx2 v[62:63], v[54:55], off
	global_store_dwordx2 v[44:45], v[42:43], off
	s_waitcnt lgkmcnt(0)
	s_branch .LBB0_19

; __device__ __forceinline__ void unpack8(const u32x4 w, f32x4& v0, f32x4& v1) { v0 = (f32x4){bf_lo(w.x), bf_hi(w.x), bf_lo(w.y), bf_hi(w.y)}; v1 = (f32x4){bf_lo(w.z), bf_hi(w.z), bf_lo(w.w), bf_hi(w.w)}; }
; __device__ __forceinline__ void rms_row_from_bf16(const bf16_t* xrow, const float* g, bf16_t* obf, unsigned char* o8, float* of32, int lane) {
;     f32x4 v[16]; float s = 0.f;
; #pragma unroll
;     for (int j = 0; j < 8; ++j) { pg8::unpack8(*(const u32x4*)(xrow + (lane + 64 * j) * 8), v[2 * j], v[2 * j + 1]); }
; #pragma unroll
;     for (int j = 0; j < 16; ++j) s += (v[j].x * v[j].x + v[j].y * v[j].y) + (v[j].z * v[j].z + v[j].w * v[j].w);
.LBB0_1213:
	v_add_co_u32_e32 v46, vcc, s5, v22
	global_load_dwordx4 v[26:29], v[22:23], off nt
	global_load_dwordx4 v[30:33], v[22:23], off offset:1024 nt
	global_load_dwordx4 v[34:37], v[22:23], off offset:2048 nt
	global_load_dwordx4 v[38:41], v[22:23], off offset:3072 nt
	v_addc_co_u32_e32 v47, vcc, 0, v23, vcc
	global_load_dwordx4 v[42:45], v[46:47], off nt
	global_load_dwordx4 v[94:97], v[46:47], off offset:1024 nt
	global_load_dwordx4 v[98:101], v[46:47], off offset:2048 nt
	global_load_dwordx4 v[102:105], v[46:47], off offset:3072 nt
	s_and_b64 vcc, exec, s[0:1]
	s_waitcnt vmcnt(0)
	v_and_b32_e32 v85, 0xffff0000, v26
	v_and_b32_e32 v83, 0xffff0000, v27
	v_and_b32_e32 v89, 0xffff0000, v28
	v_and_b32_e32 v91, 0xffff0000, v29
	v_lshlrev_b32_e32 v84, 16, v26
	v_lshlrev_b32_e32 v82, 16, v27
	v_lshlrev_b32_e32 v88, 16, v28
	v_lshlrev_b32_e32 v90, 16, v29
	v_lshlrev_b32_e32 v50, 16, v42
	v_and_b32_e32 v51, 0xffff0000, v42
	v_lshlrev_b32_e32 v52, 16, v43
	v_and_b32_e32 v53, 0xffff0000, v43
	v_lshlrev_b32_e32 v46, 16, v94
	v_and_b32_e32 v47, 0xffff0000, v94
	v_lshlrev_b32_e32 v48, 16, v95
	v_and_b32_e32 v49, 0xffff0000, v95
	v_lshlrev_b32_e32 v42, 16, v96
	v_and_b32_e32 v43, 0xffff0000, v96
	v_mul_f32_e32 v86, v85, v85
	v_mul_f32_e32 v94, v83, v83
	v_mul_f32_e32 v95, v89, v89
	v_mul_f32_e32 v96, v91, v91
	v_fmac_f32_e32 v86, v84, v84
	v_fmac_f32_e32 v94, v82, v82
	v_fmac_f32_e32 v95, v88, v88
	v_fmac_f32_e32 v96, v90, v90
	v_and_b32_e32 v79, 0xffff0000, v30
	v_and_b32_e32 v81, 0xffff0000, v31
	v_add_f32_e32 v86, v86, v94
	v_add_f32_e32 v94, v95, v96
	v_lshlrev_b32_e32 v78, 16, v30
	v_lshlrev_b32_e32 v80, 16, v31
	v_add_f32_e32 v86, v86, v94
	v_mul_f32_e32 v94, v79, v79
	v_mul_f32_e32 v95, v81, v81
	v_fmac_f32_e32 v94, v78, v78
	v_fmac_f32_e32 v95, v80, v80
	v_and_b32_e32 v75, 0xffff0000, v32
	v_and_b32_e32 v77, 0xffff0000, v33
	v_add_f32_e32 v94, v94, v95
	v_lshlrev_b32_e32 v74, 16, v32
	v_lshlrev_b32_e32 v76, 16, v33
	v_add_f32_e32 v86, v86, v94
	v_mul_f32_e32 v94, v75, v75
	v_mul_f32_e32 v95, v77, v77
	v_fmac_f32_e32 v94, v74, v74
	v_fmac_f32_e32 v95, v76, v76
	v_and_b32_e32 v67, 0xffff0000, v34
	v_and_b32_e32 v69, 0xffff0000, v35
	v_add_f32_e32 v94, v94, v95
	v_lshlrev_b32_e32 v66, 16, v34
	v_lshlrev_b32_e32 v68, 16, v35
	v_add_f32_e32 v86, v94, v86
	v_mul_f32_e32 v94, v67, v67
	v_mul_f32_e32 v95, v69, v69
	v_fmac_f32_e32 v94, v66, v66
	v_fmac_f32_e32 v95, v68, v68
	v_and_b32_e32 v71, 0xffff0000, v36
	v_and_b32_e32 v73, 0xffff0000, v37
	v_add_f32_e32 v94, v94, v95
	v_lshlrev_b32_e32 v70, 16, v36
	v_lshlrev_b32_e32 v72, 16, v37
	v_add_f32_e32 v86, v94, v86
	v_mul_f32_e32 v94, v71, v71
	v_mul_f32_e32 v95, v73, v73
	v_fmac_f32_e32 v94, v70, v70
	v_fmac_f32_e32 v95, v72, v72
	v_and_b32_e32 v63, 0xffff0000, v38
	v_and_b32_e32 v65, 0xffff0000, v39
	v_add_f32_e32 v94, v94, v95
	v_lshlrev_b32_e32 v62, 16, v38
	v_lshlrev_b32_e32 v64, 16, v39
	v_add_f32_e32 v86, v94, v86
	v_mul_f32_e32 v94, v63, v63
	v_mul_f32_e32 v95, v65, v65
	v_fmac_f32_e32 v94, v62, v62
	v_fmac_f32_e32 v95, v64, v64
	v_and_b32_e32 v59, 0xffff0000, v40
	v_and_b32_e32 v61, 0xffff0000, v41
	v_add_f32_e32 v94, v94, v95
	v_lshlrev_b32_e32 v58, 16, v40
	v_lshlrev_b32_e32 v60, 16, v41
	v_add_f32_e32 v86, v94, v86
	v_mul_f32_e32 v94, v59, v59
	v_mul_f32_e32 v95, v61, v61
	v_fmac_f32_e32 v94, v58, v58
	v_fmac_f32_e32 v95, v60, v60
	v_add_f32_e32 v94, v94, v95
	v_add_f32_e32 v86, v94, v86
	v_mul_f32_e32 v94, v51, v51
	v_mul_f32_e32 v95, v53, v53
	v_fmac_f32_e32 v94, v50, v50
	v_fmac_f32_e32 v95, v52, v52
	v_and_b32_e32 v55, 0xffff0000, v44
	v_and_b32_e32 v57, 0xffff0000, v45
	v_add_f32_e32 v94, v94, v95
	v_lshlrev_b32_e32 v54, 16, v44
	v_lshlrev_b32_e32 v56, 16, v45
	v_add_f32_e32 v86, v94, v86
	v_mul_f32_e32 v94, v55, v55
	v_mul_f32_e32 v95, v57, v57
	v_fmac_f32_e32 v94, v54, v54
	v_fmac_f32_e32 v95, v56, v56
	v_add_f32_e32 v94, v94, v95
	v_add_f32_e32 v86, v94, v86
	v_mul_f32_e32 v94, v47, v47
	v_mul_f32_e32 v95, v49, v49
	v_fmac_f32_e32 v94, v46, v46
	v_fmac_f32_e32 v95, v48, v48
	v_and_b32_e32 v45, 0xffff0000, v97
	v_add_f32_e32 v94, v94, v95
	v_lshlrev_b32_e32 v44, 16, v97
	v_add_f32_e32 v86, v94, v86
	v_mul_f32_e32 v94, v43, v43
	v_mul_f32_e32 v95, v45, v45
	v_fmac_f32_e32 v94, v42, v42
	v_fmac_f32_e32 v95, v44, v44
	v_and_b32_e32 v35, 0xffff0000, v98
	v_and_b32_e32 v37, 0xffff0000, v99
	v_add_f32_e32 v94, v94, v95
	v_lshlrev_b32_e32 v34, 16, v98
	v_lshlrev_b32_e32 v36, 16, v99
	v_add_f32_e32 v86, v94, v86
	v_mul_f32_e32 v94, v35, v35
	v_mul_f32_e32 v95, v37, v37
	v_fmac_f32_e32 v94, v34, v34
	v_fmac_f32_e32 v95, v36, v36
	v_and_b32_e32 v39, 0xffff0000, v100
	v_and_b32_e32 v41, 0xffff0000, v101
	v_add_f32_e32 v94, v94, v95
	v_lshlrev_b32_e32 v38, 16, v100
	v_lshlrev_b32_e32 v40, 16, v101
	v_add_f32_e32 v86, v94, v86
	v_mul_f32_e32 v94, v39, v39
	v_mul_f32_e32 v95, v41, v41
	v_fmac_f32_e32 v94, v38, v38
	v_fmac_f32_e32 v95, v40, v40
	v_and_b32_e32 v31, 0xffff0000, v102
	v_and_b32_e32 v33, 0xffff0000, v103
	v_add_f32_e32 v94, v94, v95
	v_lshlrev_b32_e32 v30, 16, v102
	v_lshlrev_b32_e32 v32, 16, v103
	v_add_f32_e32 v86, v94, v86
	v_mul_f32_e32 v94, v31, v31
	v_mul_f32_e32 v95, v33, v33
	v_fmac_f32_e32 v94, v30, v30
	v_fmac_f32_e32 v95, v32, v32
	v_and_b32_e32 v27, 0xffff0000, v104
	v_and_b32_e32 v29, 0xffff0000, v105
	v_add_f32_e32 v94, v94, v95
	v_lshlrev_b32_e32 v26, 16, v104
	v_lshlrev_b32_e32 v28, 16, v105
	v_add_f32_e32 v86, v94, v86
	v_mul_f32_e32 v94, v27, v27
	v_mul_f32_e32 v95, v29, v29
	v_fmac_f32_e32 v94, v26, v26
	v_fmac_f32_e32 v95, v28, v28
	v_add_f32_e32 v94, v94, v95
	v_add_f32_e32 v86, v94, v86
	ds_swizzle_b32 v94, v86 offset:swizzle(SWAP,1)
	s_waitcnt lgkmcnt(0)
	v_add_f32_e32 v86, v86, v94
	ds_swizzle_b32 v94, v86 offset:swizzle(SWAP,2)
	s_waitcnt lgkmcnt(0)
	v_add_f32_e32 v86, v86, v94
	ds_swizzle_b32 v94, v86 offset:swizzle(SWAP,4)
	s_waitcnt lgkmcnt(0)
	v_add_f32_e32 v86, v86, v94
	ds_swizzle_b32 v94, v86 offset:swizzle(SWAP,8)
	s_waitcnt lgkmcnt(0)
	v_add_f32_e32 v86, v86, v94
	ds_swizzle_b32 v94, v86 offset:swizzle(SWAP,16)
	s_waitcnt lgkmcnt(0)
	v_add_f32_e32 v86, v86, v94
	v_mov_b32_e32 v94, v86
	s_nop 1
	v_permlane32_swap_b32_e32 v86, v94
	s_cbranch_vccnz .LBB0_1212
; __device__ __forceinline__ u32x4 pack8(const f32x4 v0, const f32x4 v1) { u32x4 w; w.x = cvt_pk_bf16(v0[0], v0[1]); w.y = cvt_pk_bf16(v0[2], v0[3]); w.z = cvt_pk_bf16(v1[0], v1[1]); w.w = cvt_pk_bf16(v1[2], v1[3]); return w; }
; __device__ __forceinline__ void rms_row_from_bf16(const bf16_t* xrow, const float* g, bf16_t* obf, unsigned char* o8, float* of32, int lane) {
;     ...
;     const float rstd = 1.0f / sqrtf(wave_sum(s) * (1.f / D) + EPS);
; #pragma unroll
;     for (int j = 0; j < 8; ++j) { const int c = (lane + 64 * j) * 8; const f32x4 y0 = v[2 * j] * rstd * *(const f32x4*)(g + c), y1 = v[2 * j + 1] * rstd * *(const f32x4*)(g + c + 4);
;         if (obf) *(u32x4*)(obf + c) = pg8::pack8(y0, y1);
;         if (o8) *(u32x2*)(o8 + c) = (u32x2){pk4_i8(y0.x, y0.y, y0.z, y0.w, XN_QS), pk4_i8(y1.x, y1.y, y1.z, y1.w, XN_QS)};
;         if (of32) { *(f32x4*)(of32 + c) = y0; *(f32x4*)(of32 + c + 4) = y1; } }
	global_load_dwordx4 v[96:99], v[2:3], off offset:16
	global_load_dwordx4 v[100:103], v[2:3], off
	v_add_f32_e32 v86, v86, v94
	v_fmamk_f32 v86, v86, 0x39800000, v92
	v_mul_f32_e32 v94, 0x4f800000, v86
	v_cmp_gt_f32_e32 vcc, s8, v86
	s_nop 1
	v_cndmask_b32_e32 v86, v86, v94, vcc
	v_sqrt_f32_e32 v94, v86
	s_nop 0
	v_add_u32_e32 v95, -1, v94
	v_add_u32_e32 v104, 1, v94
	v_fma_f32 v105, -v95, v94, v86
	v_fma_f32 v106, -v104, v94, v86
	v_cmp_ge_f32_e64 s[2:3], 0, v105
	s_nop 1
	v_cndmask_b32_e64 v94, v94, v95, s[2:3]
	v_cmp_lt_f32_e64 s[2:3], 0, v106
	s_nop 1
	v_cndmask_b32_e64 v94, v94, v104, s[2:3]
	v_mul_f32_e32 v95, 0x37800000, v94
	v_cndmask_b32_e32 v94, v94, v95, vcc
	v_cmp_class_f32_e32 vcc, v86, v93
	s_nop 1
	v_cndmask_b32_e32 v86, v94, v86, vcc
	v_div_scale_f32 v94, s[2:3], v86, v86, 1.0
	v_rcp_f32_e32 v95, v94
	v_div_scale_f32 v104, vcc, 1.0, v86, 1.0
	v_fma_f32 v105, -v94, v95, 1.0
	v_fmac_f32_e32 v95, v105, v95
	v_mul_f32_e32 v105, v104, v95
	v_fma_f32 v106, -v94, v105, v104
	v_fmac_f32_e32 v105, v106, v95
	v_fma_f32 v94, -v94, v105, v104
	v_div_fmas_f32 v94, v94, v95, v105
	v_div_fixup_f32 v86, v94, v86, 1.0
	v_pk_mul_f32 v[88:89], v[86:87], v[88:89] op_sel_hi:[0,1]
	v_pk_mul_f32 v[90:91], v[86:87], v[90:91] op_sel_hi:[0,1]
	v_pk_mul_f32 v[94:95], v[86:87], v[84:85] op_sel_hi:[0,1]
	v_pk_mul_f32 v[104:105], v[86:87], v[82:83] op_sel_hi:[0,1]
	v_pk_mul_f32 v[80:81], v[86:87], v[80:81] op_sel_hi:[0,1]
	v_pk_mul_f32 v[78:79], v[86:87], v[78:79] op_sel_hi:[0,1]
	v_pk_mul_f32 v[72:73], v[86:87], v[72:73] op_sel_hi:[0,1]
	v_pk_mul_f32 v[70:71], v[86:87], v[70:71] op_sel_hi:[0,1]
	v_pk_mul_f32 v[64:65], v[86:87], v[64:65] op_sel_hi:[0,1]
	v_pk_mul_f32 v[62:63], v[86:87], v[62:63] op_sel_hi:[0,1]
	v_pk_mul_f32 v[56:57], v[86:87], v[56:57] op_sel_hi:[0,1]
	v_pk_mul_f32 v[54:55], v[86:87], v[54:55] op_sel_hi:[0,1]
	v_pk_mul_f32 v[48:49], v[86:87], v[48:49] op_sel_hi:[0,1]
	v_pk_mul_f32 v[46:47], v[86:87], v[46:47] op_sel_hi:[0,1]
	v_pk_mul_f32 v[40:41], v[86:87], v[40:41] op_sel_hi:[0,1]
	v_pk_mul_f32 v[38:39], v[86:87], v[38:39] op_sel_hi:[0,1]
	v_pk_mul_f32 v[32:33], v[86:87], v[32:33] op_sel_hi:[0,1]
	v_pk_mul_f32 v[30:31], v[86:87], v[30:31] op_sel_hi:[0,1]
	s_waitcnt vmcnt(1)
	v_pk_mul_f32 v[84:85], v[90:91], v[98:99]
	v_pk_mul_f32 v[82:83], v[88:89], v[96:97]
	s_waitcnt vmcnt(0)
	v_pk_mul_f32 v[90:91], v[104:105], v[102:103]
	v_pk_mul_f32 v[88:89], v[94:95], v[100:101]
	global_store_dwordx4 v[18:19], v[88:91], off
	global_store_dwordx4 v[18:19], v[82:85], off offset:16
	global_load_dwordx4 v[82:85], v[4:5], off
	s_nop 0
	global_load_dwordx4 v[88:91], v[4:5], off offset:16
	v_pk_mul_f32 v[94:95], v[86:87], v[76:77] op_sel_hi:[0,1]
	v_pk_mul_f32 v[96:97], v[86:87], v[74:75] op_sel_hi:[0,1]
	s_waitcnt vmcnt(1)
	v_pk_mul_f32 v[74:75], v[78:79], v[82:83]
	v_pk_mul_f32 v[76:77], v[80:81], v[84:85]
	s_waitcnt vmcnt(0)
	v_pk_mul_f32 v[78:79], v[96:97], v[88:89]
	v_pk_mul_f32 v[80:81], v[94:95], v[90:91]
	global_store_dwordx4 v[18:19], v[74:77], off offset:2048
	global_store_dwordx4 v[18:19], v[78:81], off offset:2064
	global_load_dwordx4 v[74:77], v[6:7], off offset:16
	s_nop 0
	global_load_dwordx4 v[78:81], v[6:7], off
	v_add_co_u32_e32 v82, vcc, s5, v18
	v_pk_mul_f32 v[88:89], v[86:87], v[68:69] op_sel_hi:[0,1]
	s_nop 0
	v_addc_co_u32_e32 v83, vcc, 0, v19, vcc
	v_add_co_u32_e32 v84, vcc, s6, v18
	v_pk_mul_f32 v[90:91], v[86:87], v[66:67] op_sel_hi:[0,1]
	s_nop 0
	v_addc_co_u32_e32 v85, vcc, 0, v19, vcc
	s_waitcnt vmcnt(1)
	v_pk_mul_f32 v[66:67], v[70:71], v[74:75]
	v_pk_mul_f32 v[68:69], v[72:73], v[76:77]
	s_waitcnt vmcnt(0)
	v_pk_mul_f32 v[70:71], v[90:91], v[78:79]
	v_pk_mul_f32 v[72:73], v[88:89], v[80:81]
	global_store_dwordx4 v[84:85], v[70:73], off offset:-4096
	global_store_dwordx4 v[82:83], v[66:69], off offset:16
	global_load_dwordx4 v[66:69], v[8:9], off
	s_nop 0
	global_load_dwordx4 v[70:73], v[8:9], off offset:16
	v_pk_mul_f32 v[74:75], v[86:87], v[60:61] op_sel_hi:[0,1]
	v_pk_mul_f32 v[76:77], v[86:87], v[58:59] op_sel_hi:[0,1]
	s_waitcnt vmcnt(1)
	v_pk_mul_f32 v[58:59], v[62:63], v[66:67]
	v_pk_mul_f32 v[60:61], v[64:65], v[68:69]
	s_waitcnt vmcnt(0)
	v_pk_mul_f32 v[62:63], v[76:77], v[70:71]
	v_pk_mul_f32 v[64:65], v[74:75], v[72:73]
	global_store_dwordx4 v[82:83], v[58:61], off offset:2048
	global_store_dwordx4 v[82:83], v[62:65], off offset:2064
	global_load_dwordx4 v[58:61], v[10:11], off offset:16
	s_nop 0
	global_load_dwordx4 v[62:65], v[10:11], off
	v_pk_mul_f32 v[66:67], v[86:87], v[52:53] op_sel_hi:[0,1]
	v_pk_mul_f32 v[68:69], v[86:87], v[50:51] op_sel_hi:[0,1]
	s_waitcnt vmcnt(1)
	v_pk_mul_f32 v[50:51], v[54:55], v[58:59]
	v_pk_mul_f32 v[52:53], v[56:57], v[60:61]
	s_waitcnt vmcnt(0)
	v_pk_mul_f32 v[54:55], v[68:69], v[62:63]
	v_pk_mul_f32 v[56:57], v[66:67], v[64:65]
	global_store_dwordx4 v[84:85], v[54:57], off
	global_store_dwordx4 v[84:85], v[50:53], off offset:16
	global_load_dwordx4 v[50:53], v[12:13], off
	s_nop 0
	global_load_dwordx4 v[54:57], v[12:13], off offset:16
	v_pk_mul_f32 v[58:59], v[86:87], v[44:45] op_sel_hi:[0,1]
	v_pk_mul_f32 v[60:61], v[86:87], v[42:43] op_sel_hi:[0,1]
	s_waitcnt vmcnt(1)
	v_pk_mul_f32 v[42:43], v[46:47], v[50:51]
	v_pk_mul_f32 v[44:45], v[48:49], v[52:53]
	s_waitcnt vmcnt(0)
	v_pk_mul_f32 v[46:47], v[60:61], v[54:55]
	v_pk_mul_f32 v[48:49], v[58:59], v[56:57]
	global_store_dwordx4 v[84:85], v[42:45], off offset:2048
	global_store_dwordx4 v[84:85], v[46:49], off offset:2064
	global_load_dwordx4 v[42:45], v[14:15], off offset:16
	s_nop 0
	global_load_dwordx4 v[46:49], v[14:15], off
	v_add_co_u32_e32 v50, vcc, s7, v18
	v_pk_mul_f32 v[52:53], v[86:87], v[36:37] op_sel_hi:[0,1]
	v_pk_mul_f32 v[54:55], v[86:87], v[34:35] op_sel_hi:[0,1]
	v_addc_co_u32_e32 v51, vcc, 0, v19, vcc
	s_waitcnt vmcnt(1)
	v_pk_mul_f32 v[34:35], v[38:39], v[42:43]
	v_pk_mul_f32 v[36:37], v[40:41], v[44:45]
	s_waitcnt vmcnt(0)
	v_pk_mul_f32 v[38:39], v[54:55], v[46:47]
	v_pk_mul_f32 v[40:41], v[52:53], v[48:49]
	global_store_dwordx4 v[50:51], v[38:41], off
	global_store_dwordx4 v[50:51], v[34:37], off offset:16
	global_load_dwordx4 v[34:37], v[16:17], off
	s_nop 0
	global_load_dwordx4 v[38:41], v[16:17], off offset:16
	v_pk_mul_f32 v[42:43], v[86:87], v[28:29] op_sel_hi:[0,1]
	v_pk_mul_f32 v[44:45], v[86:87], v[26:27] op_sel_hi:[0,1]
	s_waitcnt vmcnt(1)
	v_pk_mul_f32 v[26:27], v[30:31], v[34:35]
	v_pk_mul_f32 v[28:29], v[32:33], v[36:37]
	s_waitcnt vmcnt(0)
	v_pk_mul_f32 v[30:31], v[44:45], v[38:39]
	v_pk_mul_f32 v[32:33], v[42:43], v[40:41]
	global_store_dwordx4 v[50:51], v[26:29], off offset:2048
	global_store_dwordx4 v[50:51], v[30:33], off offset:2064
	s_branch .LBB0_1212
